# GEMM K-loops: removed per-phase s_setprio 1/0 flips (all six instantiations); scan RW loop as in previous version
# speedup vs baseline: 1.0092x; 1.0092x over previous
.LBB0_440:
	s_add_i32 s40, s4, 2
	s_add_i32 s41, 0, 0x10000
	s_cmp_eq_u32 s36, s4
	v_lshl_add_u64 v[146:147], v[142:143], 0, s[84:85]
	s_cselect_b64 vcc, -1, 0
	v_add_u32_e32 v139, s41, v144
	v_cndmask_b32_e32 v213, v147, v141, vcc
	v_cndmask_b32_e32 v212, v146, v140, vcc
	ds_read_b128 v[146:149], v139
	ds_read_b128 v[150:153], v139 offset:1024
	ds_read_b128 v[154:157], v139 offset:2048
	ds_read_b128 v[160:163], v139 offset:3072
	s_cselect_b32 s4, s0, s6
	s_cselect_b32 s5, s1, s7
	v_lshl_add_u64 v[196:197], v[142:143], 0, v[134:135]
	s_add_i32 m0, s17, 0xc000
	ds_read_b128 v[164:167], v145
	ds_read_b128 v[168:171], v145 offset:1024
	ds_read_b128 v[172:175], v145 offset:2048
	ds_read_b128 v[176:179], v145 offset:3072
	ds_read_b128 v[180:183], v145 offset:4096
	ds_read_b128 v[184:187], v145 offset:5120
	ds_read_b128 v[188:191], v145 offset:6144
	ds_read_b128 v[192:195], v145 offset:7168
	global_load_lds_dwordx4 v[196:197], off
	v_lshl_add_u64 v[196:197], v[142:143], 0, v[136:137]
	s_add_i32 m0, s17, 0xe000
	s_nop 0
	global_load_lds_dwordx4 v[196:197], off
	s_waitcnt lgkmcnt(8)
	s_barrier
	s_waitcnt lgkmcnt(0)
	s_waitcnt lgkmcnt(0)
	v_mfma_f32_16x16x32_bf16 v[126:129], v[146:149], v[164:167], v[126:129]
	v_mfma_f32_16x16x32_bf16 v[122:125], v[154:157], v[164:167], v[122:125]
	v_mfma_f32_16x16x32_bf16 v[118:121], v[146:149], v[172:175], v[118:121]
	v_mfma_f32_16x16x32_bf16 v[110:113], v[154:157], v[172:175], v[110:113]
	v_mfma_f32_16x16x32_bf16 v[102:105], v[146:149], v[180:183], v[102:105]
	v_mfma_f32_16x16x32_bf16 v[94:97], v[154:157], v[180:183], v[94:97]
	v_mfma_f32_16x16x32_bf16 v[86:89], v[146:149], v[188:191], v[86:89]
	v_mfma_f32_16x16x32_bf16 v[78:81], v[154:157], v[188:191], v[78:81]
	v_mfma_f32_16x16x32_bf16 v[126:129], v[150:153], v[168:171], v[126:129]
	v_mfma_f32_16x16x32_bf16 v[122:125], v[160:163], v[168:171], v[122:125]
	v_mfma_f32_16x16x32_bf16 v[118:121], v[150:153], v[176:179], v[118:121]
	v_mfma_f32_16x16x32_bf16 v[110:113], v[160:163], v[176:179], v[110:113]
	v_mfma_f32_16x16x32_bf16 v[102:105], v[150:153], v[184:187], v[102:105]
	v_mfma_f32_16x16x32_bf16 v[94:97], v[160:163], v[184:187], v[94:97]
	v_mfma_f32_16x16x32_bf16 v[86:89], v[150:153], v[192:195], v[86:89]
	v_mfma_f32_16x16x32_bf16 v[78:81], v[160:163], v[192:195], v[78:81]
	s_barrier
	s_add_i32 s89, 0, 0x14000
	s_add_i32 s41, s41, s3
	v_add_u32_e32 v139, s89, v144
	v_lshl_add_u64 v[214:215], s[4:5], 0, v[132:133]
	s_mov_b32 m0, s41
	ds_read_b128 v[196:199], v139
	ds_read_b128 v[200:203], v139 offset:1024
	ds_read_b128 v[204:207], v139 offset:2048
	ds_read_b128 v[208:211], v139 offset:3072
	global_load_lds_dwordx4 v[214:215], off
	v_lshl_add_u64 v[216:217], s[4:5], 0, v[130:131]
	s_add_i32 m0, s41, 0x2000
	s_nop 0
	global_load_lds_dwordx4 v[216:217], off
	s_barrier
	s_waitcnt lgkmcnt(0)
	s_waitcnt lgkmcnt(0)
	v_mfma_f32_16x16x32_bf16 v[114:117], v[196:199], v[164:167], v[114:117]
	v_mfma_f32_16x16x32_bf16 v[106:109], v[204:207], v[164:167], v[106:109]
	v_mfma_f32_16x16x32_bf16 v[98:101], v[196:199], v[172:175], v[98:101]
	v_mfma_f32_16x16x32_bf16 v[90:93], v[204:207], v[172:175], v[90:93]
	v_mfma_f32_16x16x32_bf16 v[82:85], v[196:199], v[180:183], v[82:85]
	v_mfma_f32_16x16x32_bf16 v[74:77], v[204:207], v[180:183], v[74:77]
	v_mfma_f32_16x16x32_bf16 v[70:73], v[196:199], v[188:191], v[70:73]
	v_mfma_f32_16x16x32_bf16 v[66:69], v[204:207], v[188:191], v[66:69]
	v_mfma_f32_16x16x32_bf16 v[114:117], v[200:203], v[168:171], v[114:117]
	v_mfma_f32_16x16x32_bf16 v[106:109], v[208:211], v[168:171], v[106:109]
	v_mfma_f32_16x16x32_bf16 v[98:101], v[200:203], v[176:179], v[98:101]
	v_mfma_f32_16x16x32_bf16 v[90:93], v[208:211], v[176:179], v[90:93]
	v_mfma_f32_16x16x32_bf16 v[82:85], v[200:203], v[184:187], v[82:85]
	v_mfma_f32_16x16x32_bf16 v[74:77], v[208:211], v[184:187], v[74:77]
	v_mfma_f32_16x16x32_bf16 v[70:73], v[200:203], v[192:195], v[70:73]
	v_mfma_f32_16x16x32_bf16 v[66:69], v[208:211], v[192:195], v[66:69]
	s_mov_b32 m0, s17
	v_lshl_add_u64 v[218:219], v[212:213], 0, v[132:133]
	s_barrier
	ds_read_b128 v[164:167], v145 offset:16384
	ds_read_b128 v[168:171], v145 offset:17408
	ds_read_b128 v[172:175], v145 offset:18432
	ds_read_b128 v[176:179], v145 offset:19456
	ds_read_b128 v[180:183], v145 offset:20480
	ds_read_b128 v[184:187], v145 offset:21504
	ds_read_b128 v[188:191], v145 offset:22528
	ds_read_b128 v[192:195], v145 offset:23552
	global_load_lds_dwordx4 v[218:219], off
	v_lshl_add_u64 v[224:225], v[212:213], 0, v[130:131]
	s_mov_b32 m0, s22
	s_nop 0
	global_load_lds_dwordx4 v[224:225], off
	s_barrier
	s_waitcnt lgkmcnt(0)
	s_waitcnt lgkmcnt(0)
	v_mfma_f32_16x16x32_bf16 v[62:65], v[146:149], v[164:167], v[62:65]
	v_mfma_f32_16x16x32_bf16 v[58:61], v[154:157], v[164:167], v[58:61]
	v_mfma_f32_16x16x32_bf16 v[54:57], v[146:149], v[172:175], v[54:57]
	v_mfma_f32_16x16x32_bf16 v[46:49], v[154:157], v[172:175], v[46:49]
	v_mfma_f32_16x16x32_bf16 v[38:41], v[146:149], v[180:183], v[38:41]
	v_mfma_f32_16x16x32_bf16 v[30:33], v[154:157], v[180:183], v[30:33]
	v_mfma_f32_16x16x32_bf16 v[22:25], v[146:149], v[188:191], v[22:25]
	v_mfma_f32_16x16x32_bf16 v[14:17], v[154:157], v[188:191], v[14:17]
	v_mfma_f32_16x16x32_bf16 v[62:65], v[150:153], v[168:171], v[62:65]
	v_mfma_f32_16x16x32_bf16 v[58:61], v[160:163], v[168:171], v[58:61]
	v_mfma_f32_16x16x32_bf16 v[54:57], v[150:153], v[176:179], v[54:57]
	v_mfma_f32_16x16x32_bf16 v[46:49], v[160:163], v[176:179], v[46:49]
	v_mfma_f32_16x16x32_bf16 v[38:41], v[150:153], v[184:187], v[38:41]
	v_mfma_f32_16x16x32_bf16 v[30:33], v[160:163], v[184:187], v[30:33]
	v_mfma_f32_16x16x32_bf16 v[22:25], v[150:153], v[192:195], v[22:25]
	v_mfma_f32_16x16x32_bf16 v[14:17], v[160:163], v[192:195], v[14:17]
	s_barrier
	s_add_u32 s4, s4, s94
	s_addc_u32 s5, s5, 0
	s_add_i32 s41, s89, s3
	v_lshl_add_u64 v[230:231], s[4:5], 0, v[132:133]
	s_mov_b32 m0, s41
	v_lshl_add_u64 v[232:233], s[4:5], 0, v[130:131]
	global_load_lds_dwordx4 v[230:231], off
	s_add_i32 m0, s41, 0x2000
	s_nop 0
	global_load_lds_dwordx4 v[232:233], off
	s_waitcnt vmcnt(6)
	s_barrier
	v_mfma_f32_16x16x32_bf16 v[50:53], v[196:199], v[164:167], v[50:53]
	v_mfma_f32_16x16x32_bf16 v[42:45], v[204:207], v[164:167], v[42:45]
	v_mfma_f32_16x16x32_bf16 v[34:37], v[196:199], v[172:175], v[34:37]
	v_mfma_f32_16x16x32_bf16 v[26:29], v[204:207], v[172:175], v[26:29]
	v_mfma_f32_16x16x32_bf16 v[18:21], v[196:199], v[180:183], v[18:21]
	v_mfma_f32_16x16x32_bf16 v[10:13], v[204:207], v[180:183], v[10:13]
	v_mfma_f32_16x16x32_bf16 v[6:9], v[196:199], v[188:191], v[6:9]
	v_mfma_f32_16x16x32_bf16 v[2:5], v[204:207], v[188:191], v[2:5]
	v_mfma_f32_16x16x32_bf16 v[50:53], v[200:203], v[168:171], v[50:53]
	v_mfma_f32_16x16x32_bf16 v[42:45], v[208:211], v[168:171], v[42:45]
	v_mfma_f32_16x16x32_bf16 v[34:37], v[200:203], v[176:179], v[34:37]
	v_mfma_f32_16x16x32_bf16 v[26:29], v[208:211], v[176:179], v[26:29]
	v_mfma_f32_16x16x32_bf16 v[18:21], v[200:203], v[184:187], v[18:21]
	v_mfma_f32_16x16x32_bf16 v[10:13], v[208:211], v[184:187], v[10:13]
	v_mfma_f32_16x16x32_bf16 v[6:9], v[200:203], v[192:195], v[6:9]
	v_mfma_f32_16x16x32_bf16 v[2:5], v[208:211], v[192:195], v[2:5]
	s_add_i32 s4, 0, 0x18000
	v_add_u32_e32 v139, s4, v144
	s_barrier
	ds_read_b128 v[146:149], v139
	ds_read_b128 v[150:153], v139 offset:1024
	ds_read_b128 v[154:157], v139 offset:2048
	ds_read_b128 v[160:163], v139 offset:3072
	v_lshl_add_u64 v[196:197], v[212:213], 0, s[94:95]
	s_mov_b32 m0, s23
	v_lshl_add_u64 v[198:199], v[196:197], 0, v[132:133]
	ds_read_b128 v[164:167], v145 offset:32768
	ds_read_b128 v[168:171], v145 offset:33792
	ds_read_b128 v[172:175], v145 offset:34816
	ds_read_b128 v[176:179], v145 offset:35840
	ds_read_b128 v[180:183], v145 offset:36864
	ds_read_b128 v[184:187], v145 offset:37888
	ds_read_b128 v[188:191], v145 offset:38912
	ds_read_b128 v[192:195], v145 offset:39936
	global_load_lds_dwordx4 v[198:199], off
	v_lshl_add_u64 v[196:197], v[196:197], 0, v[130:131]
	s_mov_b32 m0, s28
	s_nop 0
	global_load_lds_dwordx4 v[196:197], off
	s_waitcnt lgkmcnt(8)
	s_barrier
	s_waitcnt lgkmcnt(0)
	s_waitcnt lgkmcnt(0)
	v_mfma_f32_16x16x32_bf16 v[126:129], v[146:149], v[164:167], v[126:129]
	v_mfma_f32_16x16x32_bf16 v[122:125], v[154:157], v[164:167], v[122:125]
	v_mfma_f32_16x16x32_bf16 v[118:121], v[146:149], v[172:175], v[118:121]
	v_mfma_f32_16x16x32_bf16 v[110:113], v[154:157], v[172:175], v[110:113]
	v_mfma_f32_16x16x32_bf16 v[102:105], v[146:149], v[180:183], v[102:105]
	v_mfma_f32_16x16x32_bf16 v[94:97], v[154:157], v[180:183], v[94:97]
	v_mfma_f32_16x16x32_bf16 v[86:89], v[146:149], v[188:191], v[86:89]
	v_mfma_f32_16x16x32_bf16 v[78:81], v[154:157], v[188:191], v[78:81]
	v_mfma_f32_16x16x32_bf16 v[126:129], v[150:153], v[168:171], v[126:129]
	v_mfma_f32_16x16x32_bf16 v[122:125], v[160:163], v[168:171], v[122:125]
	v_mfma_f32_16x16x32_bf16 v[118:121], v[150:153], v[176:179], v[118:121]
	v_mfma_f32_16x16x32_bf16 v[110:113], v[160:163], v[176:179], v[110:113]
	v_mfma_f32_16x16x32_bf16 v[102:105], v[150:153], v[184:187], v[102:105]
	v_mfma_f32_16x16x32_bf16 v[94:97], v[160:163], v[184:187], v[94:97]
	v_mfma_f32_16x16x32_bf16 v[86:89], v[150:153], v[192:195], v[86:89]
	v_mfma_f32_16x16x32_bf16 v[78:81], v[160:163], v[192:195], v[78:81]
	s_barrier
	s_add_i32 s5, 0, 0x1c000
	s_add_i32 s4, s4, s3
	v_add_u32_e32 v139, s5, v144
	v_lshl_add_u64 v[212:213], v[214:215], 0, s[84:85]
	s_mov_b32 m0, s4
	ds_read_b128 v[196:199], v139
	ds_read_b128 v[200:203], v139 offset:1024
	ds_read_b128 v[204:207], v139 offset:2048
	ds_read_b128 v[208:211], v139 offset:3072
	global_load_lds_dwordx4 v[212:213], off
	v_lshl_add_u64 v[212:213], v[216:217], 0, s[84:85]
	s_add_i32 m0, s4, 0x2000
	s_nop 0
	global_load_lds_dwordx4 v[212:213], off
	s_barrier
	s_waitcnt lgkmcnt(0)
	s_waitcnt lgkmcnt(0)
	v_mfma_f32_16x16x32_bf16 v[114:117], v[196:199], v[164:167], v[114:117]
	v_mfma_f32_16x16x32_bf16 v[106:109], v[204:207], v[164:167], v[106:109]
	v_mfma_f32_16x16x32_bf16 v[98:101], v[196:199], v[172:175], v[98:101]
	v_mfma_f32_16x16x32_bf16 v[90:93], v[204:207], v[172:175], v[90:93]
	v_mfma_f32_16x16x32_bf16 v[82:85], v[196:199], v[180:183], v[82:85]
	v_mfma_f32_16x16x32_bf16 v[74:77], v[204:207], v[180:183], v[74:77]
	v_mfma_f32_16x16x32_bf16 v[70:73], v[196:199], v[188:191], v[70:73]
	v_mfma_f32_16x16x32_bf16 v[66:69], v[204:207], v[188:191], v[66:69]
	v_mfma_f32_16x16x32_bf16 v[114:117], v[200:203], v[168:171], v[114:117]
	v_mfma_f32_16x16x32_bf16 v[106:109], v[208:211], v[168:171], v[106:109]
	v_mfma_f32_16x16x32_bf16 v[98:101], v[200:203], v[176:179], v[98:101]
	v_mfma_f32_16x16x32_bf16 v[90:93], v[208:211], v[176:179], v[90:93]
	v_mfma_f32_16x16x32_bf16 v[82:85], v[200:203], v[184:187], v[82:85]
	v_mfma_f32_16x16x32_bf16 v[74:77], v[208:211], v[184:187], v[74:77]
	v_mfma_f32_16x16x32_bf16 v[70:73], v[200:203], v[192:195], v[70:73]
	v_mfma_f32_16x16x32_bf16 v[66:69], v[208:211], v[192:195], v[66:69]
	s_mov_b32 m0, s29
	v_lshl_add_u64 v[212:213], v[218:219], 0, s[84:85]
	s_barrier
	ds_read_b128 v[164:167], v145 offset:49152
	ds_read_b128 v[168:171], v145 offset:50176
	ds_read_b128 v[172:175], v145 offset:51200
	ds_read_b128 v[176:179], v145 offset:52224
	ds_read_b128 v[180:183], v145 offset:53248
	ds_read_b128 v[184:187], v145 offset:54272
	ds_read_b128 v[188:191], v145 offset:55296
	ds_read_b128 v[192:195], v145 offset:56320
	global_load_lds_dwordx4 v[212:213], off
	v_lshl_add_u64 v[212:213], v[224:225], 0, s[84:85]
	s_mov_b32 m0, s35
	s_nop 0
	global_load_lds_dwordx4 v[212:213], off
	s_barrier
	s_waitcnt lgkmcnt(0)
	s_waitcnt lgkmcnt(0)
	v_mfma_f32_16x16x32_bf16 v[62:65], v[146:149], v[164:167], v[62:65]
	v_mfma_f32_16x16x32_bf16 v[58:61], v[154:157], v[164:167], v[58:61]
	v_mfma_f32_16x16x32_bf16 v[54:57], v[146:149], v[172:175], v[54:57]
	v_mfma_f32_16x16x32_bf16 v[46:49], v[154:157], v[172:175], v[46:49]
	v_mfma_f32_16x16x32_bf16 v[38:41], v[146:149], v[180:183], v[38:41]
	v_mfma_f32_16x16x32_bf16 v[30:33], v[154:157], v[180:183], v[30:33]
	v_mfma_f32_16x16x32_bf16 v[22:25], v[146:149], v[188:191], v[22:25]
	v_mfma_f32_16x16x32_bf16 v[14:17], v[154:157], v[188:191], v[14:17]
	v_mfma_f32_16x16x32_bf16 v[62:65], v[150:153], v[168:171], v[62:65]
	v_mfma_f32_16x16x32_bf16 v[58:61], v[160:163], v[168:171], v[58:61]
	v_mfma_f32_16x16x32_bf16 v[54:57], v[150:153], v[176:179], v[54:57]
	v_mfma_f32_16x16x32_bf16 v[46:49], v[160:163], v[176:179], v[46:49]
	v_mfma_f32_16x16x32_bf16 v[38:41], v[150:153], v[184:187], v[38:41]
	v_mfma_f32_16x16x32_bf16 v[30:33], v[160:163], v[184:187], v[30:33]
	v_mfma_f32_16x16x32_bf16 v[22:25], v[150:153], v[192:195], v[22:25]
	v_mfma_f32_16x16x32_bf16 v[14:17], v[160:163], v[192:195], v[14:17]
	s_barrier
	s_add_i32 s4, s5, s3
	v_lshl_add_u64 v[146:147], v[230:231], 0, s[84:85]
	s_mov_b32 m0, s4
	s_nop 0
	global_load_lds_dwordx4 v[146:147], off
	v_lshl_add_u64 v[146:147], v[232:233], 0, s[84:85]
	s_add_i32 m0, s4, 0x2000
	s_nop 0
	global_load_lds_dwordx4 v[146:147], off
	s_waitcnt vmcnt(6)
	s_barrier
	v_mfma_f32_16x16x32_bf16 v[50:53], v[196:199], v[164:167], v[50:53]
	v_mfma_f32_16x16x32_bf16 v[42:45], v[204:207], v[164:167], v[42:45]
	v_mfma_f32_16x16x32_bf16 v[34:37], v[196:199], v[172:175], v[34:37]
	v_mfma_f32_16x16x32_bf16 v[26:29], v[204:207], v[172:175], v[26:29]
	v_mfma_f32_16x16x32_bf16 v[18:21], v[196:199], v[180:183], v[18:21]
	v_mfma_f32_16x16x32_bf16 v[10:13], v[204:207], v[180:183], v[10:13]
	v_mfma_f32_16x16x32_bf16 v[6:9], v[196:199], v[188:191], v[6:9]
	v_mfma_f32_16x16x32_bf16 v[2:5], v[204:207], v[188:191], v[2:5]
	v_mfma_f32_16x16x32_bf16 v[50:53], v[200:203], v[168:171], v[50:53]
	v_mfma_f32_16x16x32_bf16 v[42:45], v[208:211], v[168:171], v[42:45]
	v_mfma_f32_16x16x32_bf16 v[34:37], v[200:203], v[176:179], v[34:37]
	v_mfma_f32_16x16x32_bf16 v[26:29], v[208:211], v[176:179], v[26:29]
	v_mfma_f32_16x16x32_bf16 v[18:21], v[200:203], v[184:187], v[18:21]
	v_mfma_f32_16x16x32_bf16 v[10:13], v[208:211], v[184:187], v[10:13]
	v_mfma_f32_16x16x32_bf16 v[6:9], v[200:203], v[192:195], v[6:9]
	v_mfma_f32_16x16x32_bf16 v[2:5], v[208:211], v[192:195], v[2:5]
	s_add_u32 s6, s6, 0x100
	s_addc_u32 s7, s7, 0
	v_lshl_add_u64 v[142:143], v[142:143], 0, s[86:87]
	s_cmp_ge_u32 s40, s13
	s_mov_b32 s4, s40
	s_barrier
	s_cbranch_scc0 .LBB0_440
	s_lshl_b32 s5, s54, 22
	s_ashr_i32 s4, s54, 3
	s_and_b32 s5, s5, 0x1000000
	v_readlane_b32 s6, v251, 0
	s_add_u32 s6, s6, s5
	v_readlane_b32 s5, v251, 1
	s_addc_u32 s7, s5, 0
	s_ashr_i32 s5, s4, 31
	s_lshl_b64 s[4:5], s[4:5], 22
	s_add_u32 s4, s6, s4
	s_addc_u32 s5, s7, s5
	s_lshl_b32 s6, s54, 9
	s_and_b32 s6, s6, 0x600
	s_add_u32 s4, s4, s6
	v_lshl_add_u32 v146, s90, 8, v1
	s_addc_u32 s5, s5, 0
	v_mov_b32_e32 v139, v0
	v_ashrrev_i32_e32 v147, 31, v146
	v_lshl_add_u64 v[148:149], s[4:5], 0, v[138:139]
	v_lshlrev_b64 v[142:143], 11, v[146:147]
	v_lshl_add_u64 v[142:143], v[148:149], 0, v[142:143]
	v_cvt_pk_bf16_f32 v126, v126, v127
	v_cvt_pk_bf16_f32 v127, v128, v129
	global_store_dwordx2 v[142:143], v[126:127], off
	v_cvt_pk_bf16_f32 v122, v122, v123
	v_cvt_pk_bf16_f32 v123, v124, v125
	global_store_dwordx2 v[142:143], v[122:123], off offset:32
	v_cvt_pk_bf16_f32 v114, v114, v115
	v_cvt_pk_bf16_f32 v115, v116, v117
	global_store_dwordx2 v[142:143], v[114:115], off offset:256
	v_cvt_pk_bf16_f32 v106, v106, v107
	v_cvt_pk_bf16_f32 v107, v108, v109
	global_store_dwordx2 v[142:143], v[106:107], off offset:288
	v_or_b32_e32 v106, 16, v146
	v_ashrrev_i32_e32 v107, 31, v106
	v_lshlrev_b64 v[106:107], 11, v[106:107]
	v_lshl_add_u64 v[106:107], v[148:149], 0, v[106:107]
	v_cvt_pk_bf16_f32 v108, v118, v119
	v_cvt_pk_bf16_f32 v109, v120, v121
	global_store_dwordx2 v[106:107], v[108:109], off
	v_cvt_pk_bf16_f32 v108, v110, v111
	v_cvt_pk_bf16_f32 v109, v112, v113
	global_store_dwordx2 v[106:107], v[108:109], off offset:32
	v_cvt_pk_bf16_f32 v98, v98, v99
	v_cvt_pk_bf16_f32 v99, v100, v101
	global_store_dwordx2 v[106:107], v[98:99], off offset:256
	v_cvt_pk_bf16_f32 v90, v90, v91
	v_cvt_pk_bf16_f32 v91, v92, v93
	global_store_dwordx2 v[106:107], v[90:91], off offset:288
	v_or_b32_e32 v90, 32, v146
	v_ashrrev_i32_e32 v91, 31, v90
	v_lshlrev_b64 v[90:91], 11, v[90:91]
	v_lshl_add_u64 v[90:91], v[148:149], 0, v[90:91]
	v_cvt_pk_bf16_f32 v92, v102, v103
	v_cvt_pk_bf16_f32 v93, v104, v105
	global_store_dwordx2 v[90:91], v[92:93], off
	v_cvt_pk_bf16_f32 v92, v94, v95
	v_cvt_pk_bf16_f32 v93, v96, v97
	global_store_dwordx2 v[90:91], v[92:93], off offset:32
	v_cvt_pk_bf16_f32 v82, v82, v83
	v_cvt_pk_bf16_f32 v83, v84, v85
	global_store_dwordx2 v[90:91], v[82:83], off offset:256
	v_cvt_pk_bf16_f32 v74, v74, v75
	v_cvt_pk_bf16_f32 v75, v76, v77
	global_store_dwordx2 v[90:91], v[74:75], off offset:288
	v_or_b32_e32 v74, 48, v146
	v_ashrrev_i32_e32 v75, 31, v74
	v_lshlrev_b64 v[74:75], 11, v[74:75]
	v_lshl_add_u64 v[74:75], v[148:149], 0, v[74:75]
	v_cvt_pk_bf16_f32 v76, v86, v87
	v_cvt_pk_bf16_f32 v77, v88, v89
	global_store_dwordx2 v[74:75], v[76:77], off
	v_cvt_pk_bf16_f32 v76, v78, v79
	v_cvt_pk_bf16_f32 v77, v80, v81
	global_store_dwordx2 v[74:75], v[76:77], off offset:32
	v_cvt_pk_bf16_f32 v70, v70, v71
	v_cvt_pk_bf16_f32 v71, v72, v73
	global_store_dwordx2 v[74:75], v[70:71], off offset:256
	v_cvt_pk_bf16_f32 v66, v66, v67
	v_cvt_pk_bf16_f32 v67, v68, v69
	s_mov_b64 s[4:5], 0x40000
	global_store_dwordx2 v[74:75], v[66:67], off offset:288
	v_lshl_add_u64 v[66:67], v[142:143], 0, s[4:5]
	s_mov_b32 s4, 0x40000
	v_cvt_pk_bf16_f32 v62, v62, v63
	v_cvt_pk_bf16_f32 v63, v64, v65
	v_add_co_u32_e32 v64, vcc, s4, v142
	s_mov_b64 s[4:5], 0x48000
	s_nop 0
	v_addc_co_u32_e32 v65, vcc, 0, v143, vcc
	global_store_dwordx2 v[64:65], v[62:63], off
	v_cvt_pk_bf16_f32 v58, v58, v59
	v_cvt_pk_bf16_f32 v59, v60, v61
	global_store_dwordx2 v[66:67], v[58:59], off offset:32
	v_cvt_pk_bf16_f32 v50, v50, v51
	v_cvt_pk_bf16_f32 v51, v52, v53
	global_store_dwordx2 v[66:67], v[50:51], off offset:256
	v_cvt_pk_bf16_f32 v42, v42, v43
	v_cvt_pk_bf16_f32 v43, v44, v45
	global_store_dwordx2 v[66:67], v[42:43], off offset:288
	v_lshl_add_u64 v[42:43], v[142:143], 0, s[4:5]
	s_mov_b32 s4, 0x48000
	v_add_co_u32_e32 v50, vcc, s4, v142
	v_cvt_pk_bf16_f32 v44, v54, v55
	v_cvt_pk_bf16_f32 v45, v56, v57
	s_mov_b64 s[4:5], 0x50000
	s_nop 0
	v_addc_co_u32_e32 v51, vcc, 0, v143, vcc
	global_store_dwordx2 v[50:51], v[44:45], off
	v_cvt_pk_bf16_f32 v44, v46, v47
	v_cvt_pk_bf16_f32 v45, v48, v49
	global_store_dwordx2 v[42:43], v[44:45], off offset:32
	v_cvt_pk_bf16_f32 v34, v34, v35
	v_cvt_pk_bf16_f32 v35, v36, v37
	global_store_dwordx2 v[42:43], v[34:35], off offset:256
	v_cvt_pk_bf16_f32 v26, v26, v27
	v_cvt_pk_bf16_f32 v27, v28, v29
	global_store_dwordx2 v[42:43], v[26:27], off offset:288
	v_lshl_add_u64 v[26:27], v[142:143], 0, s[4:5]
	s_mov_b32 s4, 0x50000
	v_add_co_u32_e32 v34, vcc, s4, v142
	v_cvt_pk_bf16_f32 v28, v38, v39
	v_cvt_pk_bf16_f32 v29, v40, v41
	s_mov_b64 s[4:5], 0x58000
	s_nop 0
	v_addc_co_u32_e32 v35, vcc, 0, v143, vcc
	global_store_dwordx2 v[34:35], v[28:29], off
	v_cvt_pk_bf16_f32 v28, v30, v31
	v_cvt_pk_bf16_f32 v29, v32, v33
	global_store_dwordx2 v[26:27], v[28:29], off offset:32
	v_cvt_pk_bf16_f32 v18, v18, v19
	v_cvt_pk_bf16_f32 v19, v20, v21
	global_store_dwordx2 v[26:27], v[18:19], off offset:256
	v_cvt_pk_bf16_f32 v10, v10, v11
	v_cvt_pk_bf16_f32 v11, v12, v13
	global_store_dwordx2 v[26:27], v[10:11], off offset:288
	v_lshl_add_u64 v[10:11], v[142:143], 0, s[4:5]
	s_mov_b32 s4, 0x58000
	v_add_co_u32_e32 v18, vcc, s4, v142
	v_cvt_pk_bf16_f32 v12, v22, v23
	v_cvt_pk_bf16_f32 v13, v24, v25
	s_mov_b32 s54, s44
	s_nop 0
	v_addc_co_u32_e32 v19, vcc, 0, v143, vcc
	global_store_dwordx2 v[18:19], v[12:13], off
	v_cvt_pk_bf16_f32 v12, v14, v15
	v_cvt_pk_bf16_f32 v13, v16, v17
	global_store_dwordx2 v[10:11], v[12:13], off offset:32
	v_cvt_pk_bf16_f32 v6, v6, v7
	v_cvt_pk_bf16_f32 v7, v8, v9
	global_store_dwordx2 v[10:11], v[6:7], off offset:256
	v_cvt_pk_bf16_f32 v2, v2, v3
	v_cvt_pk_bf16_f32 v3, v4, v5
	global_store_dwordx2 v[10:11], v[2:3], off offset:288
	s_and_b64 vcc, exec, s[38:39]
	s_mov_b32 s90, s45
	s_mov_b64 s[4:5], s[0:1]
	v_mov_b64_e32 v[2:3], v[140:141]
	s_cbranch_vccz .LBB0_433
	s_waitcnt vmcnt(0)
	s_cmpk_gt_u32 s2, 0xff
	s_mov_b32 s36, s65
	s_cbranch_scc1 .LBB0_444
	s_barrier

.LBB0_461:
	s_add_i32 s17, s4, 2
	s_add_i32 s42, 0, 0x10000
	s_cmp_eq_u32 s28, s4
	v_lshl_add_u64 v[150:151], v[148:149], 0, s[84:85]
	s_cselect_b64 vcc, -1, 0
	v_add_u32_e32 v171, s42, v166
	v_cndmask_b32_e32 v165, v151, v145, vcc
	v_cndmask_b32_e32 v164, v150, v144, vcc
	ds_read_b128 v[150:153], v171
	ds_read_b128 v[154:157], v171 offset:1024
	ds_read_b128 v[160:163], v171 offset:2048
	ds_read_b128 v[172:175], v171 offset:3072
	s_cselect_b32 s4, s0, s6
	s_cselect_b32 s5, s1, s7
	v_lshl_add_u64 v[208:209], v[148:149], 0, v[140:141]
	s_add_i32 m0, s8, 0xc000
	ds_read_b128 v[176:179], v169
	ds_read_b128 v[180:183], v169 offset:1024
	ds_read_b128 v[184:187], v169 offset:2048
	ds_read_b128 v[188:191], v169 offset:3072
	ds_read_b128 v[192:195], v169 offset:4096
	ds_read_b128 v[196:199], v169 offset:5120
	ds_read_b128 v[200:203], v169 offset:6144
	ds_read_b128 v[204:207], v169 offset:7168
	global_load_lds_dwordx4 v[208:209], off
	v_lshl_add_u64 v[208:209], v[148:149], 0, v[142:143]
	s_add_i32 m0, s8, 0xe000
	s_nop 0
	global_load_lds_dwordx4 v[208:209], off
	s_waitcnt lgkmcnt(8)
	s_barrier
	s_waitcnt lgkmcnt(0)
	s_waitcnt lgkmcnt(0)
	v_mfma_f32_16x16x32_bf16 v[126:129], v[150:153], v[176:179], v[126:129]
	v_mfma_f32_16x16x32_bf16 v[122:125], v[160:163], v[176:179], v[122:125]
	v_mfma_f32_16x16x32_bf16 v[110:113], v[150:153], v[184:187], v[110:113]
	v_mfma_f32_16x16x32_bf16 v[106:109], v[160:163], v[184:187], v[106:109]
	v_mfma_f32_16x16x32_bf16 v[94:97], v[150:153], v[192:195], v[94:97]
	v_mfma_f32_16x16x32_bf16 v[90:93], v[160:163], v[192:195], v[90:93]
	v_mfma_f32_16x16x32_bf16 v[78:81], v[150:153], v[200:203], v[78:81]
	v_mfma_f32_16x16x32_bf16 v[74:77], v[160:163], v[200:203], v[74:77]
	v_mfma_f32_16x16x32_bf16 v[126:129], v[154:157], v[180:183], v[126:129]
	v_mfma_f32_16x16x32_bf16 v[122:125], v[172:175], v[180:183], v[122:125]
	v_mfma_f32_16x16x32_bf16 v[110:113], v[154:157], v[188:191], v[110:113]
	v_mfma_f32_16x16x32_bf16 v[106:109], v[172:175], v[188:191], v[106:109]
	v_mfma_f32_16x16x32_bf16 v[94:97], v[154:157], v[196:199], v[94:97]
	v_mfma_f32_16x16x32_bf16 v[90:93], v[172:175], v[196:199], v[90:93]
	v_mfma_f32_16x16x32_bf16 v[78:81], v[154:157], v[204:207], v[78:81]
	v_mfma_f32_16x16x32_bf16 v[74:77], v[172:175], v[204:207], v[74:77]
	s_barrier
	s_add_i32 s43, 0, 0x14000
	s_add_i32 s42, s42, s3
	v_add_u32_e32 v171, s43, v166
	v_lshl_add_u64 v[224:225], s[4:5], 0, v[132:133]
	s_mov_b32 m0, s42
	ds_read_b128 v[208:211], v171
	ds_read_b128 v[212:215], v171 offset:1024
	ds_read_b128 v[216:219], v171 offset:2048
	ds_read_b128 v[238:241], v171 offset:3072
	global_load_lds_dwordx4 v[224:225], off
	v_lshl_add_u64 v[230:231], s[4:5], 0, v[136:137]
	s_add_i32 m0, s42, 0x2000
	s_nop 0
	global_load_lds_dwordx4 v[230:231], off
	s_barrier
	s_waitcnt lgkmcnt(0)
	s_waitcnt lgkmcnt(0)
	v_mfma_f32_16x16x32_bf16 v[118:121], v[208:211], v[176:179], v[118:121]
	v_mfma_f32_16x16x32_bf16 v[114:117], v[216:219], v[176:179], v[114:117]
	v_mfma_f32_16x16x32_bf16 v[102:105], v[208:211], v[184:187], v[102:105]
	v_mfma_f32_16x16x32_bf16 v[98:101], v[216:219], v[184:187], v[98:101]
	v_mfma_f32_16x16x32_bf16 v[86:89], v[208:211], v[192:195], v[86:89]
	v_mfma_f32_16x16x32_bf16 v[82:85], v[216:219], v[192:195], v[82:85]
	v_mfma_f32_16x16x32_bf16 v[70:73], v[208:211], v[200:203], v[70:73]
	v_mfma_f32_16x16x32_bf16 v[66:69], v[216:219], v[200:203], v[66:69]
	v_mfma_f32_16x16x32_bf16 v[118:121], v[212:215], v[180:183], v[118:121]
	v_mfma_f32_16x16x32_bf16 v[114:117], v[238:241], v[180:183], v[114:117]
	v_mfma_f32_16x16x32_bf16 v[102:105], v[212:215], v[188:191], v[102:105]
	v_mfma_f32_16x16x32_bf16 v[98:101], v[238:241], v[188:191], v[98:101]
	v_mfma_f32_16x16x32_bf16 v[86:89], v[212:215], v[196:199], v[86:89]
	v_mfma_f32_16x16x32_bf16 v[82:85], v[238:241], v[196:199], v[82:85]
	v_mfma_f32_16x16x32_bf16 v[70:73], v[212:215], v[204:207], v[70:73]
	v_mfma_f32_16x16x32_bf16 v[66:69], v[238:241], v[204:207], v[66:69]
	s_mov_b32 m0, s8
	v_lshl_add_u64 v[232:233], v[164:165], 0, v[130:131]
	s_barrier
	ds_read_b128 v[176:179], v169 offset:16384
	ds_read_b128 v[180:183], v169 offset:17408
	ds_read_b128 v[184:187], v169 offset:18432
	ds_read_b128 v[188:191], v169 offset:19456
	ds_read_b128 v[192:195], v169 offset:20480
	ds_read_b128 v[196:199], v169 offset:21504
	ds_read_b128 v[200:203], v169 offset:22528
	ds_read_b128 v[204:207], v169 offset:23552
	global_load_lds_dwordx4 v[232:233], off
	v_lshl_add_u64 v[242:243], v[164:165], 0, v[134:135]
	s_mov_b32 m0, s9
	s_nop 0
	global_load_lds_dwordx4 v[242:243], off
	s_barrier
	s_waitcnt lgkmcnt(0)
	s_waitcnt lgkmcnt(0)
	v_mfma_f32_16x16x32_bf16 v[54:57], v[150:153], v[176:179], v[54:57]
	v_mfma_f32_16x16x32_bf16 v[50:53], v[160:163], v[176:179], v[50:53]
	v_mfma_f32_16x16x32_bf16 v[38:41], v[150:153], v[184:187], v[38:41]
	v_mfma_f32_16x16x32_bf16 v[34:37], v[160:163], v[184:187], v[34:37]
	v_mfma_f32_16x16x32_bf16 v[22:25], v[150:153], v[192:195], v[22:25]
	v_mfma_f32_16x16x32_bf16 v[18:21], v[160:163], v[192:195], v[18:21]
	v_mfma_f32_16x16x32_bf16 v[6:9], v[150:153], v[200:203], v[6:9]
	v_mfma_f32_16x16x32_bf16 v[2:5], v[160:163], v[200:203], v[2:5]
	v_mfma_f32_16x16x32_bf16 v[54:57], v[154:157], v[180:183], v[54:57]
	v_mfma_f32_16x16x32_bf16 v[50:53], v[172:175], v[180:183], v[50:53]
	v_mfma_f32_16x16x32_bf16 v[38:41], v[154:157], v[188:191], v[38:41]
	v_mfma_f32_16x16x32_bf16 v[34:37], v[172:175], v[188:191], v[34:37]
	v_mfma_f32_16x16x32_bf16 v[22:25], v[154:157], v[196:199], v[22:25]
	v_mfma_f32_16x16x32_bf16 v[18:21], v[172:175], v[196:199], v[18:21]
	v_mfma_f32_16x16x32_bf16 v[6:9], v[154:157], v[204:207], v[6:9]
	v_mfma_f32_16x16x32_bf16 v[2:5], v[172:175], v[204:207], v[2:5]
	s_barrier
	s_add_u32 s4, s4, s94
	s_addc_u32 s5, s5, 0
	s_add_i32 s42, s43, s3
	v_lshl_add_u64 v[244:245], s[4:5], 0, v[132:133]
	s_mov_b32 m0, s42
	v_lshl_add_u64 v[246:247], s[4:5], 0, v[136:137]
	global_load_lds_dwordx4 v[244:245], off
	s_add_i32 m0, s42, 0x2000
	s_nop 0
	global_load_lds_dwordx4 v[246:247], off
	s_waitcnt vmcnt(6)
	s_barrier
	v_mfma_f32_16x16x32_bf16 v[62:65], v[208:211], v[176:179], v[62:65]
	v_mfma_f32_16x16x32_bf16 v[58:61], v[216:219], v[176:179], v[58:61]
	v_mfma_f32_16x16x32_bf16 v[46:49], v[208:211], v[184:187], v[46:49]
	v_mfma_f32_16x16x32_bf16 v[42:45], v[216:219], v[184:187], v[42:45]
	v_mfma_f32_16x16x32_bf16 v[30:33], v[208:211], v[192:195], v[30:33]
	v_mfma_f32_16x16x32_bf16 v[26:29], v[216:219], v[192:195], v[26:29]
	v_mfma_f32_16x16x32_bf16 v[14:17], v[208:211], v[200:203], v[14:17]
	v_mfma_f32_16x16x32_bf16 v[10:13], v[216:219], v[200:203], v[10:13]
	v_mfma_f32_16x16x32_bf16 v[62:65], v[212:215], v[180:183], v[62:65]
	v_mfma_f32_16x16x32_bf16 v[58:61], v[238:241], v[180:183], v[58:61]
	v_mfma_f32_16x16x32_bf16 v[46:49], v[212:215], v[188:191], v[46:49]
	v_mfma_f32_16x16x32_bf16 v[42:45], v[238:241], v[188:191], v[42:45]
	v_mfma_f32_16x16x32_bf16 v[30:33], v[212:215], v[196:199], v[30:33]
	v_mfma_f32_16x16x32_bf16 v[26:29], v[238:241], v[196:199], v[26:29]
	v_mfma_f32_16x16x32_bf16 v[14:17], v[212:215], v[204:207], v[14:17]
	v_mfma_f32_16x16x32_bf16 v[10:13], v[238:241], v[204:207], v[10:13]
	s_add_i32 s4, 0, 0x18000
	v_add_u32_e32 v171, s4, v166
	s_barrier
	ds_read_b128 v[150:153], v171
	ds_read_b128 v[154:157], v171 offset:1024
	ds_read_b128 v[160:163], v171 offset:2048
	ds_read_b128 v[172:175], v171 offset:3072
	v_lshl_add_u64 v[164:165], v[164:165], 0, s[94:95]
	s_mov_b32 m0, s10
	v_lshl_add_u64 v[208:209], v[164:165], 0, v[130:131]
	ds_read_b128 v[176:179], v169 offset:32768
	ds_read_b128 v[180:183], v169 offset:33792
	ds_read_b128 v[184:187], v169 offset:34816
	ds_read_b128 v[188:191], v169 offset:35840
	ds_read_b128 v[192:195], v169 offset:36864
	ds_read_b128 v[196:199], v169 offset:37888
	ds_read_b128 v[200:203], v169 offset:38912
	ds_read_b128 v[204:207], v169 offset:39936
	global_load_lds_dwordx4 v[208:209], off
	v_lshl_add_u64 v[164:165], v[164:165], 0, v[134:135]
	s_mov_b32 m0, s11
	s_nop 0
	global_load_lds_dwordx4 v[164:165], off
	s_waitcnt lgkmcnt(8)
	s_barrier
	s_waitcnt lgkmcnt(0)
	s_waitcnt lgkmcnt(0)
	v_mfma_f32_16x16x32_bf16 v[126:129], v[150:153], v[176:179], v[126:129]
	v_mfma_f32_16x16x32_bf16 v[122:125], v[160:163], v[176:179], v[122:125]
	v_mfma_f32_16x16x32_bf16 v[110:113], v[150:153], v[184:187], v[110:113]
	v_mfma_f32_16x16x32_bf16 v[106:109], v[160:163], v[184:187], v[106:109]
	v_mfma_f32_16x16x32_bf16 v[94:97], v[150:153], v[192:195], v[94:97]
	v_mfma_f32_16x16x32_bf16 v[90:93], v[160:163], v[192:195], v[90:93]
	v_mfma_f32_16x16x32_bf16 v[78:81], v[150:153], v[200:203], v[78:81]
	v_mfma_f32_16x16x32_bf16 v[74:77], v[160:163], v[200:203], v[74:77]
	v_mfma_f32_16x16x32_bf16 v[126:129], v[154:157], v[180:183], v[126:129]
	v_mfma_f32_16x16x32_bf16 v[122:125], v[172:175], v[180:183], v[122:125]
	v_mfma_f32_16x16x32_bf16 v[110:113], v[154:157], v[188:191], v[110:113]
	v_mfma_f32_16x16x32_bf16 v[106:109], v[172:175], v[188:191], v[106:109]
	v_mfma_f32_16x16x32_bf16 v[94:97], v[154:157], v[196:199], v[94:97]
	v_mfma_f32_16x16x32_bf16 v[90:93], v[172:175], v[196:199], v[90:93]
	v_mfma_f32_16x16x32_bf16 v[78:81], v[154:157], v[204:207], v[78:81]
	v_mfma_f32_16x16x32_bf16 v[74:77], v[172:175], v[204:207], v[74:77]
	s_barrier
	s_add_i32 s5, 0, 0x1c000
	v_add_u32_e32 v164, s5, v166
	s_add_i32 s4, s4, s3
	ds_read_b128 v[208:211], v164
	ds_read_b128 v[212:215], v164 offset:1024
	ds_read_b128 v[216:219], v164 offset:2048
	ds_read_b128 v[238:241], v164 offset:3072
	v_lshl_add_u64 v[164:165], v[224:225], 0, s[84:85]
	s_mov_b32 m0, s4
	s_nop 0
	global_load_lds_dwordx4 v[164:165], off
	v_lshl_add_u64 v[164:165], v[230:231], 0, s[84:85]
	s_add_i32 m0, s4, 0x2000
	s_nop 0
	global_load_lds_dwordx4 v[164:165], off
	s_barrier
	s_waitcnt lgkmcnt(0)
	s_waitcnt lgkmcnt(0)
	v_mfma_f32_16x16x32_bf16 v[118:121], v[208:211], v[176:179], v[118:121]
	v_mfma_f32_16x16x32_bf16 v[114:117], v[216:219], v[176:179], v[114:117]
	v_mfma_f32_16x16x32_bf16 v[102:105], v[208:211], v[184:187], v[102:105]
	v_mfma_f32_16x16x32_bf16 v[98:101], v[216:219], v[184:187], v[98:101]
	v_mfma_f32_16x16x32_bf16 v[86:89], v[208:211], v[192:195], v[86:89]
	v_mfma_f32_16x16x32_bf16 v[82:85], v[216:219], v[192:195], v[82:85]
	v_mfma_f32_16x16x32_bf16 v[70:73], v[208:211], v[200:203], v[70:73]
	v_mfma_f32_16x16x32_bf16 v[66:69], v[216:219], v[200:203], v[66:69]
	v_mfma_f32_16x16x32_bf16 v[118:121], v[212:215], v[180:183], v[118:121]
	v_mfma_f32_16x16x32_bf16 v[114:117], v[238:241], v[180:183], v[114:117]
	v_mfma_f32_16x16x32_bf16 v[102:105], v[212:215], v[188:191], v[102:105]
	v_mfma_f32_16x16x32_bf16 v[98:101], v[238:241], v[188:191], v[98:101]
	v_mfma_f32_16x16x32_bf16 v[86:89], v[212:215], v[196:199], v[86:89]
	v_mfma_f32_16x16x32_bf16 v[82:85], v[238:241], v[196:199], v[82:85]
	v_mfma_f32_16x16x32_bf16 v[70:73], v[212:215], v[204:207], v[70:73]
	v_mfma_f32_16x16x32_bf16 v[66:69], v[238:241], v[204:207], v[66:69]
	s_mov_b32 m0, s12
	v_lshl_add_u64 v[164:165], v[232:233], 0, s[84:85]
	s_barrier
	ds_read_b128 v[176:179], v169 offset:49152
	ds_read_b128 v[180:183], v169 offset:50176
	ds_read_b128 v[184:187], v169 offset:51200
	ds_read_b128 v[188:191], v169 offset:52224
	ds_read_b128 v[192:195], v169 offset:53248
	ds_read_b128 v[196:199], v169 offset:54272
	ds_read_b128 v[200:203], v169 offset:55296
	ds_read_b128 v[204:207], v169 offset:56320
	global_load_lds_dwordx4 v[164:165], off
	v_lshl_add_u64 v[164:165], v[242:243], 0, s[84:85]
	s_mov_b32 m0, s22
	s_nop 0
	global_load_lds_dwordx4 v[164:165], off
	s_barrier
	s_waitcnt lgkmcnt(0)
	s_waitcnt lgkmcnt(0)
	v_mfma_f32_16x16x32_bf16 v[54:57], v[150:153], v[176:179], v[54:57]
	v_mfma_f32_16x16x32_bf16 v[50:53], v[160:163], v[176:179], v[50:53]
	v_mfma_f32_16x16x32_bf16 v[38:41], v[150:153], v[184:187], v[38:41]
	v_mfma_f32_16x16x32_bf16 v[34:37], v[160:163], v[184:187], v[34:37]
	v_mfma_f32_16x16x32_bf16 v[22:25], v[150:153], v[192:195], v[22:25]
	v_mfma_f32_16x16x32_bf16 v[18:21], v[160:163], v[192:195], v[18:21]
	v_mfma_f32_16x16x32_bf16 v[6:9], v[150:153], v[200:203], v[6:9]
	v_mfma_f32_16x16x32_bf16 v[2:5], v[160:163], v[200:203], v[2:5]
	v_mfma_f32_16x16x32_bf16 v[54:57], v[154:157], v[180:183], v[54:57]
	v_mfma_f32_16x16x32_bf16 v[50:53], v[172:175], v[180:183], v[50:53]
	v_mfma_f32_16x16x32_bf16 v[38:41], v[154:157], v[188:191], v[38:41]
	v_mfma_f32_16x16x32_bf16 v[34:37], v[172:175], v[188:191], v[34:37]
	v_mfma_f32_16x16x32_bf16 v[22:25], v[154:157], v[196:199], v[22:25]
	v_mfma_f32_16x16x32_bf16 v[18:21], v[172:175], v[196:199], v[18:21]
	v_mfma_f32_16x16x32_bf16 v[6:9], v[154:157], v[204:207], v[6:9]
	v_mfma_f32_16x16x32_bf16 v[2:5], v[172:175], v[204:207], v[2:5]
	s_barrier
	s_add_i32 s4, s5, s3
	v_lshl_add_u64 v[150:151], v[244:245], 0, s[84:85]
	s_mov_b32 m0, s4
	s_nop 0
	global_load_lds_dwordx4 v[150:151], off
	v_lshl_add_u64 v[150:151], v[246:247], 0, s[84:85]
	s_add_i32 m0, s4, 0x2000
	s_nop 0
	global_load_lds_dwordx4 v[150:151], off
	s_waitcnt vmcnt(6)
	s_barrier
	v_mfma_f32_16x16x32_bf16 v[62:65], v[208:211], v[176:179], v[62:65]
	v_mfma_f32_16x16x32_bf16 v[58:61], v[216:219], v[176:179], v[58:61]
	v_mfma_f32_16x16x32_bf16 v[46:49], v[208:211], v[184:187], v[46:49]
	v_mfma_f32_16x16x32_bf16 v[42:45], v[216:219], v[184:187], v[42:45]
	v_mfma_f32_16x16x32_bf16 v[30:33], v[208:211], v[192:195], v[30:33]
	v_mfma_f32_16x16x32_bf16 v[26:29], v[216:219], v[192:195], v[26:29]
	v_mfma_f32_16x16x32_bf16 v[14:17], v[208:211], v[200:203], v[14:17]
	v_mfma_f32_16x16x32_bf16 v[10:13], v[216:219], v[200:203], v[10:13]
	v_mfma_f32_16x16x32_bf16 v[62:65], v[212:215], v[180:183], v[62:65]
	v_mfma_f32_16x16x32_bf16 v[58:61], v[238:241], v[180:183], v[58:61]
	v_mfma_f32_16x16x32_bf16 v[46:49], v[212:215], v[188:191], v[46:49]
	v_mfma_f32_16x16x32_bf16 v[42:45], v[238:241], v[188:191], v[42:45]
	v_mfma_f32_16x16x32_bf16 v[30:33], v[212:215], v[196:199], v[30:33]
	v_mfma_f32_16x16x32_bf16 v[26:29], v[238:241], v[196:199], v[26:29]
	v_mfma_f32_16x16x32_bf16 v[14:17], v[212:215], v[204:207], v[14:17]
	v_mfma_f32_16x16x32_bf16 v[10:13], v[238:241], v[204:207], v[10:13]
	s_add_u32 s6, s6, 0x100
	s_addc_u32 s7, s7, 0
	v_lshl_add_u64 v[148:149], v[148:149], 0, s[86:87]
	s_cmp_ge_u32 s17, s13
	s_mov_b32 s4, s17
	s_barrier
	s_cbranch_scc0 .LBB0_461
	v_cmp_lt_i32_e32 vcc, v227, v222
	ds_read2st64_b32 v[148:149], v170 offset1:1
	ds_read2st64_b32 v[150:151], v170 offset0:2 offset1:3
	ds_read2st64_b32 v[156:157], v170 offset0:4 offset1:5
	ds_read2st64_b32 v[160:161], v170 offset0:6 offset1:7
	v_cndmask_b32_e32 v152, v221, v227, vcc
	v_lshlrev_b32_e32 v171, 2, v152
	s_waitcnt lgkmcnt(0)
	ds_bpermute_b32 v153, v171, v148
	ds_bpermute_b32 v152, v171, v149
	v_cmp_lt_i32_e32 vcc, v228, v222
	v_mov_b32_e32 v155, v148
	s_mov_b32 s4, 0x3a800000
	v_cndmask_b32_e32 v154, v221, v228, vcc
	v_lshlrev_b32_e32 v172, 2, v154
	v_mov_b32_e32 v154, v149
	s_waitcnt lgkmcnt(0)
	v_pk_add_f32 v[148:149], v[154:155], v[152:153]
	ds_bpermute_b32 v153, v172, v149
	ds_bpermute_b32 v152, v172, v148
	ds_bpermute_b32 v174, v171, v161
	ds_bpermute_b32 v175, v171, v160
	s_waitcnt lgkmcnt(0)
	v_pk_add_f32 v[148:149], v[148:149], v[152:153]
	s_nop 0
	v_pk_fma_f32 v[162:163], v[148:149], s[4:5], v[158:159] op_sel_hi:[1,0,0]
	ds_bpermute_b32 v149, v171, v150
	v_mul_f32_e32 v148, 0x4b800000, v163
	v_cmp_gt_f32_e32 vcc, s88, v163
	s_nop 1
	v_cndmask_b32_e32 v148, v163, v148, vcc
	v_rsq_f32_e32 v152, v148
	ds_bpermute_b32 v148, v171, v151
	v_mul_f32_e32 v153, 0x45800000, v152
	v_cndmask_b32_e32 v164, v152, v153, vcc
	v_mov_b32_e32 v152, v151
	v_mov_b32_e32 v153, v150
	v_pk_mul_f32 v[128:129], v[128:129], v[164:165] op_sel_hi:[1,0]
	v_pk_mul_f32 v[124:125], v[124:125], v[164:165] op_sel_hi:[1,0]
	s_waitcnt lgkmcnt(0)
	v_pk_add_f32 v[152:153], v[152:153], v[148:149]
	v_pk_mul_f32 v[126:127], v[126:127], v[164:165] op_sel_hi:[1,0]
	v_max_f32_e32 v148, v128, v129
	v_pk_mul_f32 v[122:123], v[122:123], v[164:165] op_sel_hi:[1,0]
	v_max_f32_e32 v149, v124, v125
	v_max3_f32 v148, v126, v127, v148
	v_max3_f32 v149, v122, v123, v149
	v_pk_mul_f32 v[120:121], v[120:121], v[164:165] op_sel_hi:[1,0]
	v_pk_mul_f32 v[116:117], v[116:117], v[164:165] op_sel_hi:[1,0]
	v_max3_f32 v148, v148, s89, v149
	v_pk_mul_f32 v[118:119], v[118:119], v[164:165] op_sel_hi:[1,0]
	v_max_f32_e32 v149, v120, v121
	v_pk_mul_f32 v[114:115], v[114:115], v[164:165] op_sel_hi:[1,0]
	v_max_f32_e32 v150, v116, v117
	v_max3_f32 v149, v118, v119, v149
	v_max3_f32 v150, v114, v115, v150
	v_max3_f32 v163, v148, v149, v150
	ds_bpermute_b32 v164, v171, v163
	ds_bpermute_b32 v151, v171, v156
	v_mov_b32_e32 v149, v156
	v_mov_b32_e32 v148, v157
	ds_bpermute_b32 v150, v171, v157
	s_waitcnt lgkmcnt(0)
	v_max_f32_e32 v156, v164, v164
	v_max_f32_e32 v157, v163, v156
	ds_bpermute_b32 v163, v172, v157
	v_mov_b32_e32 v156, v161
	v_pk_add_f32 v[148:149], v[148:149], v[150:151]
	ds_bpermute_b32 v155, v172, v153
	ds_bpermute_b32 v154, v172, v152
	s_waitcnt lgkmcnt(0)
	v_max_f32_e32 v163, v163, v163
	v_max_f32_e32 v164, v157, v163
	v_sub_f32_e32 v157, v126, v164
	v_sub_f32_e32 v163, v127, v164
	v_sub_f32_e32 v165, v128, v164
	v_sub_f32_e32 v173, v129, v164
	v_mul_f32_e32 v157, 0x3fb8aa3b, v157
	v_mul_f32_e32 v163, 0x3fb8aa3b, v163
	v_mul_f32_e32 v165, 0x3fb8aa3b, v165
	v_mul_f32_e32 v173, 0x3fb8aa3b, v173
	v_exp_f32_e32 v157, v157
	v_exp_f32_e32 v163, v163
	v_exp_f32_e32 v165, v165
	v_exp_f32_e32 v173, v173
	v_sub_f32_e32 v176, v125, v164
	v_add_f32_e32 v157, v157, v163
	v_sub_f32_e32 v163, v122, v164
	v_add_f32_e32 v161, v165, v173
	v_sub_f32_e32 v165, v123, v164
	v_sub_f32_e32 v173, v124, v164
	v_mul_f32_e32 v163, 0x3fb8aa3b, v163
	v_mul_f32_e32 v165, 0x3fb8aa3b, v165
	v_mul_f32_e32 v173, 0x3fb8aa3b, v173
	v_mul_f32_e32 v176, 0x3fb8aa3b, v176
	v_exp_f32_e32 v163, v163
	v_exp_f32_e32 v165, v165
	v_exp_f32_e32 v173, v173
	v_exp_f32_e32 v176, v176
	v_add_f32_e32 v157, v157, v161
	v_add_f32_e32 v161, v163, v165
	v_sub_f32_e32 v165, v118, v164
	v_add_f32_e32 v163, v173, v176
	v_sub_f32_e32 v173, v119, v164
	v_sub_f32_e32 v176, v120, v164
	v_sub_f32_e32 v177, v121, v164
	v_mul_f32_e32 v165, 0x3fb8aa3b, v165
	v_mul_f32_e32 v173, 0x3fb8aa3b, v173
	v_mul_f32_e32 v176, 0x3fb8aa3b, v176
	v_mul_f32_e32 v177, 0x3fb8aa3b, v177
	v_exp_f32_e32 v165, v165
	v_exp_f32_e32 v173, v173
	v_exp_f32_e32 v176, v176
	v_exp_f32_e32 v177, v177
	v_add_f32_e32 v157, 0, v157
	v_add_f32_e32 v161, v161, v163
	v_add_f32_e32 v157, v161, v157
	v_add_f32_e32 v161, v165, v173
	v_add_f32_e32 v163, v176, v177
	v_sub_f32_e32 v165, v114, v164
	v_sub_f32_e32 v173, v115, v164
	v_sub_f32_e32 v176, v116, v164
	v_sub_f32_e32 v177, v117, v164
	v_mul_f32_e32 v165, 0x3fb8aa3b, v165
	v_mul_f32_e32 v173, 0x3fb8aa3b, v173
	v_mul_f32_e32 v176, 0x3fb8aa3b, v176
	v_mul_f32_e32 v177, 0x3fb8aa3b, v177
	v_exp_f32_e32 v165, v165
	v_exp_f32_e32 v173, v173
	v_exp_f32_e32 v176, v176
	v_exp_f32_e32 v177, v177
	v_add_f32_e32 v161, v161, v163
	v_add_f32_e32 v157, v161, v157
	v_add_f32_e32 v161, v165, v173
	v_add_f32_e32 v163, v176, v177
	v_add_f32_e32 v161, v161, v163
	v_add_f32_e32 v163, v161, v157
	ds_bpermute_b32 v165, v171, v163
	v_mov_b32_e32 v157, v160
	v_pk_add_f32 v[156:157], v[156:157], v[174:175]
	ds_bpermute_b32 v151, v172, v149
	ds_bpermute_b32 v150, v172, v148
	s_waitcnt lgkmcnt(0)
	v_add_f32_e32 v163, v163, v165
	ds_bpermute_b32 v161, v172, v157
	ds_bpermute_b32 v160, v172, v156
	ds_bpermute_b32 v165, v172, v163
	v_cmp_gt_f32_e32 vcc, s88, v162
	v_add_u32_e32 v173, s45, v168
	s_and_saveexec_b64 s[4:5], s[38:39]
	s_cbranch_execz .LBB0_464
	s_waitcnt lgkmcnt(0)
	v_add_f32_e32 v165, v163, v165
	ds_write_b64 v173, v[164:165]

.LBB0_519:
	s_add_i32 s10, s4, 2
	s_add_i32 s11, 0, 0x10000
	s_cmp_eq_u32 s23, s4
	v_lshl_add_u64 v[100:101], v[2:3], 0, s[84:85]
	s_cselect_b64 vcc, -1, 0
	v_add_u32_e32 v1, s11, v167
	v_cndmask_b32_e32 v157, v101, v155, vcc
	v_cndmask_b32_e32 v156, v100, v154, vcc
	ds_read_b128 v[100:103], v1
	ds_read_b128 v[104:107], v1 offset:1024
	ds_read_b128 v[160:163], v1 offset:2048
	ds_read_b128 v[170:173], v1 offset:3072
	s_cselect_b32 s4, s0, s6
	s_cselect_b32 s5, s1, s7
	v_lshl_add_u64 v[164:165], v[2:3], 0, v[150:151]
	s_add_i32 m0, s12, 0xc000
	ds_read_b128 v[174:177], v168
	ds_read_b128 v[178:181], v168 offset:1024
	ds_read_b128 v[182:185], v168 offset:2048
	ds_read_b128 v[186:189], v168 offset:3072
	ds_read_b128 v[190:193], v168 offset:4096
	ds_read_b128 v[194:197], v168 offset:5120
	ds_read_b128 v[198:201], v168 offset:6144
	ds_read_b128 v[202:205], v168 offset:7168
	global_load_lds_dwordx4 v[164:165], off
	v_lshl_add_u64 v[164:165], v[2:3], 0, v[152:153]
	s_add_i32 m0, s12, 0xe000
	s_nop 0
	global_load_lds_dwordx4 v[164:165], off
	s_waitcnt lgkmcnt(8)
	s_barrier
	s_waitcnt lgkmcnt(0)
	s_waitcnt lgkmcnt(0)
	v_mfma_f32_16x16x32_bf16 v[136:139], v[100:103], v[174:177], v[136:139]
	v_mfma_f32_16x16x32_bf16 v[132:135], v[160:163], v[174:177], v[132:135]
	v_mfma_f32_16x16x32_bf16 v[128:131], v[100:103], v[182:185], v[128:131]
	v_mfma_f32_16x16x32_bf16 v[124:127], v[160:163], v[182:185], v[124:127]
	v_mfma_f32_16x16x32_bf16 v[120:123], v[100:103], v[190:193], v[120:123]
	v_mfma_f32_16x16x32_bf16 v[116:119], v[160:163], v[190:193], v[116:119]
	v_mfma_f32_16x16x32_bf16 v[112:115], v[100:103], v[198:201], v[112:115]
	v_mfma_f32_16x16x32_bf16 v[108:111], v[160:163], v[198:201], v[108:111]
	v_mfma_f32_16x16x32_bf16 v[136:139], v[104:107], v[178:181], v[136:139]
	v_mfma_f32_16x16x32_bf16 v[132:135], v[170:173], v[178:181], v[132:135]
	v_mfma_f32_16x16x32_bf16 v[128:131], v[104:107], v[186:189], v[128:131]
	v_mfma_f32_16x16x32_bf16 v[124:127], v[170:173], v[186:189], v[124:127]
	v_mfma_f32_16x16x32_bf16 v[120:123], v[104:107], v[194:197], v[120:123]
	v_mfma_f32_16x16x32_bf16 v[116:119], v[170:173], v[194:197], v[116:119]
	v_mfma_f32_16x16x32_bf16 v[112:115], v[104:107], v[202:205], v[112:115]
	v_mfma_f32_16x16x32_bf16 v[108:111], v[170:173], v[202:205], v[108:111]
	s_barrier
	s_add_i32 s17, 0, 0x14000
	s_add_i32 s11, s11, s3
	v_add_u32_e32 v1, s17, v167
	v_lshl_add_u64 v[164:165], s[4:5], 0, v[142:143]
	s_mov_b32 m0, s11
	ds_read_b128 v[206:209], v1
	ds_read_b128 v[210:213], v1 offset:1024
	ds_read_b128 v[214:217], v1 offset:2048
	ds_read_b128 v[238:241], v1 offset:3072
	global_load_lds_dwordx4 v[164:165], off
	v_lshl_add_u64 v[218:219], s[4:5], 0, v[146:147]
	s_add_i32 m0, s11, 0x2000
	s_nop 0
	global_load_lds_dwordx4 v[218:219], off
	s_barrier
	s_waitcnt lgkmcnt(0)
	s_waitcnt lgkmcnt(0)
	v_mfma_f32_16x16x32_bf16 v[64:67], v[206:209], v[174:177], v[64:67]
	v_mfma_f32_16x16x32_bf16 v[60:63], v[214:217], v[174:177], v[60:63]
	v_mfma_f32_16x16x32_bf16 v[56:59], v[206:209], v[182:185], v[56:59]
	v_mfma_f32_16x16x32_bf16 v[52:55], v[214:217], v[182:185], v[52:55]
	v_mfma_f32_16x16x32_bf16 v[48:51], v[206:209], v[190:193], v[48:51]
	v_mfma_f32_16x16x32_bf16 v[44:47], v[214:217], v[190:193], v[44:47]
	v_mfma_f32_16x16x32_bf16 v[40:43], v[206:209], v[198:201], v[40:43]
	v_mfma_f32_16x16x32_bf16 v[36:39], v[214:217], v[198:201], v[36:39]
	v_mfma_f32_16x16x32_bf16 v[64:67], v[210:213], v[178:181], v[64:67]
	v_mfma_f32_16x16x32_bf16 v[60:63], v[238:241], v[178:181], v[60:63]
	v_mfma_f32_16x16x32_bf16 v[56:59], v[210:213], v[186:189], v[56:59]
	v_mfma_f32_16x16x32_bf16 v[52:55], v[238:241], v[186:189], v[52:55]
	v_mfma_f32_16x16x32_bf16 v[48:51], v[210:213], v[194:197], v[48:51]
	v_mfma_f32_16x16x32_bf16 v[44:47], v[238:241], v[194:197], v[44:47]
	v_mfma_f32_16x16x32_bf16 v[40:43], v[210:213], v[202:205], v[40:43]
	v_mfma_f32_16x16x32_bf16 v[36:39], v[238:241], v[202:205], v[36:39]
	s_mov_b32 m0, s12
	v_lshl_add_u64 v[224:225], v[156:157], 0, v[140:141]
	s_barrier
	ds_read_b128 v[174:177], v168 offset:16384
	ds_read_b128 v[178:181], v168 offset:17408
	ds_read_b128 v[182:185], v168 offset:18432
	ds_read_b128 v[186:189], v168 offset:19456
	ds_read_b128 v[190:193], v168 offset:20480
	ds_read_b128 v[194:197], v168 offset:21504
	ds_read_b128 v[198:201], v168 offset:22528
	ds_read_b128 v[202:205], v168 offset:23552
	global_load_lds_dwordx4 v[224:225], off
	v_lshl_add_u64 v[230:231], v[156:157], 0, v[144:145]
	s_mov_b32 m0, s35
	s_nop 0
	global_load_lds_dwordx4 v[230:231], off
	s_barrier
	s_waitcnt lgkmcnt(0)
	s_waitcnt lgkmcnt(0)
	v_mfma_f32_16x16x32_bf16 v[96:99], v[100:103], v[174:177], v[96:99]
	v_mfma_f32_16x16x32_bf16 v[92:95], v[160:163], v[174:177], v[92:95]
	v_mfma_f32_16x16x32_bf16 v[88:91], v[100:103], v[182:185], v[88:91]
	v_mfma_f32_16x16x32_bf16 v[84:87], v[160:163], v[182:185], v[84:87]
	v_mfma_f32_16x16x32_bf16 v[80:83], v[100:103], v[190:193], v[80:83]
	v_mfma_f32_16x16x32_bf16 v[76:79], v[160:163], v[190:193], v[76:79]
	v_mfma_f32_16x16x32_bf16 v[72:75], v[100:103], v[198:201], v[72:75]
	v_mfma_f32_16x16x32_bf16 v[68:71], v[160:163], v[198:201], v[68:71]
	v_mfma_f32_16x16x32_bf16 v[96:99], v[104:107], v[178:181], v[96:99]
	v_mfma_f32_16x16x32_bf16 v[92:95], v[170:173], v[178:181], v[92:95]
	v_mfma_f32_16x16x32_bf16 v[88:91], v[104:107], v[186:189], v[88:91]
	v_mfma_f32_16x16x32_bf16 v[84:87], v[170:173], v[186:189], v[84:87]
	v_mfma_f32_16x16x32_bf16 v[80:83], v[104:107], v[194:197], v[80:83]
	v_mfma_f32_16x16x32_bf16 v[76:79], v[170:173], v[194:197], v[76:79]
	v_mfma_f32_16x16x32_bf16 v[72:75], v[104:107], v[202:205], v[72:75]
	v_mfma_f32_16x16x32_bf16 v[68:71], v[170:173], v[202:205], v[68:71]
	s_barrier
	s_add_u32 s4, s4, s94
	s_addc_u32 s5, s5, 0
	s_add_i32 s11, s17, s3
	v_lshl_add_u64 v[232:233], s[4:5], 0, v[142:143]
	s_mov_b32 m0, s11
	v_lshl_add_u64 v[242:243], s[4:5], 0, v[146:147]
	global_load_lds_dwordx4 v[232:233], off
	s_add_i32 m0, s11, 0x2000
	s_nop 0
	global_load_lds_dwordx4 v[242:243], off
	s_waitcnt vmcnt(6)
	s_barrier
	v_mfma_f32_16x16x32_bf16 v[32:35], v[206:209], v[174:177], v[32:35]
	v_mfma_f32_16x16x32_bf16 v[28:31], v[214:217], v[174:177], v[28:31]
	v_mfma_f32_16x16x32_bf16 v[24:27], v[206:209], v[182:185], v[24:27]
	v_mfma_f32_16x16x32_bf16 v[20:23], v[214:217], v[182:185], v[20:23]
	v_mfma_f32_16x16x32_bf16 v[16:19], v[206:209], v[190:193], v[16:19]
	v_mfma_f32_16x16x32_bf16 v[12:15], v[214:217], v[190:193], v[12:15]
	v_mfma_f32_16x16x32_bf16 v[8:11], v[206:209], v[198:201], v[8:11]
	v_mfma_f32_16x16x32_bf16 v[4:7], v[214:217], v[198:201], v[4:7]
	v_mfma_f32_16x16x32_bf16 v[32:35], v[210:213], v[178:181], v[32:35]
	v_mfma_f32_16x16x32_bf16 v[28:31], v[238:241], v[178:181], v[28:31]
	v_mfma_f32_16x16x32_bf16 v[24:27], v[210:213], v[186:189], v[24:27]
	v_mfma_f32_16x16x32_bf16 v[20:23], v[238:241], v[186:189], v[20:23]
	v_mfma_f32_16x16x32_bf16 v[16:19], v[210:213], v[194:197], v[16:19]
	v_mfma_f32_16x16x32_bf16 v[12:15], v[238:241], v[194:197], v[12:15]
	v_mfma_f32_16x16x32_bf16 v[8:11], v[210:213], v[202:205], v[8:11]
	v_mfma_f32_16x16x32_bf16 v[4:7], v[238:241], v[202:205], v[4:7]
	s_add_i32 s4, 0, 0x18000
	v_add_u32_e32 v1, s4, v167
	s_barrier
	ds_read_b128 v[100:103], v1
	ds_read_b128 v[104:107], v1 offset:1024
	ds_read_b128 v[160:163], v1 offset:2048
	ds_read_b128 v[170:173], v1 offset:3072
	v_lshl_add_u64 v[156:157], v[156:157], 0, s[94:95]
	s_mov_b32 m0, s44
	v_lshl_add_u64 v[206:207], v[156:157], 0, v[140:141]
	ds_read_b128 v[174:177], v168 offset:32768
	ds_read_b128 v[178:181], v168 offset:33792
	ds_read_b128 v[182:185], v168 offset:34816
	ds_read_b128 v[186:189], v168 offset:35840
	ds_read_b128 v[190:193], v168 offset:36864
	ds_read_b128 v[194:197], v168 offset:37888
	ds_read_b128 v[198:201], v168 offset:38912
	ds_read_b128 v[202:205], v168 offset:39936
	global_load_lds_dwordx4 v[206:207], off
	v_lshl_add_u64 v[156:157], v[156:157], 0, v[144:145]
	s_mov_b32 m0, s45
	s_nop 0
	global_load_lds_dwordx4 v[156:157], off
	s_waitcnt lgkmcnt(8)
	s_barrier
	s_waitcnt lgkmcnt(0)
	s_waitcnt lgkmcnt(0)
	v_mfma_f32_16x16x32_bf16 v[136:139], v[100:103], v[174:177], v[136:139]
	v_mfma_f32_16x16x32_bf16 v[132:135], v[160:163], v[174:177], v[132:135]
	v_mfma_f32_16x16x32_bf16 v[128:131], v[100:103], v[182:185], v[128:131]
	v_mfma_f32_16x16x32_bf16 v[124:127], v[160:163], v[182:185], v[124:127]
	v_mfma_f32_16x16x32_bf16 v[120:123], v[100:103], v[190:193], v[120:123]
	v_mfma_f32_16x16x32_bf16 v[116:119], v[160:163], v[190:193], v[116:119]
	v_mfma_f32_16x16x32_bf16 v[112:115], v[100:103], v[198:201], v[112:115]
	v_mfma_f32_16x16x32_bf16 v[108:111], v[160:163], v[198:201], v[108:111]
	v_mfma_f32_16x16x32_bf16 v[136:139], v[104:107], v[178:181], v[136:139]
	v_mfma_f32_16x16x32_bf16 v[132:135], v[170:173], v[178:181], v[132:135]
	v_mfma_f32_16x16x32_bf16 v[128:131], v[104:107], v[186:189], v[128:131]
	v_mfma_f32_16x16x32_bf16 v[124:127], v[170:173], v[186:189], v[124:127]
	v_mfma_f32_16x16x32_bf16 v[120:123], v[104:107], v[194:197], v[120:123]
	v_mfma_f32_16x16x32_bf16 v[116:119], v[170:173], v[194:197], v[116:119]
	v_mfma_f32_16x16x32_bf16 v[112:115], v[104:107], v[202:205], v[112:115]
	v_mfma_f32_16x16x32_bf16 v[108:111], v[170:173], v[202:205], v[108:111]
	s_barrier
	s_add_i32 s5, 0, 0x1c000
	s_add_i32 s4, s4, s3
	v_add_u32_e32 v1, s5, v167
	v_lshl_add_u64 v[156:157], v[164:165], 0, s[84:85]
	s_mov_b32 m0, s4
	ds_read_b128 v[206:209], v1
	ds_read_b128 v[210:213], v1 offset:1024
	ds_read_b128 v[214:217], v1 offset:2048
	ds_read_b128 v[238:241], v1 offset:3072
	global_load_lds_dwordx4 v[156:157], off
	v_lshl_add_u64 v[156:157], v[218:219], 0, s[84:85]
	s_add_i32 m0, s4, 0x2000
	s_nop 0
	global_load_lds_dwordx4 v[156:157], off
	s_barrier
	s_waitcnt lgkmcnt(0)
	s_waitcnt lgkmcnt(0)
	v_mfma_f32_16x16x32_bf16 v[64:67], v[206:209], v[174:177], v[64:67]
	v_mfma_f32_16x16x32_bf16 v[60:63], v[214:217], v[174:177], v[60:63]
	v_mfma_f32_16x16x32_bf16 v[56:59], v[206:209], v[182:185], v[56:59]
	v_mfma_f32_16x16x32_bf16 v[52:55], v[214:217], v[182:185], v[52:55]
	v_mfma_f32_16x16x32_bf16 v[48:51], v[206:209], v[190:193], v[48:51]
	v_mfma_f32_16x16x32_bf16 v[44:47], v[214:217], v[190:193], v[44:47]
	v_mfma_f32_16x16x32_bf16 v[40:43], v[206:209], v[198:201], v[40:43]
	v_mfma_f32_16x16x32_bf16 v[36:39], v[214:217], v[198:201], v[36:39]
	v_mfma_f32_16x16x32_bf16 v[64:67], v[210:213], v[178:181], v[64:67]
	v_mfma_f32_16x16x32_bf16 v[60:63], v[238:241], v[178:181], v[60:63]
	v_mfma_f32_16x16x32_bf16 v[56:59], v[210:213], v[186:189], v[56:59]
	v_mfma_f32_16x16x32_bf16 v[52:55], v[238:241], v[186:189], v[52:55]
	v_mfma_f32_16x16x32_bf16 v[48:51], v[210:213], v[194:197], v[48:51]
	v_mfma_f32_16x16x32_bf16 v[44:47], v[238:241], v[194:197], v[44:47]
	v_mfma_f32_16x16x32_bf16 v[40:43], v[210:213], v[202:205], v[40:43]
	v_mfma_f32_16x16x32_bf16 v[36:39], v[238:241], v[202:205], v[36:39]
	s_mov_b32 m0, s54
	v_lshl_add_u64 v[156:157], v[224:225], 0, s[84:85]
	s_barrier
	ds_read_b128 v[174:177], v168 offset:49152
	ds_read_b128 v[178:181], v168 offset:50176
	ds_read_b128 v[182:185], v168 offset:51200
	ds_read_b128 v[186:189], v168 offset:52224
	ds_read_b128 v[190:193], v168 offset:53248
	ds_read_b128 v[194:197], v168 offset:54272
	ds_read_b128 v[198:201], v168 offset:55296
	ds_read_b128 v[202:205], v168 offset:56320
	global_load_lds_dwordx4 v[156:157], off
	v_lshl_add_u64 v[156:157], v[230:231], 0, s[84:85]
	s_mov_b32 m0, s2
	s_nop 0
	global_load_lds_dwordx4 v[156:157], off
	s_barrier
	s_waitcnt lgkmcnt(0)
	s_waitcnt lgkmcnt(0)
	v_mfma_f32_16x16x32_bf16 v[96:99], v[100:103], v[174:177], v[96:99]
	v_mfma_f32_16x16x32_bf16 v[92:95], v[160:163], v[174:177], v[92:95]
	v_mfma_f32_16x16x32_bf16 v[88:91], v[100:103], v[182:185], v[88:91]
	v_mfma_f32_16x16x32_bf16 v[84:87], v[160:163], v[182:185], v[84:87]
	v_mfma_f32_16x16x32_bf16 v[80:83], v[100:103], v[190:193], v[80:83]
	v_mfma_f32_16x16x32_bf16 v[76:79], v[160:163], v[190:193], v[76:79]
	v_mfma_f32_16x16x32_bf16 v[72:75], v[100:103], v[198:201], v[72:75]
	v_mfma_f32_16x16x32_bf16 v[68:71], v[160:163], v[198:201], v[68:71]
	v_mfma_f32_16x16x32_bf16 v[96:99], v[104:107], v[178:181], v[96:99]
	v_mfma_f32_16x16x32_bf16 v[92:95], v[170:173], v[178:181], v[92:95]
	v_mfma_f32_16x16x32_bf16 v[88:91], v[104:107], v[186:189], v[88:91]
	v_mfma_f32_16x16x32_bf16 v[84:87], v[170:173], v[186:189], v[84:87]
	v_mfma_f32_16x16x32_bf16 v[80:83], v[104:107], v[194:197], v[80:83]
	v_mfma_f32_16x16x32_bf16 v[76:79], v[170:173], v[194:197], v[76:79]
	v_mfma_f32_16x16x32_bf16 v[72:75], v[104:107], v[202:205], v[72:75]
	v_mfma_f32_16x16x32_bf16 v[68:71], v[170:173], v[202:205], v[68:71]
	s_barrier
	s_add_i32 s4, s5, s3
	v_lshl_add_u64 v[100:101], v[232:233], 0, s[84:85]
	s_mov_b32 m0, s4
	s_nop 0
	global_load_lds_dwordx4 v[100:101], off
	v_lshl_add_u64 v[100:101], v[242:243], 0, s[84:85]
	s_add_i32 m0, s4, 0x2000
	s_nop 0
	global_load_lds_dwordx4 v[100:101], off
	s_waitcnt vmcnt(6)
	s_barrier
	v_mfma_f32_16x16x32_bf16 v[32:35], v[206:209], v[174:177], v[32:35]
	v_mfma_f32_16x16x32_bf16 v[28:31], v[214:217], v[174:177], v[28:31]
	v_mfma_f32_16x16x32_bf16 v[24:27], v[206:209], v[182:185], v[24:27]
	v_mfma_f32_16x16x32_bf16 v[20:23], v[214:217], v[182:185], v[20:23]
	v_mfma_f32_16x16x32_bf16 v[16:19], v[206:209], v[190:193], v[16:19]
	v_mfma_f32_16x16x32_bf16 v[12:15], v[214:217], v[190:193], v[12:15]
	v_mfma_f32_16x16x32_bf16 v[8:11], v[206:209], v[198:201], v[8:11]
	v_mfma_f32_16x16x32_bf16 v[4:7], v[214:217], v[198:201], v[4:7]
	v_mfma_f32_16x16x32_bf16 v[32:35], v[210:213], v[178:181], v[32:35]
	v_mfma_f32_16x16x32_bf16 v[28:31], v[238:241], v[178:181], v[28:31]
	v_mfma_f32_16x16x32_bf16 v[24:27], v[210:213], v[186:189], v[24:27]
	v_mfma_f32_16x16x32_bf16 v[20:23], v[238:241], v[186:189], v[20:23]
	v_mfma_f32_16x16x32_bf16 v[16:19], v[210:213], v[194:197], v[16:19]
	v_mfma_f32_16x16x32_bf16 v[12:15], v[238:241], v[194:197], v[12:15]
	v_mfma_f32_16x16x32_bf16 v[8:11], v[210:213], v[202:205], v[8:11]
	v_mfma_f32_16x16x32_bf16 v[4:7], v[238:241], v[202:205], v[4:7]
	s_add_u32 s6, s6, 0x100
	s_addc_u32 s7, s7, 0
	v_lshl_add_u64 v[2:3], v[2:3], 0, s[86:87]
	s_cmp_ge_u32 s10, s13
	s_mov_b32 s4, s10
	s_barrier
	s_cbranch_scc0 .LBB0_519
	s_lshl_b32 s4, s8, 8
	v_lshl_add_u32 v169, s9, 8, v166
	s_cmp_lt_i32 s8, 5
	s_movk_i32 s96, 0x180
	s_cbranch_scc0 .LBB0_575
	s_add_i32 s5, s4, 0x17f
	s_cmpk_gt_u32 s5, 0x2fe
	v_or_b32_e32 v156, s4, v148
	s_cselect_b64 s[6:7], -1, 0
	s_and_b64 vcc, exec, s[6:7]
	v_ashrrev_i32_e32 v157, 31, v156
	s_cbranch_vccnz .LBB0_523
	v_lshl_add_u64 v[2:3], v[156:157], 2, s[68:69]
	global_load_dwordx4 v[100:103], v[2:3], off offset:16
	global_load_dwordx4 v[104:107], v[2:3], off
	s_branch .LBB0_524

.LBB0_649:
	s_add_i32 s42, s4, 2
	s_add_i32 s43, 0, 0x10000
	s_cmp_eq_u32 s35, s4
	v_lshl_add_u64 v[132:133], v[130:131], 0, s[84:85]
	s_cselect_b64 vcc, -1, 0
	v_add_u32_e32 v144, s43, v237
	v_cndmask_b32_e32 v157, v133, v177, vcc
	v_cndmask_b32_e32 v156, v132, v176, vcc
	ds_read_b128 v[132:135], v144
	ds_read_b128 v[136:139], v144 offset:1024
	ds_read_b128 v[140:143], v144 offset:2048
	ds_read_b128 v[144:147], v144 offset:3072
	s_cselect_b32 s4, s0, s6
	s_cselect_b32 s5, s1, s7
	v_lshl_add_u64 v[202:203], v[130:131], 0, v[172:173]
	s_add_i32 m0, s8, 0xc000
	ds_read_b128 v[148:151], v243
	ds_read_b128 v[152:155], v243 offset:1024
	ds_read_b128 v[178:181], v243 offset:2048
	ds_read_b128 v[182:185], v243 offset:3072
	ds_read_b128 v[186:189], v243 offset:4096
	ds_read_b128 v[190:193], v243 offset:5120
	ds_read_b128 v[194:197], v243 offset:6144
	ds_read_b128 v[198:201], v243 offset:7168
	global_load_lds_dwordx4 v[202:203], off
	v_lshl_add_u64 v[202:203], v[130:131], 0, v[174:175]
	s_add_i32 m0, s8, 0xe000
	s_nop 0
	global_load_lds_dwordx4 v[202:203], off
	s_waitcnt lgkmcnt(8)
	s_barrier
	s_waitcnt lgkmcnt(0)
	s_waitcnt lgkmcnt(0)
	v_mfma_f32_16x16x32_bf16 v[126:129], v[132:135], v[148:151], v[126:129]
	v_mfma_f32_16x16x32_bf16 v[122:125], v[140:143], v[148:151], v[122:125]
	v_mfma_f32_16x16x32_bf16 v[110:113], v[132:135], v[178:181], v[110:113]
	v_mfma_f32_16x16x32_bf16 v[106:109], v[140:143], v[178:181], v[106:109]
	v_mfma_f32_16x16x32_bf16 v[98:101], v[132:135], v[186:189], v[98:101]
	v_mfma_f32_16x16x32_bf16 v[90:93], v[140:143], v[186:189], v[90:93]
	v_mfma_f32_16x16x32_bf16 v[82:85], v[132:135], v[194:197], v[82:85]
	v_mfma_f32_16x16x32_bf16 v[74:77], v[140:143], v[194:197], v[74:77]
	v_mfma_f32_16x16x32_bf16 v[126:129], v[136:139], v[152:155], v[126:129]
	v_mfma_f32_16x16x32_bf16 v[122:125], v[144:147], v[152:155], v[122:125]
	v_mfma_f32_16x16x32_bf16 v[110:113], v[136:139], v[182:185], v[110:113]
	v_mfma_f32_16x16x32_bf16 v[106:109], v[144:147], v[182:185], v[106:109]
	v_mfma_f32_16x16x32_bf16 v[98:101], v[136:139], v[190:193], v[98:101]
	v_mfma_f32_16x16x32_bf16 v[90:93], v[144:147], v[190:193], v[90:93]
	v_mfma_f32_16x16x32_bf16 v[82:85], v[136:139], v[198:201], v[82:85]
	v_mfma_f32_16x16x32_bf16 v[74:77], v[144:147], v[198:201], v[74:77]
	s_barrier
	s_add_i32 s89, 0, 0x14000
	s_add_i32 s43, s43, s3
	v_add_u32_e32 v169, s89, v237
	v_lshl_add_u64 v[218:219], s[4:5], 0, v[162:163]
	s_mov_b32 m0, s43
	ds_read_b128 v[202:205], v169
	ds_read_b128 v[206:209], v169 offset:1024
	ds_read_b128 v[210:213], v169 offset:2048
	ds_read_b128 v[214:217], v169 offset:3072
	global_load_lds_dwordx4 v[218:219], off
	v_lshl_add_u64 v[224:225], s[4:5], 0, v[166:167]
	s_add_i32 m0, s43, 0x2000
	s_nop 0
	global_load_lds_dwordx4 v[224:225], off
	s_barrier
	s_waitcnt lgkmcnt(0)
	s_waitcnt lgkmcnt(0)
	v_mfma_f32_16x16x32_bf16 v[118:121], v[202:205], v[148:151], v[118:121]
	v_mfma_f32_16x16x32_bf16 v[114:117], v[210:213], v[148:151], v[114:117]
	v_mfma_f32_16x16x32_bf16 v[102:105], v[202:205], v[178:181], v[102:105]
	v_mfma_f32_16x16x32_bf16 v[94:97], v[210:213], v[178:181], v[94:97]
	v_mfma_f32_16x16x32_bf16 v[86:89], v[202:205], v[186:189], v[86:89]
	v_mfma_f32_16x16x32_bf16 v[78:81], v[210:213], v[186:189], v[78:81]
	v_mfma_f32_16x16x32_bf16 v[70:73], v[202:205], v[194:197], v[70:73]
	v_mfma_f32_16x16x32_bf16 v[66:69], v[210:213], v[194:197], v[66:69]
	v_mfma_f32_16x16x32_bf16 v[118:121], v[206:209], v[152:155], v[118:121]
	v_mfma_f32_16x16x32_bf16 v[114:117], v[214:217], v[152:155], v[114:117]
	v_mfma_f32_16x16x32_bf16 v[102:105], v[206:209], v[182:185], v[102:105]
	v_mfma_f32_16x16x32_bf16 v[94:97], v[214:217], v[182:185], v[94:97]
	v_mfma_f32_16x16x32_bf16 v[86:89], v[206:209], v[190:193], v[86:89]
	v_mfma_f32_16x16x32_bf16 v[78:81], v[214:217], v[190:193], v[78:81]
	v_mfma_f32_16x16x32_bf16 v[70:73], v[206:209], v[198:201], v[70:73]
	v_mfma_f32_16x16x32_bf16 v[66:69], v[214:217], v[198:201], v[66:69]
	s_mov_b32 m0, s8
	v_lshl_add_u64 v[230:231], v[156:157], 0, v[160:161]
	s_barrier
	ds_read_b128 v[148:151], v243 offset:16384
	ds_read_b128 v[152:155], v243 offset:17408
	ds_read_b128 v[178:181], v243 offset:18432
	ds_read_b128 v[182:185], v243 offset:19456
	ds_read_b128 v[186:189], v243 offset:20480
	ds_read_b128 v[190:193], v243 offset:21504
	ds_read_b128 v[194:197], v243 offset:22528
	ds_read_b128 v[198:201], v243 offset:23552
	global_load_lds_dwordx4 v[230:231], off
	v_lshl_add_u64 v[232:233], v[156:157], 0, v[164:165]
	s_mov_b32 m0, s9
	s_nop 0
	global_load_lds_dwordx4 v[232:233], off
	s_barrier
	s_waitcnt lgkmcnt(0)
	s_waitcnt lgkmcnt(0)
	v_mfma_f32_16x16x32_bf16 v[62:65], v[132:135], v[148:151], v[62:65]
	v_mfma_f32_16x16x32_bf16 v[58:61], v[140:143], v[148:151], v[58:61]
	v_mfma_f32_16x16x32_bf16 v[46:49], v[132:135], v[178:181], v[46:49]
	v_mfma_f32_16x16x32_bf16 v[42:45], v[140:143], v[178:181], v[42:45]
	v_mfma_f32_16x16x32_bf16 v[34:37], v[132:135], v[186:189], v[34:37]
	v_mfma_f32_16x16x32_bf16 v[26:29], v[140:143], v[186:189], v[26:29]
	v_mfma_f32_16x16x32_bf16 v[18:21], v[132:135], v[194:197], v[18:21]
	v_mfma_f32_16x16x32_bf16 v[10:13], v[140:143], v[194:197], v[10:13]
	v_mfma_f32_16x16x32_bf16 v[62:65], v[136:139], v[152:155], v[62:65]
	v_mfma_f32_16x16x32_bf16 v[58:61], v[144:147], v[152:155], v[58:61]
	v_mfma_f32_16x16x32_bf16 v[46:49], v[136:139], v[182:185], v[46:49]
	v_mfma_f32_16x16x32_bf16 v[42:45], v[144:147], v[182:185], v[42:45]
	v_mfma_f32_16x16x32_bf16 v[34:37], v[136:139], v[190:193], v[34:37]
	v_mfma_f32_16x16x32_bf16 v[26:29], v[144:147], v[190:193], v[26:29]
	v_mfma_f32_16x16x32_bf16 v[18:21], v[136:139], v[198:201], v[18:21]
	v_mfma_f32_16x16x32_bf16 v[10:13], v[144:147], v[198:201], v[10:13]
	s_barrier
	s_add_u32 s4, s4, s94
	s_addc_u32 s5, s5, 0
	s_add_i32 s43, s89, s3
	v_lshl_add_u64 v[244:245], s[4:5], 0, v[162:163]
	s_mov_b32 m0, s43
	v_lshl_add_u64 v[246:247], s[4:5], 0, v[166:167]
	global_load_lds_dwordx4 v[244:245], off
	s_add_i32 m0, s43, 0x2000
	s_nop 0
	global_load_lds_dwordx4 v[246:247], off
	s_waitcnt vmcnt(6)
	s_barrier
	v_mfma_f32_16x16x32_bf16 v[54:57], v[202:205], v[148:151], v[54:57]
	v_mfma_f32_16x16x32_bf16 v[50:53], v[210:213], v[148:151], v[50:53]
	v_mfma_f32_16x16x32_bf16 v[38:41], v[202:205], v[178:181], v[38:41]
	v_mfma_f32_16x16x32_bf16 v[30:33], v[210:213], v[178:181], v[30:33]
	v_mfma_f32_16x16x32_bf16 v[22:25], v[202:205], v[186:189], v[22:25]
	v_mfma_f32_16x16x32_bf16 v[14:17], v[210:213], v[186:189], v[14:17]
	v_mfma_f32_16x16x32_bf16 v[6:9], v[202:205], v[194:197], v[6:9]
	v_mfma_f32_16x16x32_bf16 v[2:5], v[210:213], v[194:197], v[2:5]
	v_mfma_f32_16x16x32_bf16 v[54:57], v[206:209], v[152:155], v[54:57]
	v_mfma_f32_16x16x32_bf16 v[50:53], v[214:217], v[152:155], v[50:53]
	v_mfma_f32_16x16x32_bf16 v[38:41], v[206:209], v[182:185], v[38:41]
	v_mfma_f32_16x16x32_bf16 v[30:33], v[214:217], v[182:185], v[30:33]
	v_mfma_f32_16x16x32_bf16 v[22:25], v[206:209], v[190:193], v[22:25]
	v_mfma_f32_16x16x32_bf16 v[14:17], v[214:217], v[190:193], v[14:17]
	v_mfma_f32_16x16x32_bf16 v[6:9], v[206:209], v[198:201], v[6:9]
	v_mfma_f32_16x16x32_bf16 v[2:5], v[214:217], v[198:201], v[2:5]
	s_add_i32 s4, 0, 0x18000
	v_add_u32_e32 v144, s4, v237
	s_barrier
	ds_read_b128 v[132:135], v144
	ds_read_b128 v[136:139], v144 offset:1024
	ds_read_b128 v[140:143], v144 offset:2048
	ds_read_b128 v[144:147], v144 offset:3072
	v_lshl_add_u64 v[156:157], v[156:157], 0, s[94:95]
	s_mov_b32 m0, s10
	v_lshl_add_u64 v[202:203], v[156:157], 0, v[160:161]
	ds_read_b128 v[148:151], v243 offset:32768
	ds_read_b128 v[152:155], v243 offset:33792
	ds_read_b128 v[178:181], v243 offset:34816
	ds_read_b128 v[182:185], v243 offset:35840
	ds_read_b128 v[186:189], v243 offset:36864
	ds_read_b128 v[190:193], v243 offset:37888
	ds_read_b128 v[194:197], v243 offset:38912
	ds_read_b128 v[198:201], v243 offset:39936
	global_load_lds_dwordx4 v[202:203], off
	v_lshl_add_u64 v[156:157], v[156:157], 0, v[164:165]
	s_mov_b32 m0, s11
	s_nop 0
	global_load_lds_dwordx4 v[156:157], off
	s_waitcnt lgkmcnt(8)
	s_barrier
	s_waitcnt lgkmcnt(0)
	s_waitcnt lgkmcnt(0)
	v_mfma_f32_16x16x32_bf16 v[126:129], v[132:135], v[148:151], v[126:129]
	v_mfma_f32_16x16x32_bf16 v[122:125], v[140:143], v[148:151], v[122:125]
	v_mfma_f32_16x16x32_bf16 v[110:113], v[132:135], v[178:181], v[110:113]
	v_mfma_f32_16x16x32_bf16 v[106:109], v[140:143], v[178:181], v[106:109]
	v_mfma_f32_16x16x32_bf16 v[98:101], v[132:135], v[186:189], v[98:101]
	v_mfma_f32_16x16x32_bf16 v[90:93], v[140:143], v[186:189], v[90:93]
	v_mfma_f32_16x16x32_bf16 v[82:85], v[132:135], v[194:197], v[82:85]
	v_mfma_f32_16x16x32_bf16 v[74:77], v[140:143], v[194:197], v[74:77]
	v_mfma_f32_16x16x32_bf16 v[126:129], v[136:139], v[152:155], v[126:129]
	v_mfma_f32_16x16x32_bf16 v[122:125], v[144:147], v[152:155], v[122:125]
	v_mfma_f32_16x16x32_bf16 v[110:113], v[136:139], v[182:185], v[110:113]
	v_mfma_f32_16x16x32_bf16 v[106:109], v[144:147], v[182:185], v[106:109]
	v_mfma_f32_16x16x32_bf16 v[98:101], v[136:139], v[190:193], v[98:101]
	v_mfma_f32_16x16x32_bf16 v[90:93], v[144:147], v[190:193], v[90:93]
	v_mfma_f32_16x16x32_bf16 v[82:85], v[136:139], v[198:201], v[82:85]
	v_mfma_f32_16x16x32_bf16 v[74:77], v[144:147], v[198:201], v[74:77]
	s_barrier
	s_add_i32 s5, 0, 0x1c000
	v_add_u32_e32 v156, s5, v237
	s_add_i32 s4, s4, s3
	ds_read_b128 v[202:205], v156
	ds_read_b128 v[206:209], v156 offset:1024
	ds_read_b128 v[210:213], v156 offset:2048
	ds_read_b128 v[214:217], v156 offset:3072
	v_lshl_add_u64 v[156:157], v[218:219], 0, s[84:85]
	s_mov_b32 m0, s4
	s_nop 0
	global_load_lds_dwordx4 v[156:157], off
	v_lshl_add_u64 v[156:157], v[224:225], 0, s[84:85]
	s_add_i32 m0, s4, 0x2000
	s_nop 0
	global_load_lds_dwordx4 v[156:157], off
	s_barrier
	s_waitcnt lgkmcnt(0)
	s_waitcnt lgkmcnt(0)
	v_mfma_f32_16x16x32_bf16 v[118:121], v[202:205], v[148:151], v[118:121]
	v_mfma_f32_16x16x32_bf16 v[114:117], v[210:213], v[148:151], v[114:117]
	v_mfma_f32_16x16x32_bf16 v[102:105], v[202:205], v[178:181], v[102:105]
	v_mfma_f32_16x16x32_bf16 v[94:97], v[210:213], v[178:181], v[94:97]
	v_mfma_f32_16x16x32_bf16 v[86:89], v[202:205], v[186:189], v[86:89]
	v_mfma_f32_16x16x32_bf16 v[78:81], v[210:213], v[186:189], v[78:81]
	v_mfma_f32_16x16x32_bf16 v[70:73], v[202:205], v[194:197], v[70:73]
	v_mfma_f32_16x16x32_bf16 v[66:69], v[210:213], v[194:197], v[66:69]
	v_mfma_f32_16x16x32_bf16 v[118:121], v[206:209], v[152:155], v[118:121]
	v_mfma_f32_16x16x32_bf16 v[114:117], v[214:217], v[152:155], v[114:117]
	v_mfma_f32_16x16x32_bf16 v[102:105], v[206:209], v[182:185], v[102:105]
	v_mfma_f32_16x16x32_bf16 v[94:97], v[214:217], v[182:185], v[94:97]
	v_mfma_f32_16x16x32_bf16 v[86:89], v[206:209], v[190:193], v[86:89]
	v_mfma_f32_16x16x32_bf16 v[78:81], v[214:217], v[190:193], v[78:81]
	v_mfma_f32_16x16x32_bf16 v[70:73], v[206:209], v[198:201], v[70:73]
	v_mfma_f32_16x16x32_bf16 v[66:69], v[214:217], v[198:201], v[66:69]
	s_mov_b32 m0, s12
	v_lshl_add_u64 v[156:157], v[230:231], 0, s[84:85]
	s_barrier
	ds_read_b128 v[148:151], v243 offset:49152
	ds_read_b128 v[152:155], v243 offset:50176
	ds_read_b128 v[178:181], v243 offset:51200
	ds_read_b128 v[182:185], v243 offset:52224
	ds_read_b128 v[186:189], v243 offset:53248
	ds_read_b128 v[190:193], v243 offset:54272
	ds_read_b128 v[194:197], v243 offset:55296
	ds_read_b128 v[198:201], v243 offset:56320
	global_load_lds_dwordx4 v[156:157], off
	v_lshl_add_u64 v[156:157], v[232:233], 0, s[84:85]
	s_mov_b32 m0, s28
	s_nop 0
	global_load_lds_dwordx4 v[156:157], off
	s_barrier
	s_waitcnt lgkmcnt(0)
	s_waitcnt lgkmcnt(0)
	v_mfma_f32_16x16x32_bf16 v[62:65], v[132:135], v[148:151], v[62:65]
	v_mfma_f32_16x16x32_bf16 v[58:61], v[140:143], v[148:151], v[58:61]
	v_mfma_f32_16x16x32_bf16 v[46:49], v[132:135], v[178:181], v[46:49]
	v_mfma_f32_16x16x32_bf16 v[42:45], v[140:143], v[178:181], v[42:45]
	v_mfma_f32_16x16x32_bf16 v[34:37], v[132:135], v[186:189], v[34:37]
	v_mfma_f32_16x16x32_bf16 v[26:29], v[140:143], v[186:189], v[26:29]
	v_mfma_f32_16x16x32_bf16 v[18:21], v[132:135], v[194:197], v[18:21]
	v_mfma_f32_16x16x32_bf16 v[10:13], v[140:143], v[194:197], v[10:13]
	v_mfma_f32_16x16x32_bf16 v[62:65], v[136:139], v[152:155], v[62:65]
	v_mfma_f32_16x16x32_bf16 v[58:61], v[144:147], v[152:155], v[58:61]
	v_mfma_f32_16x16x32_bf16 v[46:49], v[136:139], v[182:185], v[46:49]
	v_mfma_f32_16x16x32_bf16 v[42:45], v[144:147], v[182:185], v[42:45]
	v_mfma_f32_16x16x32_bf16 v[34:37], v[136:139], v[190:193], v[34:37]
	v_mfma_f32_16x16x32_bf16 v[26:29], v[144:147], v[190:193], v[26:29]
	v_mfma_f32_16x16x32_bf16 v[18:21], v[136:139], v[198:201], v[18:21]
	v_mfma_f32_16x16x32_bf16 v[10:13], v[144:147], v[198:201], v[10:13]
	s_barrier
	s_add_i32 s4, s5, s3
	v_lshl_add_u64 v[132:133], v[244:245], 0, s[84:85]
	s_mov_b32 m0, s4
	s_nop 0
	global_load_lds_dwordx4 v[132:133], off
	v_lshl_add_u64 v[132:133], v[246:247], 0, s[84:85]
	s_add_i32 m0, s4, 0x2000
	s_nop 0
	global_load_lds_dwordx4 v[132:133], off
	s_waitcnt vmcnt(6)
	s_barrier
	v_mfma_f32_16x16x32_bf16 v[54:57], v[202:205], v[148:151], v[54:57]
	v_mfma_f32_16x16x32_bf16 v[50:53], v[210:213], v[148:151], v[50:53]
	v_mfma_f32_16x16x32_bf16 v[38:41], v[202:205], v[178:181], v[38:41]
	v_mfma_f32_16x16x32_bf16 v[30:33], v[210:213], v[178:181], v[30:33]
	v_mfma_f32_16x16x32_bf16 v[22:25], v[202:205], v[186:189], v[22:25]
	v_mfma_f32_16x16x32_bf16 v[14:17], v[210:213], v[186:189], v[14:17]
	v_mfma_f32_16x16x32_bf16 v[6:9], v[202:205], v[194:197], v[6:9]
	v_mfma_f32_16x16x32_bf16 v[2:5], v[210:213], v[194:197], v[2:5]
	v_mfma_f32_16x16x32_bf16 v[54:57], v[206:209], v[152:155], v[54:57]
	v_mfma_f32_16x16x32_bf16 v[50:53], v[214:217], v[152:155], v[50:53]
	v_mfma_f32_16x16x32_bf16 v[38:41], v[206:209], v[182:185], v[38:41]
	v_mfma_f32_16x16x32_bf16 v[30:33], v[214:217], v[182:185], v[30:33]
	v_mfma_f32_16x16x32_bf16 v[22:25], v[206:209], v[190:193], v[22:25]
	v_mfma_f32_16x16x32_bf16 v[14:17], v[214:217], v[190:193], v[14:17]
	v_mfma_f32_16x16x32_bf16 v[6:9], v[206:209], v[198:201], v[6:9]
	v_mfma_f32_16x16x32_bf16 v[2:5], v[214:217], v[198:201], v[2:5]
	s_add_u32 s6, s6, 0x100
	s_addc_u32 s7, s7, 0
	v_lshl_add_u64 v[130:131], v[130:131], 0, s[86:87]
	s_cmp_ge_u32 s42, s13
	s_mov_b32 s4, s42
	s_barrier
	s_cbranch_scc0 .LBB0_649
	s_lshl_b32 s6, s23, 8
	v_lshl_or_b32 v178, s22, 8, v238
	v_add_u32_e32 v130, s6, v1
	v_ashrrev_i32_e32 v179, 31, v178
	v_lshlrev_b64 v[186:187], 1, v[178:179]
	v_ashrrev_i32_e32 v131, 31, v130
	v_lshl_add_u64 v[190:191], s[18:19], 0, v[186:187]
	v_lshlrev_b64 v[188:189], 11, v[130:131]
	v_lshl_add_u64 v[132:133], v[190:191], 0, v[188:189]
	global_load_dwordx4 v[192:195], v[132:133], off
	global_load_dwordx4 v[154:157], v[132:133], off offset:256
	v_or_b32_e32 v132, 16, v130
	v_ashrrev_i32_e32 v133, 31, v132
	v_lshlrev_b64 v[184:185], 11, v[132:133]
	v_lshl_add_u64 v[132:133], v[190:191], 0, v[184:185]
	global_load_dwordx4 v[150:153], v[132:133], off
	global_load_dwordx4 v[146:149], v[132:133], off offset:256
	v_or_b32_e32 v132, 32, v130
	v_ashrrev_i32_e32 v133, 31, v132
	v_lshlrev_b64 v[182:183], 11, v[132:133]
	v_or_b32_e32 v130, 48, v130
	v_lshl_add_u64 v[132:133], v[190:191], 0, v[182:183]
	v_ashrrev_i32_e32 v131, 31, v130
	global_load_dwordx4 v[142:145], v[132:133], off
	global_load_dwordx4 v[138:141], v[132:133], off offset:256
	v_lshlrev_b64 v[180:181], 11, v[130:131]
	v_lshl_add_u64 v[130:131], v[190:191], 0, v[180:181]
	global_load_dwordx4 v[134:137], v[130:131], off
	s_nop 0
	global_load_dwordx4 v[130:133], v[130:131], off offset:256
	v_mov_b32_e32 v169, v168
	s_mov_b64 s[4:5], 0x40000
	v_cmp_lt_i32_e32 vcc, v227, v222
	s_waitcnt vmcnt(0)
	v_lshlrev_b32_e32 v196, 16, v192
	v_and_b32_e32 v197, 0xffff0000, v192
	v_lshlrev_b32_e32 v192, 16, v193
	v_and_b32_e32 v193, 0xffff0000, v193
	v_lshlrev_b32_e32 v198, 16, v194
	v_and_b32_e32 v199, 0xffff0000, v194
	v_lshlrev_b32_e32 v194, 16, v195
	v_and_b32_e32 v195, 0xffff0000, v195
	v_pk_fma_f32 v[128:129], v[168:169], v[128:129], v[192:193]
	v_pk_fma_f32 v[126:127], v[170:171], v[126:127], v[196:197]
	v_pk_fma_f32 v[192:193], v[168:169], v[124:125], v[194:195]
	v_pk_fma_f32 v[124:125], v[170:171], v[122:123], v[198:199]
	v_mul_f32_e32 v122, v127, v127
	v_mul_f32_e32 v123, v129, v129
	v_fmac_f32_e32 v122, v126, v126
	v_fmac_f32_e32 v123, v128, v128
	v_add_f32_e32 v122, v122, v123
	v_mul_f32_e32 v123, v125, v125
	v_mul_f32_e32 v194, v193, v193
	v_fmac_f32_e32 v123, v124, v124
	v_fmac_f32_e32 v194, v192, v192
	v_add_f32_e32 v123, v123, v194
	v_add_f32_e32 v194, v122, v123
	v_cvt_pk_bf16_f32 v122, v126, v127
	v_cvt_pk_bf16_f32 v123, v128, v129
	v_lshlrev_b32_e32 v126, 16, v154
	v_and_b32_e32 v127, 0xffff0000, v154
	v_lshlrev_b32_e32 v128, 16, v155
	v_and_b32_e32 v129, 0xffff0000, v155
	v_lshlrev_b32_e32 v154, 16, v156
	v_and_b32_e32 v155, 0xffff0000, v156
	v_lshlrev_b32_e32 v156, 16, v157
	v_and_b32_e32 v157, 0xffff0000, v157
	v_pk_fma_f32 v[120:121], v[168:169], v[120:121], v[128:129]
	v_pk_fma_f32 v[118:119], v[170:171], v[118:119], v[126:127]
	v_pk_fma_f32 v[126:127], v[168:169], v[116:117], v[156:157]
	v_pk_fma_f32 v[116:117], v[170:171], v[114:115], v[154:155]
	v_mul_f32_e32 v114, v119, v119
	v_mul_f32_e32 v115, v121, v121
	v_fmac_f32_e32 v114, v118, v118
	v_fmac_f32_e32 v115, v120, v120
	v_add_f32_e32 v114, v114, v115
	v_mul_f32_e32 v115, v117, v117
	v_mul_f32_e32 v128, v127, v127
	v_fmac_f32_e32 v115, v116, v116
	v_fmac_f32_e32 v128, v126, v126
	v_add_f32_e32 v115, v115, v128
	v_add_f32_e32 v114, v114, v115
	v_cvt_pk_bf16_f32 v124, v124, v125
	v_cvt_pk_bf16_f32 v125, v192, v193
	v_add_f32_e32 v244, v194, v114
	v_cvt_pk_bf16_f32 v114, v118, v119
	v_cvt_pk_bf16_f32 v115, v120, v121
	v_lshlrev_b32_e32 v118, 16, v150
	v_and_b32_e32 v119, 0xffff0000, v150
	v_lshlrev_b32_e32 v120, 16, v151
	v_and_b32_e32 v121, 0xffff0000, v151
	v_pk_fma_f32 v[154:155], v[168:169], v[112:113], v[120:121]
	v_pk_fma_f32 v[156:157], v[170:171], v[110:111], v[118:119]
	v_lshlrev_b32_e32 v110, 16, v146
	v_and_b32_e32 v111, 0xffff0000, v146
	v_lshlrev_b32_e32 v112, 16, v147
	v_and_b32_e32 v113, 0xffff0000, v147
	v_lshlrev_b32_e32 v118, 16, v148
	v_and_b32_e32 v119, 0xffff0000, v148
	v_lshlrev_b32_e32 v120, 16, v149
	v_and_b32_e32 v121, 0xffff0000, v149
	v_pk_fma_f32 v[146:147], v[168:169], v[104:105], v[112:113]
	v_pk_fma_f32 v[192:193], v[170:171], v[102:103], v[110:111]
	v_pk_fma_f32 v[148:149], v[168:169], v[96:97], v[120:121]
	v_pk_fma_f32 v[198:199], v[170:171], v[94:95], v[118:119]
	v_lshlrev_b32_e32 v94, 16, v142
	v_and_b32_e32 v95, 0xffff0000, v142
	v_lshlrev_b32_e32 v96, 16, v143
	v_and_b32_e32 v97, 0xffff0000, v143
	v_lshlrev_b32_e32 v110, 16, v144
	v_and_b32_e32 v111, 0xffff0000, v144
	v_lshlrev_b32_e32 v112, 16, v145
	v_and_b32_e32 v113, 0xffff0000, v145
	v_pk_fma_f32 v[142:143], v[168:169], v[100:101], v[96:97]
	v_pk_fma_f32 v[194:195], v[170:171], v[98:99], v[94:95]
	v_pk_fma_f32 v[144:145], v[168:169], v[92:93], v[112:113]
	v_pk_fma_f32 v[196:197], v[170:171], v[90:91], v[110:111]
	v_lshlrev_b32_e32 v90, 16, v138
	v_and_b32_e32 v91, 0xffff0000, v138
	v_lshlrev_b32_e32 v92, 16, v139
	v_and_b32_e32 v93, 0xffff0000, v139
	v_lshlrev_b32_e32 v98, 16, v140
	v_and_b32_e32 v99, 0xffff0000, v140
	v_lshlrev_b32_e32 v100, 16, v141
	v_and_b32_e32 v101, 0xffff0000, v141
	v_pk_fma_f32 v[200:201], v[168:169], v[88:89], v[92:93]
	v_pk_fma_f32 v[208:209], v[170:171], v[86:87], v[90:91]
	v_pk_fma_f32 v[204:205], v[168:169], v[80:81], v[100:101]
	v_pk_fma_f32 v[210:211], v[170:171], v[78:79], v[98:99]
	v_lshlrev_b32_e32 v78, 16, v134
	v_and_b32_e32 v79, 0xffff0000, v134
	v_lshlrev_b32_e32 v80, 16, v135
	v_and_b32_e32 v81, 0xffff0000, v135
	v_lshlrev_b32_e32 v86, 16, v136
	v_and_b32_e32 v87, 0xffff0000, v136
	v_lshlrev_b32_e32 v88, 16, v137
	v_and_b32_e32 v89, 0xffff0000, v137
	v_cvt_pk_bf16_f32 v116, v116, v117
	v_cvt_pk_bf16_f32 v117, v126, v127
	v_lshlrev_b32_e32 v126, 16, v152
	v_and_b32_e32 v127, 0xffff0000, v152
	v_lshlrev_b32_e32 v128, 16, v153
	v_and_b32_e32 v129, 0xffff0000, v153
	v_pk_fma_f32 v[138:139], v[168:169], v[84:85], v[80:81]
	v_pk_fma_f32 v[202:203], v[170:171], v[82:83], v[78:79]
	v_pk_fma_f32 v[140:141], v[168:169], v[76:77], v[88:89]
	v_pk_fma_f32 v[206:207], v[170:171], v[74:75], v[86:87]
	v_lshlrev_b32_e32 v74, 16, v130
	v_and_b32_e32 v75, 0xffff0000, v130
	v_lshlrev_b32_e32 v76, 16, v131
	v_and_b32_e32 v77, 0xffff0000, v131
	v_lshlrev_b32_e32 v78, 16, v132
	v_and_b32_e32 v79, 0xffff0000, v132
	v_lshlrev_b32_e32 v80, 16, v133
	v_and_b32_e32 v81, 0xffff0000, v133
	v_lshl_add_u64 v[136:137], v[188:189], 0, s[4:5]
	s_mov_b64 s[4:5], 0x48000
	v_pk_fma_f32 v[150:151], v[168:169], v[108:109], v[128:129]
	v_pk_fma_f32 v[152:153], v[170:171], v[106:107], v[126:127]
	v_cvt_pk_bf16_f32 v106, v156, v157
	v_cvt_pk_bf16_f32 v107, v154, v155
	v_pk_fma_f32 v[212:213], v[168:169], v[72:73], v[76:77]
	v_cvt_pk_bf16_f32 v108, v152, v153
	v_cvt_pk_bf16_f32 v109, v150, v151
	v_cvt_pk_bf16_f32 v102, v192, v193
	v_cvt_pk_bf16_f32 v103, v146, v147
	v_cvt_pk_bf16_f32 v104, v198, v199
	v_cvt_pk_bf16_f32 v105, v148, v149
	v_cvt_pk_bf16_f32 v94, v194, v195
	v_cvt_pk_bf16_f32 v95, v142, v143
	v_cvt_pk_bf16_f32 v96, v196, v197
	v_cvt_pk_bf16_f32 v97, v144, v145
	v_cvt_pk_bf16_f32 v118, v208, v209
	v_cvt_pk_bf16_f32 v119, v200, v201
	v_cvt_pk_bf16_f32 v120, v210, v211
	v_cvt_pk_bf16_f32 v121, v204, v205
	v_cvt_pk_bf16_f32 v98, v202, v203
	v_cvt_pk_bf16_f32 v99, v138, v139
	v_cvt_pk_bf16_f32 v100, v206, v207
	v_cvt_pk_bf16_f32 v101, v140, v141
	v_pk_fma_f32 v[216:217], v[170:171], v[70:71], v[74:75]
	v_pk_fma_f32 v[214:215], v[168:169], v[68:69], v[80:81]
	v_pk_fma_f32 v[218:219], v[170:171], v[66:67], v[78:79]
	v_cvt_pk_bf16_f32 v126, v216, v217
	v_cvt_pk_bf16_f32 v127, v212, v213
	v_lshl_add_u64 v[66:67], v[190:191], 0, v[136:137]
	v_cvt_pk_bf16_f32 v128, v218, v219
	v_cvt_pk_bf16_f32 v129, v214, v215
	v_lshl_add_u64 v[134:135], v[188:189], 0, s[4:5]
	s_mov_b64 s[4:5], 0x50000
	global_load_dwordx4 v[110:113], v[66:67], off
	global_load_dwordx4 v[90:93], v[66:67], off offset:256
	v_lshl_add_u64 v[66:67], v[190:191], 0, v[134:135]
	v_lshl_add_u64 v[132:133], v[188:189], 0, s[4:5]
	s_mov_b64 s[4:5], 0x58000
	global_load_dwordx4 v[86:89], v[66:67], off
	global_load_dwordx4 v[82:85], v[66:67], off offset:256
	v_lshl_add_u64 v[66:67], v[190:191], 0, v[132:133]
	v_lshl_add_u64 v[130:131], v[188:189], 0, s[4:5]
	global_load_dwordx4 v[78:81], v[66:67], off
	global_load_dwordx4 v[74:77], v[66:67], off offset:256
	v_lshl_add_u64 v[66:67], v[190:191], 0, v[130:131]
	global_load_dwordx4 v[70:73], v[66:67], off
	s_nop 0
	global_load_dwordx4 v[66:69], v[66:67], off offset:256
	v_cndmask_b32_e32 v169, v221, v227, vcc
	v_lshl_add_u64 v[188:189], s[18:19], 0, v[188:189]
	v_lshlrev_b32_e32 v190, 2, v169
	v_lshl_add_u64 v[186:187], v[188:189], 0, v[186:187]
	global_store_dwordx4 v[186:187], v[122:125], off
	global_store_dwordx4 v[186:187], v[114:117], off offset:256
	ds_bpermute_b32 v114, v190, v244
	v_cmp_lt_i32_e32 vcc, v228, v222
	s_waitcnt lgkmcnt(0)
	v_add_f32_e32 v114, v244, v114
	v_cndmask_b32_e32 v169, v221, v228, vcc
	v_lshlrev_b32_e32 v191, 2, v169
	ds_bpermute_b32 v115, v191, v114
	s_and_saveexec_b64 s[4:5], s[38:39]
	s_cbranch_execz .LBB0_652
	s_waitcnt lgkmcnt(0)
	v_add_f32_e32 v114, v114, v115
	v_add_u32_e32 v115, s90, v239
	ds_write_b32 v115, v114

.LBB0_691:
	s_add_i32 s6, s0, 2
	s_add_i32 s7, 0, 0x10000
	s_cmp_eq_u32 s44, s0
	v_lshl_add_u64 v[100:101], v[98:99], 0, s[84:85]
	s_cselect_b64 vcc, -1, 0
	v_add_u32_e32 v104, s7, v176
	v_cndmask_b32_e32 v175, v101, v165, vcc
	v_cndmask_b32_e32 v174, v100, v164, vcc
	ds_read_b128 v[100:103], v104
	ds_read_b128 v[138:141], v104 offset:1024
	ds_read_b128 v[142:145], v104 offset:2048
	ds_read_b128 v[166:169], v104 offset:3072
	s_cselect_b32 s0, s22, s4
	s_cselect_b32 s1, s23, s5
	v_lshl_add_u64 v[104:105], v[98:99], 0, v[156:157]
	s_add_i32 m0, s10, 0xc000
	ds_read_b128 v[170:173], v178
	ds_read_b128 v[180:183], v178 offset:1024
	ds_read_b128 v[184:187], v178 offset:2048
	ds_read_b128 v[188:191], v178 offset:3072
	ds_read_b128 v[192:195], v178 offset:4096
	ds_read_b128 v[196:199], v178 offset:5120
	ds_read_b128 v[200:203], v178 offset:6144
	ds_read_b128 v[204:207], v178 offset:7168
	global_load_lds_dwordx4 v[104:105], off
	v_lshl_add_u64 v[104:105], v[98:99], 0, v[160:161]
	s_add_i32 m0, s10, 0xe000
	s_nop 0
	global_load_lds_dwordx4 v[104:105], off
	s_waitcnt lgkmcnt(8)
	s_barrier
	s_waitcnt lgkmcnt(0)
	s_waitcnt lgkmcnt(0)
	v_mfma_f32_16x16x32_bf16 v[134:137], v[100:103], v[170:173], v[134:137]
	v_mfma_f32_16x16x32_bf16 v[130:133], v[142:145], v[170:173], v[130:133]
	v_mfma_f32_16x16x32_bf16 v[126:129], v[100:103], v[184:187], v[126:129]
	v_mfma_f32_16x16x32_bf16 v[122:125], v[142:145], v[184:187], v[122:125]
	v_mfma_f32_16x16x32_bf16 v[118:121], v[100:103], v[192:195], v[118:121]
	v_mfma_f32_16x16x32_bf16 v[114:117], v[142:145], v[192:195], v[114:117]
	v_mfma_f32_16x16x32_bf16 v[110:113], v[100:103], v[200:203], v[110:113]
	v_mfma_f32_16x16x32_bf16 v[104:107], v[142:145], v[200:203], v[106:109]
	v_mfma_f32_16x16x32_bf16 v[134:137], v[138:141], v[180:183], v[134:137]
	v_mfma_f32_16x16x32_bf16 v[130:133], v[166:169], v[180:183], v[130:133]
	v_mfma_f32_16x16x32_bf16 v[126:129], v[138:141], v[188:191], v[126:129]
	v_mfma_f32_16x16x32_bf16 v[122:125], v[166:169], v[188:191], v[122:125]
	v_mfma_f32_16x16x32_bf16 v[118:121], v[138:141], v[196:199], v[118:121]
	v_mfma_f32_16x16x32_bf16 v[114:117], v[166:169], v[196:199], v[114:117]
	v_mfma_f32_16x16x32_bf16 v[110:113], v[138:141], v[204:207], v[110:113]
	v_mfma_f32_16x16x32_bf16 v[104:107], v[166:169], v[204:207], v[104:107]
	s_barrier
	s_add_i32 s36, 0, 0x14000
	s_add_i32 s7, s7, s9
	v_add_u32_e32 v108, s36, v176
	v_lshl_add_u64 v[242:243], s[0:1], 0, v[148:149]
	s_mov_b32 m0, s7
	ds_read_b128 v[208:211], v108
	ds_read_b128 v[212:215], v108 offset:1024
	ds_read_b128 v[216:219], v108 offset:2048
	ds_read_b128 v[238:241], v108 offset:3072
	global_load_lds_dwordx4 v[242:243], off
	v_lshl_add_u64 v[244:245], s[0:1], 0, v[152:153]
	s_add_i32 m0, s7, 0x2000
	s_nop 0
	global_load_lds_dwordx4 v[244:245], off
	s_barrier
	s_waitcnt lgkmcnt(0)
	s_waitcnt lgkmcnt(0)
	v_mfma_f32_16x16x32_bf16 v[62:65], v[208:211], v[170:173], v[62:65]
	v_mfma_f32_16x16x32_bf16 v[58:61], v[216:219], v[170:173], v[58:61]
	v_mfma_f32_16x16x32_bf16 v[54:57], v[208:211], v[184:187], v[54:57]
	v_mfma_f32_16x16x32_bf16 v[50:53], v[216:219], v[184:187], v[50:53]
	v_mfma_f32_16x16x32_bf16 v[46:49], v[208:211], v[192:195], v[46:49]
	v_mfma_f32_16x16x32_bf16 v[42:45], v[216:219], v[192:195], v[42:45]
	v_mfma_f32_16x16x32_bf16 v[38:41], v[208:211], v[200:203], v[38:41]
	v_mfma_f32_16x16x32_bf16 v[34:37], v[216:219], v[200:203], v[34:37]
	v_mfma_f32_16x16x32_bf16 v[62:65], v[212:215], v[180:183], v[62:65]
	v_mfma_f32_16x16x32_bf16 v[58:61], v[238:241], v[180:183], v[58:61]
	v_mfma_f32_16x16x32_bf16 v[54:57], v[212:215], v[188:191], v[54:57]
	v_mfma_f32_16x16x32_bf16 v[50:53], v[238:241], v[188:191], v[50:53]
	v_mfma_f32_16x16x32_bf16 v[46:49], v[212:215], v[196:199], v[46:49]
	v_mfma_f32_16x16x32_bf16 v[42:45], v[238:241], v[196:199], v[42:45]
	v_mfma_f32_16x16x32_bf16 v[38:41], v[212:215], v[204:207], v[38:41]
	v_mfma_f32_16x16x32_bf16 v[34:37], v[238:241], v[204:207], v[34:37]
	s_mov_b32 m0, s10
	v_lshl_add_u64 v[246:247], v[174:175], 0, v[146:147]
	s_barrier
	ds_read_b128 v[170:173], v178 offset:16384
	ds_read_b128 v[180:183], v178 offset:17408
	ds_read_b128 v[184:187], v178 offset:18432
	ds_read_b128 v[188:191], v178 offset:19456
	ds_read_b128 v[192:195], v178 offset:20480
	ds_read_b128 v[196:199], v178 offset:21504
	ds_read_b128 v[200:203], v178 offset:22528
	ds_read_b128 v[204:207], v178 offset:23552
	global_load_lds_dwordx4 v[246:247], off
	v_lshl_add_u64 v[248:249], v[174:175], 0, v[150:151]
	s_mov_b32 m0, s11
	s_nop 0
	global_load_lds_dwordx4 v[248:249], off
	s_barrier
	s_waitcnt lgkmcnt(0)
	s_waitcnt lgkmcnt(0)
	v_mfma_f32_16x16x32_bf16 v[94:97], v[100:103], v[170:173], v[94:97]
	v_mfma_f32_16x16x32_bf16 v[90:93], v[142:145], v[170:173], v[90:93]
	v_mfma_f32_16x16x32_bf16 v[86:89], v[100:103], v[184:187], v[86:89]
	v_mfma_f32_16x16x32_bf16 v[82:85], v[142:145], v[184:187], v[82:85]
	v_mfma_f32_16x16x32_bf16 v[78:81], v[100:103], v[192:195], v[78:81]
	v_mfma_f32_16x16x32_bf16 v[74:77], v[142:145], v[192:195], v[74:77]
	v_mfma_f32_16x16x32_bf16 v[70:73], v[100:103], v[200:203], v[70:73]
	v_mfma_f32_16x16x32_bf16 v[66:69], v[142:145], v[200:203], v[66:69]
	v_mfma_f32_16x16x32_bf16 v[94:97], v[138:141], v[180:183], v[94:97]
	v_mfma_f32_16x16x32_bf16 v[90:93], v[166:169], v[180:183], v[90:93]
	v_mfma_f32_16x16x32_bf16 v[86:89], v[138:141], v[188:191], v[86:89]
	v_mfma_f32_16x16x32_bf16 v[82:85], v[166:169], v[188:191], v[82:85]
	v_mfma_f32_16x16x32_bf16 v[78:81], v[138:141], v[196:199], v[78:81]
	v_mfma_f32_16x16x32_bf16 v[74:77], v[166:169], v[196:199], v[74:77]
	v_mfma_f32_16x16x32_bf16 v[70:73], v[138:141], v[204:207], v[70:73]
	v_mfma_f32_16x16x32_bf16 v[66:69], v[166:169], v[204:207], v[66:69]
	s_barrier
	s_add_u32 s0, s0, s94
	s_addc_u32 s1, s1, 0
	s_add_i32 s7, s36, s9
	v_lshl_add_u64 v[230:231], s[0:1], 0, v[148:149]
	s_mov_b32 m0, s7
	v_lshl_add_u64 v[224:225], s[0:1], 0, v[152:153]
	global_load_lds_dwordx4 v[230:231], off
	s_add_i32 m0, s7, 0x2000
	s_nop 0
	global_load_lds_dwordx4 v[224:225], off
	s_waitcnt vmcnt(6)
	s_barrier
	v_mfma_f32_16x16x32_bf16 v[30:33], v[208:211], v[170:173], v[30:33]
	v_mfma_f32_16x16x32_bf16 v[26:29], v[216:219], v[170:173], v[26:29]
	v_mfma_f32_16x16x32_bf16 v[22:25], v[208:211], v[184:187], v[22:25]
	v_mfma_f32_16x16x32_bf16 v[18:21], v[216:219], v[184:187], v[18:21]
	v_mfma_f32_16x16x32_bf16 v[14:17], v[208:211], v[192:195], v[14:17]
	v_mfma_f32_16x16x32_bf16 v[10:13], v[216:219], v[192:195], v[10:13]
	v_mfma_f32_16x16x32_bf16 v[6:9], v[208:211], v[200:203], v[6:9]
	v_mfma_f32_16x16x32_bf16 v[2:5], v[216:219], v[200:203], v[2:5]
	v_mfma_f32_16x16x32_bf16 v[30:33], v[212:215], v[180:183], v[30:33]
	v_mfma_f32_16x16x32_bf16 v[26:29], v[238:241], v[180:183], v[26:29]
	v_mfma_f32_16x16x32_bf16 v[22:25], v[212:215], v[188:191], v[22:25]
	v_mfma_f32_16x16x32_bf16 v[18:21], v[238:241], v[188:191], v[18:21]
	v_mfma_f32_16x16x32_bf16 v[14:17], v[212:215], v[196:199], v[14:17]
	v_mfma_f32_16x16x32_bf16 v[10:13], v[238:241], v[196:199], v[10:13]
	v_mfma_f32_16x16x32_bf16 v[6:9], v[212:215], v[204:207], v[6:9]
	v_mfma_f32_16x16x32_bf16 v[2:5], v[238:241], v[204:207], v[2:5]
	s_add_i32 s0, 0, 0x18000
	v_add_u32_e32 v108, s0, v176
	s_barrier
	ds_read_b128 v[100:103], v108
	ds_read_b128 v[138:141], v108 offset:1024
	ds_read_b128 v[142:145], v108 offset:2048
	ds_read_b128 v[166:169], v108 offset:3072
	v_lshl_add_u64 v[108:109], v[174:175], 0, s[94:95]
	s_mov_b32 m0, s8
	v_lshl_add_u64 v[174:175], v[108:109], 0, v[146:147]
	ds_read_b128 v[170:173], v178 offset:32768
	ds_read_b128 v[180:183], v178 offset:33792
	ds_read_b128 v[184:187], v178 offset:34816
	ds_read_b128 v[188:191], v178 offset:35840
	ds_read_b128 v[192:195], v178 offset:36864
	ds_read_b128 v[196:199], v178 offset:37888
	ds_read_b128 v[200:203], v178 offset:38912
	ds_read_b128 v[204:207], v178 offset:39936
	global_load_lds_dwordx4 v[174:175], off
	v_lshl_add_u64 v[108:109], v[108:109], 0, v[150:151]
	s_mov_b32 m0, s2
	s_nop 0
	global_load_lds_dwordx4 v[108:109], off
	s_waitcnt lgkmcnt(8)
	s_barrier
	s_waitcnt lgkmcnt(0)
	s_waitcnt lgkmcnt(0)
	v_mfma_f32_16x16x32_bf16 v[134:137], v[100:103], v[170:173], v[134:137]
	v_mfma_f32_16x16x32_bf16 v[130:133], v[142:145], v[170:173], v[130:133]
	v_mfma_f32_16x16x32_bf16 v[126:129], v[100:103], v[184:187], v[126:129]
	v_mfma_f32_16x16x32_bf16 v[122:125], v[142:145], v[184:187], v[122:125]
	v_mfma_f32_16x16x32_bf16 v[118:121], v[100:103], v[192:195], v[118:121]
	v_mfma_f32_16x16x32_bf16 v[114:117], v[142:145], v[192:195], v[114:117]
	v_mfma_f32_16x16x32_bf16 v[108:111], v[100:103], v[200:203], v[110:113]
	v_mfma_f32_16x16x32_bf16 v[104:107], v[142:145], v[200:203], v[104:107]
	v_mfma_f32_16x16x32_bf16 v[134:137], v[138:141], v[180:183], v[134:137]
	v_mfma_f32_16x16x32_bf16 v[130:133], v[166:169], v[180:183], v[130:133]
	v_mfma_f32_16x16x32_bf16 v[126:129], v[138:141], v[188:191], v[126:129]
	v_mfma_f32_16x16x32_bf16 v[122:125], v[166:169], v[188:191], v[122:125]
	v_mfma_f32_16x16x32_bf16 v[118:121], v[138:141], v[196:199], v[118:121]
	v_mfma_f32_16x16x32_bf16 v[114:117], v[166:169], v[196:199], v[114:117]
	v_mfma_f32_16x16x32_bf16 v[110:113], v[138:141], v[204:207], v[108:111]
	v_mfma_f32_16x16x32_bf16 v[106:109], v[166:169], v[204:207], v[104:107]
	s_barrier
	s_add_i32 s1, 0, 0x1c000
	v_add_u32_e32 v104, s1, v176
	s_add_i32 s0, s0, s9
	ds_read_b128 v[208:211], v104
	ds_read_b128 v[212:215], v104 offset:1024
	ds_read_b128 v[216:219], v104 offset:2048
	ds_read_b128 v[238:241], v104 offset:3072
	v_lshl_add_u64 v[104:105], v[242:243], 0, s[84:85]
	s_mov_b32 m0, s0
	s_nop 0
	global_load_lds_dwordx4 v[104:105], off
	v_lshl_add_u64 v[104:105], v[244:245], 0, s[84:85]
	s_add_i32 m0, s0, 0x2000
	s_nop 0
	global_load_lds_dwordx4 v[104:105], off
	s_barrier
	s_waitcnt lgkmcnt(0)
	s_waitcnt lgkmcnt(0)
	v_mfma_f32_16x16x32_bf16 v[62:65], v[208:211], v[170:173], v[62:65]
	v_mfma_f32_16x16x32_bf16 v[58:61], v[216:219], v[170:173], v[58:61]
	v_mfma_f32_16x16x32_bf16 v[54:57], v[208:211], v[184:187], v[54:57]
	v_mfma_f32_16x16x32_bf16 v[50:53], v[216:219], v[184:187], v[50:53]
	v_mfma_f32_16x16x32_bf16 v[46:49], v[208:211], v[192:195], v[46:49]
	v_mfma_f32_16x16x32_bf16 v[42:45], v[216:219], v[192:195], v[42:45]
	v_mfma_f32_16x16x32_bf16 v[38:41], v[208:211], v[200:203], v[38:41]
	v_mfma_f32_16x16x32_bf16 v[34:37], v[216:219], v[200:203], v[34:37]
	v_mfma_f32_16x16x32_bf16 v[62:65], v[212:215], v[180:183], v[62:65]
	v_mfma_f32_16x16x32_bf16 v[58:61], v[238:241], v[180:183], v[58:61]
	v_mfma_f32_16x16x32_bf16 v[54:57], v[212:215], v[188:191], v[54:57]
	v_mfma_f32_16x16x32_bf16 v[50:53], v[238:241], v[188:191], v[50:53]
	v_mfma_f32_16x16x32_bf16 v[46:49], v[212:215], v[196:199], v[46:49]
	v_mfma_f32_16x16x32_bf16 v[42:45], v[238:241], v[196:199], v[42:45]
	v_mfma_f32_16x16x32_bf16 v[38:41], v[212:215], v[204:207], v[38:41]
	v_mfma_f32_16x16x32_bf16 v[34:37], v[238:241], v[204:207], v[34:37]
	s_mov_b32 m0, s54
	v_lshl_add_u64 v[104:105], v[246:247], 0, s[84:85]
	s_barrier
	ds_read_b128 v[170:173], v178 offset:49152
	ds_read_b128 v[180:183], v178 offset:50176
	ds_read_b128 v[184:187], v178 offset:51200
	ds_read_b128 v[188:191], v178 offset:52224
	ds_read_b128 v[192:195], v178 offset:53248
	ds_read_b128 v[196:199], v178 offset:54272
	ds_read_b128 v[200:203], v178 offset:55296
	ds_read_b128 v[204:207], v178 offset:56320
	global_load_lds_dwordx4 v[104:105], off
	v_lshl_add_u64 v[104:105], v[248:249], 0, s[84:85]
	s_mov_b32 m0, s3
	s_nop 0
	global_load_lds_dwordx4 v[104:105], off
	s_barrier
	s_waitcnt lgkmcnt(0)
	s_waitcnt lgkmcnt(0)
	v_mfma_f32_16x16x32_bf16 v[94:97], v[100:103], v[170:173], v[94:97]
	v_mfma_f32_16x16x32_bf16 v[90:93], v[142:145], v[170:173], v[90:93]
	v_mfma_f32_16x16x32_bf16 v[86:89], v[100:103], v[184:187], v[86:89]
	v_mfma_f32_16x16x32_bf16 v[82:85], v[142:145], v[184:187], v[82:85]
	v_mfma_f32_16x16x32_bf16 v[78:81], v[100:103], v[192:195], v[78:81]
	v_mfma_f32_16x16x32_bf16 v[74:77], v[142:145], v[192:195], v[74:77]
	v_mfma_f32_16x16x32_bf16 v[70:73], v[100:103], v[200:203], v[70:73]
	v_mfma_f32_16x16x32_bf16 v[66:69], v[142:145], v[200:203], v[66:69]
	v_mfma_f32_16x16x32_bf16 v[94:97], v[138:141], v[180:183], v[94:97]
	v_mfma_f32_16x16x32_bf16 v[90:93], v[166:169], v[180:183], v[90:93]
	v_mfma_f32_16x16x32_bf16 v[86:89], v[138:141], v[188:191], v[86:89]
	v_mfma_f32_16x16x32_bf16 v[82:85], v[166:169], v[188:191], v[82:85]
	v_mfma_f32_16x16x32_bf16 v[78:81], v[138:141], v[196:199], v[78:81]
	v_mfma_f32_16x16x32_bf16 v[74:77], v[166:169], v[196:199], v[74:77]
	v_mfma_f32_16x16x32_bf16 v[70:73], v[138:141], v[204:207], v[70:73]
	v_mfma_f32_16x16x32_bf16 v[66:69], v[166:169], v[204:207], v[66:69]
	s_barrier
	s_add_i32 s0, s1, s9
	v_lshl_add_u64 v[100:101], v[230:231], 0, s[84:85]
	s_mov_b32 m0, s0
	s_nop 0
	global_load_lds_dwordx4 v[100:101], off
	v_lshl_add_u64 v[100:101], v[224:225], 0, s[84:85]
	s_add_i32 m0, s0, 0x2000
	s_nop 0
	global_load_lds_dwordx4 v[100:101], off
	s_waitcnt vmcnt(6)
	s_barrier
	v_mfma_f32_16x16x32_bf16 v[30:33], v[208:211], v[170:173], v[30:33]
	v_mfma_f32_16x16x32_bf16 v[26:29], v[216:219], v[170:173], v[26:29]
	v_mfma_f32_16x16x32_bf16 v[22:25], v[208:211], v[184:187], v[22:25]
	v_mfma_f32_16x16x32_bf16 v[18:21], v[216:219], v[184:187], v[18:21]
	v_mfma_f32_16x16x32_bf16 v[14:17], v[208:211], v[192:195], v[14:17]
	v_mfma_f32_16x16x32_bf16 v[10:13], v[216:219], v[192:195], v[10:13]
	v_mfma_f32_16x16x32_bf16 v[6:9], v[208:211], v[200:203], v[6:9]
	v_mfma_f32_16x16x32_bf16 v[2:5], v[216:219], v[200:203], v[2:5]
	v_mfma_f32_16x16x32_bf16 v[30:33], v[212:215], v[180:183], v[30:33]
	v_mfma_f32_16x16x32_bf16 v[26:29], v[238:241], v[180:183], v[26:29]
	v_mfma_f32_16x16x32_bf16 v[22:25], v[212:215], v[188:191], v[22:25]
	v_mfma_f32_16x16x32_bf16 v[18:21], v[238:241], v[188:191], v[18:21]
	v_mfma_f32_16x16x32_bf16 v[14:17], v[212:215], v[196:199], v[14:17]
	v_mfma_f32_16x16x32_bf16 v[10:13], v[238:241], v[196:199], v[10:13]
	v_mfma_f32_16x16x32_bf16 v[6:9], v[212:215], v[204:207], v[6:9]
	v_mfma_f32_16x16x32_bf16 v[2:5], v[238:241], v[204:207], v[2:5]
	s_add_u32 s4, s4, 0x100
	s_addc_u32 s5, s5, 0
	v_lshl_add_u64 v[98:99], v[98:99], 0, s[86:87]
	s_cmp_ge_u32 s6, s13
	s_mov_b32 s0, s6
	s_barrier
	s_cbranch_scc0 .LBB0_691
	s_and_b64 vcc, exec, s[42:43]
	s_cbranch_vccz .LBB0_694
	ds_read2st64_b32 v[98:99], v179 offset0:6 offset1:7
	ds_read2st64_b32 v[102:103], v179 offset0:4 offset1:5
	ds_read2st64_b32 v[104:105], v179 offset0:2 offset1:3
	ds_read2st64_b32 v[100:101], v179 offset1:1
	v_cmp_lt_i32_e32 vcc, v227, v222
	s_mov_b32 s0, 0x358637bd
	s_mov_b32 s4, 0x3a800000
	v_cndmask_b32_e32 v138, v221, v227, vcc
	v_cmp_lt_i32_e32 vcc, v228, v222
	v_lshlrev_b32_e32 v142, 2, v138
	s_waitcnt lgkmcnt(0)
	ds_bpermute_b32 v139, v142, v101
	v_cndmask_b32_e32 v138, v221, v228, vcc
	v_lshlrev_b32_e32 v143, 2, v138
	ds_bpermute_b32 v138, v142, v100
	s_mov_b32 s6, 0x45800000
	s_waitcnt lgkmcnt(0)
	v_pk_add_f32 v[100:101], v[100:101], v[138:139]
	ds_bpermute_b32 v138, v143, v100
	ds_bpermute_b32 v139, v143, v101
	s_waitcnt lgkmcnt(0)
	v_pk_add_f32 v[138:139], v[100:101], v[138:139]
	v_mov_b64_e32 v[100:101], s[0:1]
	v_pk_fma_f32 v[138:139], v[138:139], s[4:5], v[100:101] op_sel_hi:[1,0,0]
	s_nop 0
	v_mul_f32_e32 v140, 0x4b800000, v138
	v_cmp_gt_f32_e64 s[0:1], s88, v138
	v_cmp_gt_f32_e32 vcc, s88, v139
	s_nop 0
	v_cndmask_b32_e64 v138, v138, v140, s[0:1]
	v_mul_f32_e32 v140, 0x4b800000, v139
	v_cndmask_b32_e32 v139, v139, v140, vcc
	v_rsq_f32_e32 v138, v138
	v_rsq_f32_e32 v139, v139
	s_nop 0
	v_pk_mul_f32 v[140:141], v[138:139], s[6:7] op_sel_hi:[1,0]
	s_nop 0
	v_cndmask_b32_e64 v174, v138, v140, s[0:1]
	v_cndmask_b32_e32 v175, v139, v141, vcc
	ds_bpermute_b32 v138, v142, v104
	ds_bpermute_b32 v139, v142, v105
	s_waitcnt lgkmcnt(0)
	v_pk_add_f32 v[104:105], v[104:105], v[138:139]
	ds_bpermute_b32 v138, v143, v104
	ds_bpermute_b32 v139, v143, v105
	s_waitcnt lgkmcnt(0)
	v_pk_add_f32 v[104:105], v[104:105], v[138:139]
	s_nop 0
	v_pk_fma_f32 v[104:105], v[104:105], s[4:5], v[100:101] op_sel_hi:[1,0,0]
	s_nop 0
	v_mul_f32_e32 v138, 0x4b800000, v104
	v_cmp_gt_f32_e64 s[0:1], s88, v104
	v_cmp_gt_f32_e32 vcc, s88, v105
	s_nop 0
	v_cndmask_b32_e64 v104, v104, v138, s[0:1]
	v_mul_f32_e32 v138, 0x4b800000, v105
	v_cndmask_b32_e32 v105, v105, v138, vcc
	v_rsq_f32_e32 v104, v104
	v_rsq_f32_e32 v105, v105
	s_nop 0
	v_pk_mul_f32 v[138:139], v[104:105], s[6:7] op_sel_hi:[1,0]
	s_nop 0
	v_cndmask_b32_e64 v172, v104, v138, s[0:1]
	v_cndmask_b32_e32 v173, v105, v139, vcc
	ds_bpermute_b32 v104, v142, v102
	ds_bpermute_b32 v105, v142, v103
	s_waitcnt lgkmcnt(0)
	v_pk_add_f32 v[102:103], v[102:103], v[104:105]
	ds_bpermute_b32 v104, v143, v102
	ds_bpermute_b32 v105, v143, v103
	s_waitcnt lgkmcnt(0)
	v_pk_add_f32 v[102:103], v[102:103], v[104:105]
	s_nop 0
	v_pk_fma_f32 v[102:103], v[102:103], s[4:5], v[100:101] op_sel_hi:[1,0,0]
	s_nop 0
	v_mul_f32_e32 v104, 0x4b800000, v102
	v_cmp_gt_f32_e64 s[0:1], s88, v102
	v_cmp_gt_f32_e32 vcc, s88, v103
	s_nop 0
	v_cndmask_b32_e64 v102, v102, v104, s[0:1]
	v_mul_f32_e32 v104, 0x4b800000, v103
	v_cndmask_b32_e32 v103, v103, v104, vcc
	v_rsq_f32_e32 v102, v102
	v_rsq_f32_e32 v103, v103
	s_nop 0
	v_pk_mul_f32 v[104:105], v[102:103], s[6:7] op_sel_hi:[1,0]
	s_nop 0
	v_cndmask_b32_e64 v170, v102, v104, s[0:1]
	v_cndmask_b32_e32 v171, v103, v105, vcc
	ds_bpermute_b32 v102, v142, v98
	ds_bpermute_b32 v103, v142, v99
	s_waitcnt lgkmcnt(0)
	v_pk_add_f32 v[98:99], v[98:99], v[102:103]
	ds_bpermute_b32 v102, v143, v98
	ds_bpermute_b32 v103, v143, v99
	s_waitcnt lgkmcnt(0)
	v_pk_add_f32 v[98:99], v[98:99], v[102:103]
	s_nop 0
	v_pk_fma_f32 v[98:99], v[98:99], s[4:5], v[100:101] op_sel_hi:[1,0,0]
	s_nop 0
	v_mul_f32_e32 v100, 0x4b800000, v98
	v_cmp_gt_f32_e64 s[0:1], s88, v98
	v_cmp_gt_f32_e32 vcc, s88, v99
	s_nop 0
	v_cndmask_b32_e64 v98, v98, v100, s[0:1]
	v_mul_f32_e32 v100, 0x4b800000, v99
	v_cndmask_b32_e32 v99, v99, v100, vcc
	v_rsq_f32_e32 v98, v98
	v_rsq_f32_e32 v99, v99
	s_nop 0
	v_pk_mul_f32 v[100:101], v[98:99], s[6:7] op_sel_hi:[1,0]
	s_nop 0
	v_cndmask_b32_e64 v168, v98, v100, s[0:1]
	v_cndmask_b32_e32 v169, v99, v101, vcc
	s_branch .LBB0_695

.LBB0_824:
	s_add_i32 s7, 0, 0x10000
	v_add_u32_e32 v145, s7, v153
	ds_read_b128 v[162:165], v145
	ds_read_b128 v[166:169], v145 offset:1024
	ds_read_b128 v[170:173], v145 offset:2048
	ds_read_b128 v[174:177], v145 offset:3072
	s_add_i32 s6, s0, 2
	s_cmp_eq_u32 s44, s0
	v_lshl_add_u64 v[150:151], v[148:149], 0, s[84:85]
	s_cselect_b64 vcc, -1, 0
	s_cselect_b32 s0, s22, s4
	v_cndmask_b32_e32 v151, v151, v147, vcc
	v_cndmask_b32_e32 v150, v150, v146, vcc
	s_cselect_b32 s1, s23, s5
	v_lshl_add_u64 v[210:211], v[148:149], 0, v[140:141]
	s_add_i32 m0, s28, 0xc000
	ds_read_b128 v[178:181], v157
	ds_read_b128 v[182:185], v157 offset:1024
	ds_read_b128 v[186:189], v157 offset:2048
	ds_read_b128 v[190:193], v157 offset:3072
	ds_read_b128 v[194:197], v157 offset:4096
	ds_read_b128 v[198:201], v157 offset:5120
	ds_read_b128 v[202:205], v157 offset:6144
	ds_read_b128 v[206:209], v157 offset:7168
	global_load_lds_dwordx4 v[210:211], off
	v_lshl_add_u64 v[210:211], v[148:149], 0, v[142:143]
	s_add_i32 m0, s28, 0xe000
	s_nop 0
	global_load_lds_dwordx4 v[210:211], off
	s_waitcnt lgkmcnt(8)
	s_barrier
	s_waitcnt lgkmcnt(0)
	s_waitcnt lgkmcnt(0)
	v_mfma_f32_16x16x32_bf16 v[126:129], v[162:165], v[178:181], v[126:129]
	v_mfma_f32_16x16x32_bf16 v[118:121], v[170:173], v[178:181], v[118:121]
	v_mfma_f32_16x16x32_bf16 v[110:113], v[162:165], v[186:189], v[110:113]
	v_mfma_f32_16x16x32_bf16 v[102:105], v[170:173], v[186:189], v[102:105]
	v_mfma_f32_16x16x32_bf16 v[94:97], v[162:165], v[194:197], v[94:97]
	v_mfma_f32_16x16x32_bf16 v[86:89], v[170:173], v[194:197], v[86:89]
	v_mfma_f32_16x16x32_bf16 v[78:81], v[162:165], v[202:205], v[78:81]
	v_mfma_f32_16x16x32_bf16 v[70:73], v[170:173], v[202:205], v[70:73]
	v_mfma_f32_16x16x32_bf16 v[126:129], v[166:169], v[182:185], v[126:129]
	v_mfma_f32_16x16x32_bf16 v[118:121], v[174:177], v[182:185], v[118:121]
	v_mfma_f32_16x16x32_bf16 v[110:113], v[166:169], v[190:193], v[110:113]
	v_mfma_f32_16x16x32_bf16 v[102:105], v[174:177], v[190:193], v[102:105]
	v_mfma_f32_16x16x32_bf16 v[94:97], v[166:169], v[198:201], v[94:97]
	v_mfma_f32_16x16x32_bf16 v[86:89], v[174:177], v[198:201], v[86:89]
	v_mfma_f32_16x16x32_bf16 v[78:81], v[166:169], v[206:209], v[78:81]
	v_mfma_f32_16x16x32_bf16 v[70:73], v[174:177], v[206:209], v[70:73]
	s_barrier
	s_add_i32 s40, 0, 0x14000
	s_add_i32 s7, s7, s3
	v_add_u32_e32 v145, s40, v153
	v_lshl_add_u64 v[218:219], s[0:1], 0, v[134:135]
	s_mov_b32 m0, s7
	ds_read_b128 v[210:213], v145
	ds_read_b128 v[214:217], v145 offset:1024
	ds_read_b128 v[238:241], v145 offset:2048
	ds_read_b128 v[242:245], v145 offset:3072
	global_load_lds_dwordx4 v[218:219], off
	v_lshl_add_u64 v[224:225], s[0:1], 0, v[130:131]
	s_add_i32 m0, s7, 0x2000
	s_nop 0
	global_load_lds_dwordx4 v[224:225], off
	s_barrier
	s_waitcnt lgkmcnt(0)
	s_waitcnt lgkmcnt(0)
	v_mfma_f32_16x16x32_bf16 v[122:125], v[210:213], v[178:181], v[122:125]
	v_mfma_f32_16x16x32_bf16 v[114:117], v[238:241], v[178:181], v[114:117]
	v_mfma_f32_16x16x32_bf16 v[106:109], v[210:213], v[186:189], v[106:109]
	v_mfma_f32_16x16x32_bf16 v[98:101], v[238:241], v[186:189], v[98:101]
	v_mfma_f32_16x16x32_bf16 v[90:93], v[210:213], v[194:197], v[90:93]
	v_mfma_f32_16x16x32_bf16 v[82:85], v[238:241], v[194:197], v[82:85]
	v_mfma_f32_16x16x32_bf16 v[74:77], v[210:213], v[202:205], v[74:77]
	v_mfma_f32_16x16x32_bf16 v[66:69], v[238:241], v[202:205], v[66:69]
	v_mfma_f32_16x16x32_bf16 v[122:125], v[214:217], v[182:185], v[122:125]
	v_mfma_f32_16x16x32_bf16 v[114:117], v[242:245], v[182:185], v[114:117]
	v_mfma_f32_16x16x32_bf16 v[106:109], v[214:217], v[190:193], v[106:109]
	v_mfma_f32_16x16x32_bf16 v[98:101], v[242:245], v[190:193], v[98:101]
	v_mfma_f32_16x16x32_bf16 v[90:93], v[214:217], v[198:201], v[90:93]
	v_mfma_f32_16x16x32_bf16 v[82:85], v[242:245], v[198:201], v[82:85]
	v_mfma_f32_16x16x32_bf16 v[74:77], v[214:217], v[206:209], v[74:77]
	v_mfma_f32_16x16x32_bf16 v[66:69], v[242:245], v[206:209], v[66:69]
	s_mov_b32 m0, s28
	v_lshl_add_u64 v[230:231], v[150:151], 0, v[136:137]
	s_barrier
	ds_read_b128 v[178:181], v157 offset:16384
	ds_read_b128 v[182:185], v157 offset:17408
	ds_read_b128 v[186:189], v157 offset:18432
	ds_read_b128 v[190:193], v157 offset:19456
	ds_read_b128 v[194:197], v157 offset:20480
	ds_read_b128 v[198:201], v157 offset:21504
	ds_read_b128 v[202:205], v157 offset:22528
	ds_read_b128 v[206:209], v157 offset:23552
	global_load_lds_dwordx4 v[230:231], off
	v_lshl_add_u64 v[246:247], v[150:151], 0, v[132:133]
	s_mov_b32 m0, s29
	s_nop 0
	global_load_lds_dwordx4 v[246:247], off
	s_barrier
	s_waitcnt lgkmcnt(0)
	s_waitcnt lgkmcnt(0)
	v_mfma_f32_16x16x32_bf16 v[58:61], v[162:165], v[178:181], v[58:61]
	v_mfma_f32_16x16x32_bf16 v[50:53], v[170:173], v[178:181], v[50:53]
	v_mfma_f32_16x16x32_bf16 v[42:45], v[162:165], v[186:189], v[42:45]
	v_mfma_f32_16x16x32_bf16 v[34:37], v[170:173], v[186:189], v[34:37]
	v_mfma_f32_16x16x32_bf16 v[26:29], v[162:165], v[194:197], v[26:29]
	v_mfma_f32_16x16x32_bf16 v[18:21], v[170:173], v[194:197], v[18:21]
	v_mfma_f32_16x16x32_bf16 v[6:9], v[162:165], v[202:205], v[6:9]
	v_mfma_f32_16x16x32_bf16 v[2:5], v[170:173], v[202:205], v[2:5]
	v_mfma_f32_16x16x32_bf16 v[58:61], v[166:169], v[182:185], v[58:61]
	v_mfma_f32_16x16x32_bf16 v[50:53], v[174:177], v[182:185], v[50:53]
	v_mfma_f32_16x16x32_bf16 v[42:45], v[166:169], v[190:193], v[42:45]
	v_mfma_f32_16x16x32_bf16 v[34:37], v[174:177], v[190:193], v[34:37]
	v_mfma_f32_16x16x32_bf16 v[26:29], v[166:169], v[198:201], v[26:29]
	v_mfma_f32_16x16x32_bf16 v[18:21], v[174:177], v[198:201], v[18:21]
	v_mfma_f32_16x16x32_bf16 v[6:9], v[166:169], v[206:209], v[6:9]
	v_mfma_f32_16x16x32_bf16 v[2:5], v[174:177], v[206:209], v[2:5]
	s_barrier
	s_add_u32 s0, s0, s94
	s_addc_u32 s1, s1, 0
	s_add_i32 s7, s40, s3
	v_lshl_add_u64 v[248:249], s[0:1], 0, v[134:135]
	s_mov_b32 m0, s7
	v_lshl_add_u64 v[232:233], s[0:1], 0, v[130:131]
	global_load_lds_dwordx4 v[248:249], off
	s_add_i32 m0, s7, 0x2000
	s_nop 0
	global_load_lds_dwordx4 v[232:233], off
	s_waitcnt vmcnt(6)
	s_barrier
	v_mfma_f32_16x16x32_bf16 v[62:65], v[210:213], v[178:181], v[62:65]
	v_mfma_f32_16x16x32_bf16 v[54:57], v[238:241], v[178:181], v[54:57]
	v_mfma_f32_16x16x32_bf16 v[46:49], v[210:213], v[186:189], v[46:49]
	v_mfma_f32_16x16x32_bf16 v[38:41], v[238:241], v[186:189], v[38:41]
	v_mfma_f32_16x16x32_bf16 v[30:33], v[210:213], v[194:197], v[30:33]
	v_mfma_f32_16x16x32_bf16 v[22:25], v[238:241], v[194:197], v[22:25]
	v_mfma_f32_16x16x32_bf16 v[14:17], v[210:213], v[202:205], v[14:17]
	v_mfma_f32_16x16x32_bf16 v[10:13], v[238:241], v[202:205], v[10:13]
	v_mfma_f32_16x16x32_bf16 v[62:65], v[214:217], v[182:185], v[62:65]
	v_mfma_f32_16x16x32_bf16 v[54:57], v[242:245], v[182:185], v[54:57]
	v_mfma_f32_16x16x32_bf16 v[46:49], v[214:217], v[190:193], v[46:49]
	v_mfma_f32_16x16x32_bf16 v[38:41], v[242:245], v[190:193], v[38:41]
	v_mfma_f32_16x16x32_bf16 v[30:33], v[214:217], v[198:201], v[30:33]
	v_mfma_f32_16x16x32_bf16 v[22:25], v[242:245], v[198:201], v[22:25]
	v_mfma_f32_16x16x32_bf16 v[14:17], v[214:217], v[206:209], v[14:17]
	v_mfma_f32_16x16x32_bf16 v[10:13], v[242:245], v[206:209], v[10:13]
	s_add_i32 s0, 0, 0x18000
	v_add_u32_e32 v145, s0, v153
	s_barrier
	ds_read_b128 v[162:165], v145
	ds_read_b128 v[166:169], v145 offset:1024
	ds_read_b128 v[170:173], v145 offset:2048
	ds_read_b128 v[174:177], v145 offset:3072
	v_lshl_add_u64 v[150:151], v[150:151], 0, s[94:95]
	s_mov_b32 m0, s34
	v_lshl_add_u64 v[210:211], v[150:151], 0, v[136:137]
	ds_read_b128 v[178:181], v157 offset:32768
	ds_read_b128 v[182:185], v157 offset:33792
	ds_read_b128 v[186:189], v157 offset:34816
	ds_read_b128 v[190:193], v157 offset:35840
	ds_read_b128 v[194:197], v157 offset:36864
	ds_read_b128 v[198:201], v157 offset:37888
	ds_read_b128 v[202:205], v157 offset:38912
	ds_read_b128 v[206:209], v157 offset:39936
	global_load_lds_dwordx4 v[210:211], off
	v_lshl_add_u64 v[150:151], v[150:151], 0, v[132:133]
	s_mov_b32 m0, s35
	s_nop 0
	global_load_lds_dwordx4 v[150:151], off
	s_waitcnt lgkmcnt(8)
	s_barrier
	s_waitcnt lgkmcnt(0)
	s_waitcnt lgkmcnt(0)
	v_mfma_f32_16x16x32_bf16 v[126:129], v[162:165], v[178:181], v[126:129]
	v_mfma_f32_16x16x32_bf16 v[118:121], v[170:173], v[178:181], v[118:121]
	v_mfma_f32_16x16x32_bf16 v[110:113], v[162:165], v[186:189], v[110:113]
	v_mfma_f32_16x16x32_bf16 v[102:105], v[170:173], v[186:189], v[102:105]
	v_mfma_f32_16x16x32_bf16 v[94:97], v[162:165], v[194:197], v[94:97]
	v_mfma_f32_16x16x32_bf16 v[86:89], v[170:173], v[194:197], v[86:89]
	v_mfma_f32_16x16x32_bf16 v[78:81], v[162:165], v[202:205], v[78:81]
	v_mfma_f32_16x16x32_bf16 v[70:73], v[170:173], v[202:205], v[70:73]
	v_mfma_f32_16x16x32_bf16 v[126:129], v[166:169], v[182:185], v[126:129]
	v_mfma_f32_16x16x32_bf16 v[118:121], v[174:177], v[182:185], v[118:121]
	v_mfma_f32_16x16x32_bf16 v[110:113], v[166:169], v[190:193], v[110:113]
	v_mfma_f32_16x16x32_bf16 v[102:105], v[174:177], v[190:193], v[102:105]
	v_mfma_f32_16x16x32_bf16 v[94:97], v[166:169], v[198:201], v[94:97]
	v_mfma_f32_16x16x32_bf16 v[86:89], v[174:177], v[198:201], v[86:89]
	v_mfma_f32_16x16x32_bf16 v[78:81], v[166:169], v[206:209], v[78:81]
	v_mfma_f32_16x16x32_bf16 v[70:73], v[174:177], v[206:209], v[70:73]
	s_barrier
	s_add_i32 s1, 0, 0x1c000
	s_add_i32 s0, s0, s3
	v_add_u32_e32 v145, s1, v153
	v_lshl_add_u64 v[150:151], v[218:219], 0, s[84:85]
	s_mov_b32 m0, s0
	ds_read_b128 v[210:213], v145
	ds_read_b128 v[214:217], v145 offset:1024
	ds_read_b128 v[238:241], v145 offset:2048
	ds_read_b128 v[242:245], v145 offset:3072
	global_load_lds_dwordx4 v[150:151], off
	v_lshl_add_u64 v[150:151], v[224:225], 0, s[84:85]
	s_add_i32 m0, s0, 0x2000
	s_nop 0
	global_load_lds_dwordx4 v[150:151], off
	s_barrier
	s_waitcnt lgkmcnt(0)
	s_waitcnt lgkmcnt(0)
	v_mfma_f32_16x16x32_bf16 v[122:125], v[210:213], v[178:181], v[122:125]
	v_mfma_f32_16x16x32_bf16 v[114:117], v[238:241], v[178:181], v[114:117]
	v_mfma_f32_16x16x32_bf16 v[106:109], v[210:213], v[186:189], v[106:109]
	v_mfma_f32_16x16x32_bf16 v[98:101], v[238:241], v[186:189], v[98:101]
	v_mfma_f32_16x16x32_bf16 v[90:93], v[210:213], v[194:197], v[90:93]
	v_mfma_f32_16x16x32_bf16 v[82:85], v[238:241], v[194:197], v[82:85]
	v_mfma_f32_16x16x32_bf16 v[74:77], v[210:213], v[202:205], v[74:77]
	v_mfma_f32_16x16x32_bf16 v[66:69], v[238:241], v[202:205], v[66:69]
	v_mfma_f32_16x16x32_bf16 v[122:125], v[214:217], v[182:185], v[122:125]
	v_mfma_f32_16x16x32_bf16 v[114:117], v[242:245], v[182:185], v[114:117]
	v_mfma_f32_16x16x32_bf16 v[106:109], v[214:217], v[190:193], v[106:109]
	v_mfma_f32_16x16x32_bf16 v[98:101], v[242:245], v[190:193], v[98:101]
	v_mfma_f32_16x16x32_bf16 v[90:93], v[214:217], v[198:201], v[90:93]
	v_mfma_f32_16x16x32_bf16 v[82:85], v[242:245], v[198:201], v[82:85]
	v_mfma_f32_16x16x32_bf16 v[74:77], v[214:217], v[206:209], v[74:77]
	v_mfma_f32_16x16x32_bf16 v[66:69], v[242:245], v[206:209], v[66:69]
	s_mov_b32 m0, s36
	v_lshl_add_u64 v[150:151], v[230:231], 0, s[84:85]
	s_barrier
	ds_read_b128 v[178:181], v157 offset:49152
	ds_read_b128 v[182:185], v157 offset:50176
	ds_read_b128 v[186:189], v157 offset:51200
	ds_read_b128 v[190:193], v157 offset:52224
	ds_read_b128 v[194:197], v157 offset:53248
	ds_read_b128 v[198:201], v157 offset:54272
	ds_read_b128 v[202:205], v157 offset:55296
	ds_read_b128 v[206:209], v157 offset:56320
	global_load_lds_dwordx4 v[150:151], off
	v_lshl_add_u64 v[150:151], v[246:247], 0, s[84:85]
	s_mov_b32 m0, s42
	s_nop 0
	global_load_lds_dwordx4 v[150:151], off
	s_barrier
	s_waitcnt lgkmcnt(0)
	s_waitcnt lgkmcnt(0)
	v_mfma_f32_16x16x32_bf16 v[58:61], v[162:165], v[178:181], v[58:61]
	v_mfma_f32_16x16x32_bf16 v[50:53], v[170:173], v[178:181], v[50:53]
	v_mfma_f32_16x16x32_bf16 v[42:45], v[162:165], v[186:189], v[42:45]
	v_mfma_f32_16x16x32_bf16 v[34:37], v[170:173], v[186:189], v[34:37]
	v_mfma_f32_16x16x32_bf16 v[26:29], v[162:165], v[194:197], v[26:29]
	v_mfma_f32_16x16x32_bf16 v[18:21], v[170:173], v[194:197], v[18:21]
	v_mfma_f32_16x16x32_bf16 v[6:9], v[162:165], v[202:205], v[6:9]
	v_mfma_f32_16x16x32_bf16 v[2:5], v[170:173], v[202:205], v[2:5]
	v_mfma_f32_16x16x32_bf16 v[58:61], v[166:169], v[182:185], v[58:61]
	v_mfma_f32_16x16x32_bf16 v[50:53], v[174:177], v[182:185], v[50:53]
	v_mfma_f32_16x16x32_bf16 v[42:45], v[166:169], v[190:193], v[42:45]
	v_mfma_f32_16x16x32_bf16 v[34:37], v[174:177], v[190:193], v[34:37]
	v_mfma_f32_16x16x32_bf16 v[26:29], v[166:169], v[198:201], v[26:29]
	v_mfma_f32_16x16x32_bf16 v[18:21], v[174:177], v[198:201], v[18:21]
	v_mfma_f32_16x16x32_bf16 v[6:9], v[166:169], v[206:209], v[6:9]
	v_mfma_f32_16x16x32_bf16 v[2:5], v[174:177], v[206:209], v[2:5]
	s_barrier
	s_add_i32 s0, s1, s3
	v_lshl_add_u64 v[150:151], v[248:249], 0, s[84:85]
	s_mov_b32 m0, s0
	s_nop 0
	global_load_lds_dwordx4 v[150:151], off
	v_lshl_add_u64 v[150:151], v[232:233], 0, s[84:85]
	s_add_i32 m0, s0, 0x2000
	s_nop 0
	global_load_lds_dwordx4 v[150:151], off
	s_waitcnt vmcnt(6)
	s_barrier
	v_mfma_f32_16x16x32_bf16 v[62:65], v[210:213], v[178:181], v[62:65]
	v_mfma_f32_16x16x32_bf16 v[54:57], v[238:241], v[178:181], v[54:57]
	v_mfma_f32_16x16x32_bf16 v[46:49], v[210:213], v[186:189], v[46:49]
	v_mfma_f32_16x16x32_bf16 v[38:41], v[238:241], v[186:189], v[38:41]
	v_mfma_f32_16x16x32_bf16 v[30:33], v[210:213], v[194:197], v[30:33]
	v_mfma_f32_16x16x32_bf16 v[22:25], v[238:241], v[194:197], v[22:25]
	v_mfma_f32_16x16x32_bf16 v[14:17], v[210:213], v[202:205], v[14:17]
	v_mfma_f32_16x16x32_bf16 v[10:13], v[238:241], v[202:205], v[10:13]
	v_mfma_f32_16x16x32_bf16 v[62:65], v[214:217], v[182:185], v[62:65]
	v_mfma_f32_16x16x32_bf16 v[54:57], v[242:245], v[182:185], v[54:57]
	v_mfma_f32_16x16x32_bf16 v[46:49], v[214:217], v[190:193], v[46:49]
	v_mfma_f32_16x16x32_bf16 v[38:41], v[242:245], v[190:193], v[38:41]
	v_mfma_f32_16x16x32_bf16 v[30:33], v[214:217], v[198:201], v[30:33]
	v_mfma_f32_16x16x32_bf16 v[22:25], v[242:245], v[198:201], v[22:25]
	v_mfma_f32_16x16x32_bf16 v[14:17], v[214:217], v[206:209], v[14:17]
	v_mfma_f32_16x16x32_bf16 v[10:13], v[242:245], v[206:209], v[10:13]
	s_add_u32 s4, s4, 0x100
	s_addc_u32 s5, s5, 0
	v_lshl_add_u64 v[148:149], v[148:149], 0, s[86:87]
	s_cmp_ge_u32 s6, s13
	s_mov_b32 s0, s6
	s_barrier
	s_cbranch_scc0 .LBB0_824
	v_cmp_lt_i32_e32 vcc, v227, v222
	ds_read2st64_b32 v[150:151], v161 offset1:1
	ds_read2st64_b32 v[168:169], v161 offset0:2 offset1:3
	ds_read2st64_b32 v[170:171], v161 offset0:4 offset1:5
	ds_read2st64_b32 v[148:149], v161 offset0:6 offset1:7
	v_cndmask_b32_e32 v145, v221, v227, vcc
	v_lshlrev_b32_e32 v145, 2, v145
	s_waitcnt lgkmcnt(0)
	ds_bpermute_b32 v167, v145, v150
	ds_bpermute_b32 v166, v145, v151
	v_cmp_lt_i32_e32 vcc, v228, v222
	v_mov_b32_e32 v162, v151
	v_mov_b32_e32 v163, v150
	v_cndmask_b32_e32 v152, v221, v228, vcc
	v_lshlrev_b32_e32 v165, 2, v152
	s_waitcnt lgkmcnt(0)
	v_pk_add_f32 v[150:151], v[162:163], v[166:167]
	ds_bpermute_b32 v163, v165, v151
	ds_bpermute_b32 v162, v165, v150
	s_mov_b32 s0, 0x358637bd
	s_mov_b32 s4, 0x3a800000
	ds_bpermute_b32 v175, v145, v168
	ds_bpermute_b32 v174, v145, v169
	s_waitcnt lgkmcnt(0)
	v_pk_add_f32 v[162:163], v[150:151], v[162:163]
	v_mov_b64_e32 v[150:151], s[0:1]
	v_pk_fma_f32 v[162:163], v[162:163], s[4:5], v[150:151] op_sel_hi:[1,0,0]
	v_mov_b32_e32 v172, v169
	v_mul_f32_e32 v152, 0x4b800000, v163
	v_cmp_gt_f32_e64 s[0:1], s88, v163
	v_mov_b32_e32 v173, v168
	v_pk_add_f32 v[168:169], v[172:173], v[174:175]
	v_cndmask_b32_e64 v152, v163, v152, s[0:1]
	v_rsq_f32_e32 v152, v152
	v_cmp_gt_f32_e32 vcc, s88, v162
	ds_bpermute_b32 v173, v165, v169
	ds_bpermute_b32 v172, v165, v168
	v_mul_f32_e32 v154, 0x45800000, v152
	v_cndmask_b32_e64 v166, v152, v154, s[0:1]
	v_mul_f32_e32 v152, 0x4b800000, v162
	v_cndmask_b32_e32 v152, v162, v152, vcc
	v_rsq_f32_e32 v152, v152
	s_waitcnt lgkmcnt(0)
	v_pk_add_f32 v[168:169], v[168:169], v[172:173]
	ds_bpermute_b32 v173, v145, v170
	v_pk_fma_f32 v[168:169], v[168:169], s[4:5], v[150:151] op_sel_hi:[1,0,0]
	v_mul_f32_e32 v154, 0x45800000, v152
	v_cndmask_b32_e32 v162, v152, v154, vcc
	v_mul_f32_e32 v152, 0x4b800000, v169
	v_cmp_gt_f32_e64 s[0:1], s88, v169
	ds_bpermute_b32 v172, v145, v171
	v_cmp_gt_f32_e32 vcc, s88, v168
	v_cndmask_b32_e64 v152, v169, v152, s[0:1]
	v_rsq_f32_e32 v152, v152
	v_mov_b32_e32 v169, v170
	v_lshl_or_b32 v164, s17, 7, v155
	s_mov_b32 s17, s90
	v_mul_f32_e32 v154, 0x45800000, v152
	v_cndmask_b32_e64 v160, v152, v154, s[0:1]
	v_mul_f32_e32 v152, 0x4b800000, v168
	v_cndmask_b32_e32 v152, v168, v152, vcc
	v_mov_b32_e32 v168, v171
	s_waitcnt lgkmcnt(0)
	v_pk_add_f32 v[168:169], v[168:169], v[172:173]
	ds_bpermute_b32 v171, v165, v169
	ds_bpermute_b32 v170, v165, v168
	v_rsq_f32_e32 v152, v152
	s_mov_b32 s40, s91
	s_waitcnt lgkmcnt(0)
	v_pk_add_f32 v[168:169], v[168:169], v[170:171]
	v_mul_f32_e32 v154, 0x45800000, v152
	v_pk_fma_f32 v[168:169], v[168:169], s[4:5], v[150:151] op_sel_hi:[1,0,0]
	v_cndmask_b32_e32 v156, v152, v154, vcc
	v_mul_f32_e32 v152, 0x4b800000, v169
	v_cmp_gt_f32_e64 s[0:1], s88, v169
	ds_bpermute_b32 v171, v145, v148
	ds_bpermute_b32 v170, v145, v149
	v_cndmask_b32_e64 v152, v169, v152, s[0:1]
	v_rsq_f32_e32 v152, v152
	v_cmp_gt_f32_e32 vcc, s88, v168
	v_mov_b32_e32 v169, v148
	v_mul_f32_e32 v154, 0x45800000, v152
	v_cndmask_b32_e64 v154, v152, v154, s[0:1]
	v_mul_f32_e32 v152, 0x4b800000, v168
	v_cndmask_b32_e32 v152, v168, v152, vcc
	v_mov_b32_e32 v168, v149
	s_waitcnt lgkmcnt(0)
	v_pk_add_f32 v[148:149], v[168:169], v[170:171]
	ds_bpermute_b32 v169, v165, v149
	ds_bpermute_b32 v168, v165, v148
	v_rsq_f32_e32 v152, v152
	v_ashrrev_i32_e32 v165, 31, v164
	s_waitcnt lgkmcnt(0)
	v_pk_add_f32 v[148:149], v[148:149], v[168:169]
	s_nop 0
	v_pk_fma_f32 v[148:149], v[148:149], s[4:5], v[150:151] op_sel_hi:[1,0,0]
	v_mov_b32_e32 v168, v122
	v_mul_f32_e32 v145, 0x4b800000, v149
	v_cmp_gt_f32_e64 s[0:1], s88, v149
	v_mov_b32_e32 v169, v126
	v_pk_mul_f32 v[168:169], v[168:169], v[166:167] op_sel_hi:[1,0]
	v_cndmask_b32_e64 v145, v149, v145, s[0:1]
	v_rsq_f32_e32 v145, v145
	v_mul_f32_e32 v122, 0xbfb8aa3b, v169
	v_exp_f32_e32 v122, v122
	v_mul_f32_e32 v163, 0x45800000, v152
	v_mul_f32_e32 v149, 0x45800000, v145
	v_cndmask_b32_e32 v152, v152, v163, vcc
	v_cmp_gt_f32_e32 vcc, s88, v148
	v_cndmask_b32_e64 v150, v145, v149, s[0:1]
	v_mul_f32_e32 v145, 0x4b800000, v148
	v_cndmask_b32_e32 v145, v148, v145, vcc
	v_add_f32_e32 v122, 1.0, v122
	v_rsq_f32_e32 v145, v145
	v_rcp_f32_e32 v122, v122
	v_mov_b32_e32 v126, v123
	s_mov_b64 s[4:5], s[22:23]
	v_mul_f32_e32 v148, 0x45800000, v145
	v_mul_f32_e32 v122, v169, v122
	v_cndmask_b32_e32 v148, v145, v148, vcc
	v_mul_f32_e32 v145, v168, v122
	v_pk_mul_f32 v[122:123], v[126:127], v[166:167] op_sel_hi:[1,0]
	s_and_b64 vcc, exec, s[38:39]
	v_mul_f32_e32 v126, 0xbfb8aa3b, v123
	v_exp_f32_e32 v126, v126
	s_nop 0
	v_add_f32_e32 v126, 1.0, v126
	v_rcp_f32_e32 v126, v126
	s_nop 0
	v_mul_f32_e32 v123, v123, v126
	v_mul_f32_e32 v126, v122, v123
	v_mov_b32_e32 v122, v124
	v_mov_b32_e32 v123, v128
	v_pk_mul_f32 v[122:123], v[122:123], v[166:167] op_sel_hi:[1,0]
	v_mov_b32_e32 v128, v125
	v_mul_f32_e32 v124, 0xbfb8aa3b, v123
	v_exp_f32_e32 v124, v124
	s_nop 0
	v_add_f32_e32 v124, 1.0, v124
	v_rcp_f32_e32 v124, v124
	s_nop 0
	v_mul_f32_e32 v123, v123, v124
	v_mul_f32_e32 v124, v122, v123
	v_pk_mul_f32 v[122:123], v[128:129], v[166:167] op_sel_hi:[1,0]
	s_nop 0
	v_mul_f32_e32 v125, 0xbfb8aa3b, v123
	v_exp_f32_e32 v125, v125
	s_nop 0
	v_add_f32_e32 v125, 1.0, v125
	v_rcp_f32_e32 v125, v125
	s_nop 0
	v_mul_f32_e32 v123, v123, v125
	v_mul_f32_e32 v125, v122, v123
	v_mov_b32_e32 v122, v114
	v_mov_b32_e32 v123, v118
	v_pk_mul_f32 v[122:123], v[122:123], v[166:167] op_sel_hi:[1,0]
	v_mov_b32_e32 v118, v115
	v_mul_f32_e32 v114, 0xbfb8aa3b, v123
	v_exp_f32_e32 v114, v114
	s_nop 0
	v_add_f32_e32 v114, 1.0, v114
	v_rcp_f32_e32 v114, v114
	s_nop 0
	v_mul_f32_e32 v114, v123, v114
	v_mul_f32_e32 v122, v122, v114
	v_pk_mul_f32 v[114:115], v[118:119], v[166:167] op_sel_hi:[1,0]
	s_nop 0
	v_mul_f32_e32 v118, 0xbfb8aa3b, v115
	v_exp_f32_e32 v118, v118
	s_nop 0
	v_add_f32_e32 v118, 1.0, v118
	v_rcp_f32_e32 v118, v118
	s_nop 0
	v_mul_f32_e32 v115, v115, v118
	v_mul_f32_e32 v123, v114, v115
	v_mov_b32_e32 v114, v116
	v_mov_b32_e32 v115, v120
	v_pk_mul_f32 v[114:115], v[114:115], v[166:167] op_sel_hi:[1,0]
	v_mov_b32_e32 v120, v117
	v_mul_f32_e32 v116, 0xbfb8aa3b, v115
	v_exp_f32_e32 v116, v116
	v_cvt_pk_bf16_f32 v118, v145, v126
	v_cvt_pk_bf16_f32 v119, v124, v125
	s_nop 0
	v_add_f32_e32 v116, 1.0, v116
	v_rcp_f32_e32 v116, v116
	s_nop 0
	v_mul_f32_e32 v115, v115, v116
	v_mul_f32_e32 v116, v114, v115
	v_pk_mul_f32 v[114:115], v[120:121], v[166:167] op_sel_hi:[1,0]
	v_cvt_pk_bf16_f32 v120, v122, v123
	s_nop 0
	v_mul_f32_e32 v117, 0xbfb8aa3b, v115
	v_exp_f32_e32 v117, v117
	s_nop 0
	v_add_f32_e32 v117, 1.0, v117
	v_rcp_f32_e32 v117, v117
	s_nop 0
	v_mul_f32_e32 v115, v115, v117
	v_mul_f32_e32 v114, v114, v115
	v_cvt_pk_bf16_f32 v121, v116, v114
	v_mov_b64_e32 v[114:115], s[20:21]
	v_mad_i64_i32 v[122:123], s[0:1], v144, s89, v[114:115]
	v_lshlrev_b64 v[116:117], 1, v[164:165]
	v_lshl_add_u64 v[122:123], v[122:123], 0, v[116:117]
	global_store_dwordx4 v[122:123], v[118:121], off
	s_nop 1
	v_mov_b32_e32 v118, v106
	v_mov_b32_e32 v119, v110
	v_pk_mul_f32 v[118:119], v[118:119], v[162:163] op_sel_hi:[1,0]
	v_mov_b32_e32 v110, v107
	v_mul_f32_e32 v106, 0xbfb8aa3b, v119
	v_exp_f32_e32 v106, v106
	s_nop 0
	v_add_f32_e32 v106, 1.0, v106
	v_rcp_f32_e32 v106, v106
	s_nop 0
	v_mul_f32_e32 v106, v119, v106
	v_mul_f32_e32 v118, v118, v106
	v_pk_mul_f32 v[106:107], v[110:111], v[162:163] op_sel_hi:[1,0]
	s_nop 0
	v_mul_f32_e32 v110, 0xbfb8aa3b, v107
	v_exp_f32_e32 v110, v110
	s_nop 0
	v_add_f32_e32 v110, 1.0, v110
	v_rcp_f32_e32 v110, v110
	s_nop 0
	v_mul_f32_e32 v107, v107, v110
	v_mul_f32_e32 v110, v106, v107
	v_mov_b32_e32 v106, v108
	v_mov_b32_e32 v107, v112
	v_pk_mul_f32 v[106:107], v[106:107], v[162:163] op_sel_hi:[1,0]
	v_mov_b32_e32 v112, v109
	v_mul_f32_e32 v108, 0xbfb8aa3b, v107
	v_exp_f32_e32 v108, v108
	s_nop 0
	v_add_f32_e32 v108, 1.0, v108
	v_rcp_f32_e32 v108, v108
	s_nop 0
	v_mul_f32_e32 v107, v107, v108
	v_mul_f32_e32 v108, v106, v107
	v_pk_mul_f32 v[106:107], v[112:113], v[162:163] op_sel_hi:[1,0]
	s_nop 0
	v_mul_f32_e32 v109, 0xbfb8aa3b, v107
	v_exp_f32_e32 v109, v109
	s_nop 0
	v_add_f32_e32 v109, 1.0, v109
	v_rcp_f32_e32 v109, v109
	s_nop 0
	v_mul_f32_e32 v107, v107, v109
	v_mul_f32_e32 v109, v106, v107
	v_mov_b32_e32 v106, v98
	v_mov_b32_e32 v107, v102
	v_pk_mul_f32 v[106:107], v[106:107], v[162:163] op_sel_hi:[1,0]
	v_mov_b32_e32 v102, v99
	v_mul_f32_e32 v98, 0xbfb8aa3b, v107
	v_exp_f32_e32 v98, v98
	s_nop 0
	v_add_f32_e32 v98, 1.0, v98
	v_rcp_f32_e32 v98, v98
	s_nop 0
	v_mul_f32_e32 v98, v107, v98
	v_mul_f32_e32 v106, v106, v98
	v_pk_mul_f32 v[98:99], v[102:103], v[162:163] op_sel_hi:[1,0]
	s_nop 0
	v_mul_f32_e32 v102, 0xbfb8aa3b, v99
	v_exp_f32_e32 v102, v102
	s_nop 0
	v_add_f32_e32 v102, 1.0, v102
	v_rcp_f32_e32 v102, v102
	s_nop 0
	v_mul_f32_e32 v99, v99, v102
	v_mul_f32_e32 v102, v98, v99
	v_mov_b32_e32 v98, v100
	v_mov_b32_e32 v99, v104
	v_pk_mul_f32 v[98:99], v[98:99], v[162:163] op_sel_hi:[1,0]
	v_mov_b32_e32 v104, v101
	v_mul_f32_e32 v100, 0xbfb8aa3b, v99
	v_exp_f32_e32 v100, v100
	s_nop 0
	v_add_f32_e32 v100, 1.0, v100
	v_rcp_f32_e32 v100, v100
	s_nop 0
	v_mul_f32_e32 v99, v99, v100
	v_mul_f32_e32 v103, v98, v99
	v_pk_mul_f32 v[98:99], v[104:105], v[162:163] op_sel_hi:[1,0]
	v_or_b32_e32 v104, 16, v144
	v_mul_f32_e32 v100, 0xbfb8aa3b, v99
	v_exp_f32_e32 v100, v100
	s_nop 0
	v_add_f32_e32 v100, 1.0, v100
	v_rcp_f32_e32 v100, v100
	s_nop 0
	v_mul_f32_e32 v99, v99, v100
	v_mul_f32_e32 v101, v98, v99
	v_cvt_pk_bf16_f32 v98, v118, v110
	v_cvt_pk_bf16_f32 v99, v108, v109
	v_cvt_pk_bf16_f32 v100, v106, v102
	v_cvt_pk_bf16_f32 v101, v103, v101
	v_mad_i64_i32 v[102:103], s[0:1], v104, s89, v[114:115]
	v_lshl_add_u64 v[102:103], v[102:103], 0, v[116:117]
	global_store_dwordx4 v[102:103], v[98:101], off
	s_nop 1
	v_mov_b32_e32 v98, v90
	v_mov_b32_e32 v99, v94
	v_pk_mul_f32 v[98:99], v[98:99], v[160:161] op_sel_hi:[1,0]
	v_mov_b32_e32 v94, v91
	v_mul_f32_e32 v90, 0xbfb8aa3b, v99
	v_exp_f32_e32 v90, v90
	s_nop 0
	v_add_f32_e32 v90, 1.0, v90
	v_rcp_f32_e32 v90, v90
	s_nop 0
	v_mul_f32_e32 v90, v99, v90
	v_mul_f32_e32 v98, v98, v90
	v_pk_mul_f32 v[90:91], v[94:95], v[160:161] op_sel_hi:[1,0]
	s_nop 0
	v_mul_f32_e32 v94, 0xbfb8aa3b, v91
	v_exp_f32_e32 v94, v94
	s_nop 0
	v_add_f32_e32 v94, 1.0, v94
	v_rcp_f32_e32 v94, v94
	s_nop 0
	v_mul_f32_e32 v91, v91, v94
	v_mul_f32_e32 v94, v90, v91
	v_mov_b32_e32 v90, v92
	v_mov_b32_e32 v91, v96
	v_pk_mul_f32 v[90:91], v[90:91], v[160:161] op_sel_hi:[1,0]
	v_mov_b32_e32 v96, v93
	v_mul_f32_e32 v92, 0xbfb8aa3b, v91
	v_exp_f32_e32 v92, v92
	s_nop 0
	v_add_f32_e32 v92, 1.0, v92
	v_rcp_f32_e32 v92, v92
	s_nop 0
	v_mul_f32_e32 v91, v91, v92
	v_mul_f32_e32 v92, v90, v91
	v_pk_mul_f32 v[90:91], v[96:97], v[160:161] op_sel_hi:[1,0]
	s_nop 0
	v_mul_f32_e32 v93, 0xbfb8aa3b, v91
	v_exp_f32_e32 v93, v93
	s_nop 0
	v_add_f32_e32 v93, 1.0, v93
	v_rcp_f32_e32 v93, v93
	s_nop 0
	v_mul_f32_e32 v91, v91, v93
	v_mul_f32_e32 v93, v90, v91
	v_mov_b32_e32 v90, v82
	v_mov_b32_e32 v91, v86
	v_pk_mul_f32 v[90:91], v[90:91], v[160:161] op_sel_hi:[1,0]
	v_mov_b32_e32 v86, v83
	v_mul_f32_e32 v82, 0xbfb8aa3b, v91
	v_exp_f32_e32 v82, v82
	s_nop 0
	v_add_f32_e32 v82, 1.0, v82
	v_rcp_f32_e32 v82, v82
	s_nop 0
	v_mul_f32_e32 v82, v91, v82
	v_mul_f32_e32 v90, v90, v82
	v_pk_mul_f32 v[82:83], v[86:87], v[160:161] op_sel_hi:[1,0]
	s_nop 0
	v_mul_f32_e32 v86, 0xbfb8aa3b, v83
	v_exp_f32_e32 v86, v86
	s_nop 0
	v_add_f32_e32 v86, 1.0, v86
	v_rcp_f32_e32 v86, v86
	s_nop 0
	v_mul_f32_e32 v83, v83, v86
	v_mul_f32_e32 v86, v82, v83
	v_mov_b32_e32 v82, v84
	v_mov_b32_e32 v83, v88
	v_pk_mul_f32 v[82:83], v[82:83], v[160:161] op_sel_hi:[1,0]
	v_mov_b32_e32 v88, v85
	v_mul_f32_e32 v84, 0xbfb8aa3b, v83
	v_exp_f32_e32 v84, v84
	s_nop 0
	v_add_f32_e32 v84, 1.0, v84
	v_rcp_f32_e32 v84, v84
	s_nop 0
	v_mul_f32_e32 v83, v83, v84
	v_mul_f32_e32 v87, v82, v83
	v_pk_mul_f32 v[82:83], v[88:89], v[160:161] op_sel_hi:[1,0]
	v_or_b32_e32 v88, 32, v144
	v_mul_f32_e32 v84, 0xbfb8aa3b, v83
	v_exp_f32_e32 v84, v84
	s_nop 0
	v_add_f32_e32 v84, 1.0, v84
	v_rcp_f32_e32 v84, v84
	s_nop 0
	v_mul_f32_e32 v83, v83, v84
	v_mul_f32_e32 v85, v82, v83
	v_cvt_pk_bf16_f32 v82, v98, v94
	v_cvt_pk_bf16_f32 v83, v92, v93
	v_cvt_pk_bf16_f32 v84, v90, v86
	v_cvt_pk_bf16_f32 v85, v87, v85
	v_mad_i64_i32 v[86:87], s[0:1], v88, s89, v[114:115]
	v_lshl_add_u64 v[86:87], v[86:87], 0, v[116:117]
	global_store_dwordx4 v[86:87], v[82:85], off
	s_nop 1
	v_mov_b32_e32 v82, v74
	v_mov_b32_e32 v83, v78
	v_pk_mul_f32 v[82:83], v[82:83], v[156:157] op_sel_hi:[1,0]
	v_mov_b32_e32 v78, v75
	v_mul_f32_e32 v74, 0xbfb8aa3b, v83
	v_exp_f32_e32 v74, v74
	s_nop 0
	v_add_f32_e32 v74, 1.0, v74
	v_rcp_f32_e32 v74, v74
	s_nop 0
	v_mul_f32_e32 v74, v83, v74
	v_mul_f32_e32 v82, v82, v74
	v_pk_mul_f32 v[74:75], v[78:79], v[156:157] op_sel_hi:[1,0]
	s_nop 0
	v_mul_f32_e32 v78, 0xbfb8aa3b, v75
	v_exp_f32_e32 v78, v78
	s_nop 0
	v_add_f32_e32 v78, 1.0, v78
	v_rcp_f32_e32 v78, v78
	s_nop 0
	v_mul_f32_e32 v75, v75, v78
	v_mul_f32_e32 v78, v74, v75
	v_mov_b32_e32 v74, v76
	v_mov_b32_e32 v75, v80
	v_pk_mul_f32 v[74:75], v[74:75], v[156:157] op_sel_hi:[1,0]
	v_mov_b32_e32 v80, v77
	v_mul_f32_e32 v76, 0xbfb8aa3b, v75
	v_exp_f32_e32 v76, v76
	s_nop 0
	v_add_f32_e32 v76, 1.0, v76
	v_rcp_f32_e32 v76, v76
	s_nop 0
	v_mul_f32_e32 v75, v75, v76
	v_mul_f32_e32 v76, v74, v75
	v_pk_mul_f32 v[74:75], v[80:81], v[156:157] op_sel_hi:[1,0]
	s_nop 0
	v_mul_f32_e32 v77, 0xbfb8aa3b, v75
	v_exp_f32_e32 v77, v77
	s_nop 0
	v_add_f32_e32 v77, 1.0, v77
	v_rcp_f32_e32 v77, v77
	s_nop 0
	v_mul_f32_e32 v75, v75, v77
	v_mul_f32_e32 v77, v74, v75
	v_mov_b32_e32 v74, v66
	v_mov_b32_e32 v75, v70
	v_pk_mul_f32 v[74:75], v[74:75], v[156:157] op_sel_hi:[1,0]
	v_mov_b32_e32 v70, v67
	v_mul_f32_e32 v66, 0xbfb8aa3b, v75
	v_exp_f32_e32 v66, v66
	s_nop 0
	v_add_f32_e32 v66, 1.0, v66
	v_rcp_f32_e32 v66, v66
	s_nop 0
	v_mul_f32_e32 v66, v75, v66
	v_mul_f32_e32 v74, v74, v66
	v_pk_mul_f32 v[66:67], v[70:71], v[156:157] op_sel_hi:[1,0]
	s_nop 0
	v_mul_f32_e32 v70, 0xbfb8aa3b, v67
	v_exp_f32_e32 v70, v70
	s_nop 0
	v_add_f32_e32 v70, 1.0, v70
	v_rcp_f32_e32 v70, v70
	s_nop 0
	v_mul_f32_e32 v67, v67, v70
	v_mul_f32_e32 v70, v66, v67
	v_mov_b32_e32 v66, v68
	v_mov_b32_e32 v67, v72
	v_pk_mul_f32 v[66:67], v[66:67], v[156:157] op_sel_hi:[1,0]
	v_mov_b32_e32 v72, v69
	v_mul_f32_e32 v68, 0xbfb8aa3b, v67
	v_exp_f32_e32 v68, v68
	s_nop 0
	v_add_f32_e32 v68, 1.0, v68
	v_rcp_f32_e32 v68, v68
	s_nop 0
	v_mul_f32_e32 v67, v67, v68
	v_mul_f32_e32 v71, v66, v67
	v_pk_mul_f32 v[66:67], v[72:73], v[156:157] op_sel_hi:[1,0]
	v_or_b32_e32 v72, 48, v144
	v_mul_f32_e32 v68, 0xbfb8aa3b, v67
	v_exp_f32_e32 v68, v68
	s_nop 0
	v_add_f32_e32 v68, 1.0, v68
	v_rcp_f32_e32 v68, v68
	s_nop 0
	v_mul_f32_e32 v67, v67, v68
	v_mul_f32_e32 v69, v66, v67
	v_cvt_pk_bf16_f32 v66, v82, v78
	v_cvt_pk_bf16_f32 v67, v76, v77
	v_cvt_pk_bf16_f32 v68, v74, v70
	v_cvt_pk_bf16_f32 v69, v71, v69
	v_mad_i64_i32 v[70:71], s[0:1], v72, s89, v[114:115]
	v_lshl_add_u64 v[70:71], v[70:71], 0, v[116:117]
	global_store_dwordx4 v[70:71], v[66:69], off
	s_nop 1
	v_mov_b32_e32 v66, v62
	v_mov_b32_e32 v67, v58
	v_pk_mul_f32 v[66:67], v[66:67], v[154:155] op_sel_hi:[1,0]
	v_add_u32_e32 v68, 0x80, v144
	v_mul_f32_e32 v58, 0xbfb8aa3b, v67
	v_exp_f32_e32 v58, v58
	s_nop 0
	v_add_f32_e32 v58, 1.0, v58
	v_rcp_f32_e32 v58, v58
	s_nop 0
	v_mul_f32_e32 v58, v67, v58
	v_mul_f32_e32 v62, v66, v58
	v_mov_b32_e32 v58, v63
	v_pk_mul_f32 v[58:59], v[58:59], v[154:155] op_sel_hi:[1,0]
	s_nop 0
	v_mul_f32_e32 v63, 0xbfb8aa3b, v59
	v_exp_f32_e32 v63, v63
	s_nop 0
	v_add_f32_e32 v63, 1.0, v63
	v_rcp_f32_e32 v63, v63
	s_nop 0
	v_mul_f32_e32 v59, v59, v63
	v_mul_f32_e32 v63, v58, v59
	v_mov_b32_e32 v58, v64
	v_mov_b32_e32 v59, v60
	v_pk_mul_f32 v[58:59], v[58:59], v[154:155] op_sel_hi:[1,0]
	s_nop 0
	v_mul_f32_e32 v60, 0xbfb8aa3b, v59
	v_exp_f32_e32 v60, v60
	s_nop 0
	v_add_f32_e32 v60, 1.0, v60
	v_rcp_f32_e32 v60, v60
	s_nop 0
	v_mul_f32_e32 v59, v59, v60
	v_mov_b32_e32 v60, v65
	v_mul_f32_e32 v64, v58, v59
	v_pk_mul_f32 v[58:59], v[60:61], v[154:155] op_sel_hi:[1,0]
	s_nop 0
	v_mul_f32_e32 v60, 0xbfb8aa3b, v59
	v_exp_f32_e32 v60, v60
	s_nop 0
	v_add_f32_e32 v60, 1.0, v60
	v_rcp_f32_e32 v60, v60
	s_nop 0
	v_mul_f32_e32 v59, v59, v60
	v_mul_f32_e32 v60, v58, v59
	v_mov_b32_e32 v58, v54
	v_mov_b32_e32 v59, v50
	v_pk_mul_f32 v[58:59], v[58:59], v[154:155] op_sel_hi:[1,0]
	s_nop 0
	v_mul_f32_e32 v50, 0xbfb8aa3b, v59
	v_exp_f32_e32 v50, v50
	s_nop 0
	v_add_f32_e32 v50, 1.0, v50
	v_rcp_f32_e32 v50, v50
	s_nop 0
	v_mul_f32_e32 v50, v59, v50
	v_mul_f32_e32 v54, v58, v50
	v_mov_b32_e32 v50, v55
	v_pk_mul_f32 v[50:51], v[50:51], v[154:155] op_sel_hi:[1,0]
	s_nop 0
	v_mul_f32_e32 v55, 0xbfb8aa3b, v51
	v_exp_f32_e32 v55, v55
	s_nop 0
	v_add_f32_e32 v55, 1.0, v55
	v_rcp_f32_e32 v55, v55
	s_nop 0
	v_mul_f32_e32 v51, v51, v55
	v_mul_f32_e32 v55, v50, v51
	v_mov_b32_e32 v50, v56
	v_mov_b32_e32 v51, v52
	v_pk_mul_f32 v[50:51], v[50:51], v[154:155] op_sel_hi:[1,0]
	s_nop 0
	v_mul_f32_e32 v52, 0xbfb8aa3b, v51
	v_exp_f32_e32 v52, v52
	s_nop 0
	v_add_f32_e32 v52, 1.0, v52
	v_rcp_f32_e32 v52, v52
	s_nop 0
	v_mul_f32_e32 v51, v51, v52
	v_mov_b32_e32 v52, v57
	v_mul_f32_e32 v56, v50, v51
	v_pk_mul_f32 v[50:51], v[52:53], v[154:155] op_sel_hi:[1,0]
	s_nop 0
	v_mul_f32_e32 v52, 0xbfb8aa3b, v51
	v_exp_f32_e32 v52, v52
	s_nop 0
	v_add_f32_e32 v52, 1.0, v52
	v_rcp_f32_e32 v52, v52
	s_nop 0
	v_mul_f32_e32 v51, v51, v52
	v_mul_f32_e32 v53, v50, v51
	v_cvt_pk_bf16_f32 v50, v62, v63
	v_cvt_pk_bf16_f32 v51, v64, v60
	v_cvt_pk_bf16_f32 v52, v54, v55
	v_mad_i64_i32 v[54:55], s[0:1], v68, s89, v[114:115]
	v_lshl_add_u64 v[54:55], v[54:55], 0, v[116:117]
	v_cvt_pk_bf16_f32 v53, v56, v53
	global_store_dwordx4 v[54:55], v[50:53], off
	s_nop 1
	v_mov_b32_e32 v50, v46
	v_mov_b32_e32 v51, v42
	v_pk_mul_f32 v[50:51], v[50:51], v[152:153] op_sel_hi:[1,0]
	s_nop 0
	v_mul_f32_e32 v42, 0xbfb8aa3b, v51
	v_exp_f32_e32 v42, v42
	s_nop 0
	v_add_f32_e32 v42, 1.0, v42
	v_rcp_f32_e32 v42, v42
	s_nop 0
	v_mul_f32_e32 v42, v51, v42
	v_mul_f32_e32 v46, v50, v42
	v_mov_b32_e32 v42, v47
	v_pk_mul_f32 v[42:43], v[42:43], v[152:153] op_sel_hi:[1,0]
	s_nop 0
	v_mul_f32_e32 v47, 0xbfb8aa3b, v43
	v_exp_f32_e32 v47, v47
	s_nop 0
	v_add_f32_e32 v47, 1.0, v47
	v_rcp_f32_e32 v47, v47
	s_nop 0
	v_mul_f32_e32 v43, v43, v47
	v_mul_f32_e32 v47, v42, v43
	v_mov_b32_e32 v42, v48
	v_mov_b32_e32 v43, v44
	v_pk_mul_f32 v[42:43], v[42:43], v[152:153] op_sel_hi:[1,0]
	s_nop 0
	v_mul_f32_e32 v44, 0xbfb8aa3b, v43
	v_exp_f32_e32 v44, v44
	s_nop 0
	v_add_f32_e32 v44, 1.0, v44
	v_rcp_f32_e32 v44, v44
	s_nop 0
	v_mul_f32_e32 v43, v43, v44
	v_mov_b32_e32 v44, v49
	v_mul_f32_e32 v48, v42, v43
	v_pk_mul_f32 v[42:43], v[44:45], v[152:153] op_sel_hi:[1,0]
	s_nop 0
	v_mul_f32_e32 v44, 0xbfb8aa3b, v43
	v_exp_f32_e32 v44, v44
	s_nop 0
	v_add_f32_e32 v44, 1.0, v44
	v_rcp_f32_e32 v44, v44
	s_nop 0
	v_mul_f32_e32 v43, v43, v44
	v_mul_f32_e32 v44, v42, v43
	v_mov_b32_e32 v42, v38
	v_mov_b32_e32 v43, v34
	v_pk_mul_f32 v[42:43], v[42:43], v[152:153] op_sel_hi:[1,0]
	s_nop 0
	v_mul_f32_e32 v34, 0xbfb8aa3b, v43
	v_exp_f32_e32 v34, v34
	s_nop 0
	v_add_f32_e32 v34, 1.0, v34
	v_rcp_f32_e32 v34, v34
	s_nop 0
	v_mul_f32_e32 v34, v43, v34
	v_mul_f32_e32 v38, v42, v34
	v_mov_b32_e32 v34, v39
	v_pk_mul_f32 v[34:35], v[34:35], v[152:153] op_sel_hi:[1,0]
	s_nop 0
	v_mul_f32_e32 v39, 0xbfb8aa3b, v35
	v_exp_f32_e32 v39, v39
	s_nop 0
	v_add_f32_e32 v39, 1.0, v39
	v_rcp_f32_e32 v39, v39
	s_nop 0
	v_mul_f32_e32 v35, v35, v39
	v_mul_f32_e32 v39, v34, v35
	v_mov_b32_e32 v34, v40
	v_mov_b32_e32 v35, v36
	v_pk_mul_f32 v[34:35], v[34:35], v[152:153] op_sel_hi:[1,0]
	s_nop 0
	v_mul_f32_e32 v36, 0xbfb8aa3b, v35
	v_exp_f32_e32 v36, v36
	s_nop 0
	v_add_f32_e32 v36, 1.0, v36
	v_rcp_f32_e32 v36, v36
	s_nop 0
	v_mul_f32_e32 v35, v35, v36
	v_mov_b32_e32 v36, v41
	v_mul_f32_e32 v40, v34, v35
	v_pk_mul_f32 v[34:35], v[36:37], v[152:153] op_sel_hi:[1,0]
	v_add_u32_e32 v41, 0x90, v144
	v_mul_f32_e32 v36, 0xbfb8aa3b, v35
	v_exp_f32_e32 v36, v36
	s_nop 0
	v_add_f32_e32 v36, 1.0, v36
	v_rcp_f32_e32 v36, v36
	s_nop 0
	v_mul_f32_e32 v35, v35, v36
	v_mul_f32_e32 v37, v34, v35
	v_cvt_pk_bf16_f32 v34, v46, v47
	v_cvt_pk_bf16_f32 v35, v48, v44
	v_cvt_pk_bf16_f32 v36, v38, v39
	v_mad_i64_i32 v[38:39], s[0:1], v41, s89, v[114:115]
	v_lshl_add_u64 v[38:39], v[38:39], 0, v[116:117]
	v_cvt_pk_bf16_f32 v37, v40, v37
	global_store_dwordx4 v[38:39], v[34:37], off
	s_nop 1
	v_mov_b32_e32 v34, v30
	v_mov_b32_e32 v35, v26
	v_pk_mul_f32 v[34:35], v[34:35], v[150:151] op_sel_hi:[1,0]
	s_nop 0
	v_mul_f32_e32 v26, 0xbfb8aa3b, v35
	v_exp_f32_e32 v26, v26
	s_nop 0
	v_add_f32_e32 v26, 1.0, v26
	v_rcp_f32_e32 v26, v26
	s_nop 0
	v_mul_f32_e32 v26, v35, v26
	v_mul_f32_e32 v30, v34, v26
	v_mov_b32_e32 v26, v31
	v_pk_mul_f32 v[26:27], v[26:27], v[150:151] op_sel_hi:[1,0]
	s_nop 0
	v_mul_f32_e32 v31, 0xbfb8aa3b, v27
	v_exp_f32_e32 v31, v31
	s_nop 0
	v_add_f32_e32 v31, 1.0, v31
	v_rcp_f32_e32 v31, v31
	s_nop 0
	v_mul_f32_e32 v27, v27, v31
	v_mul_f32_e32 v31, v26, v27
	v_mov_b32_e32 v26, v32
	v_mov_b32_e32 v27, v28
	v_pk_mul_f32 v[26:27], v[26:27], v[150:151] op_sel_hi:[1,0]
	s_nop 0
	v_mul_f32_e32 v28, 0xbfb8aa3b, v27
	v_exp_f32_e32 v28, v28
	s_nop 0
	v_add_f32_e32 v28, 1.0, v28
	v_rcp_f32_e32 v28, v28
	s_nop 0
	v_mul_f32_e32 v27, v27, v28
	v_mov_b32_e32 v28, v33
	v_mul_f32_e32 v32, v26, v27
	v_pk_mul_f32 v[26:27], v[28:29], v[150:151] op_sel_hi:[1,0]
	s_nop 0
	v_mul_f32_e32 v28, 0xbfb8aa3b, v27
	v_exp_f32_e32 v28, v28
	s_nop 0
	v_add_f32_e32 v28, 1.0, v28
	v_rcp_f32_e32 v28, v28
	s_nop 0
	v_mul_f32_e32 v27, v27, v28
	v_mul_f32_e32 v28, v26, v27
	v_mov_b32_e32 v26, v22
	v_mov_b32_e32 v27, v18
	v_pk_mul_f32 v[26:27], v[26:27], v[150:151] op_sel_hi:[1,0]
	s_nop 0
	v_mul_f32_e32 v18, 0xbfb8aa3b, v27
	v_exp_f32_e32 v18, v18
	s_nop 0
	v_add_f32_e32 v18, 1.0, v18
	v_rcp_f32_e32 v18, v18
	s_nop 0
	v_mul_f32_e32 v18, v27, v18
	v_mul_f32_e32 v22, v26, v18
	v_mov_b32_e32 v18, v23
	v_pk_mul_f32 v[18:19], v[18:19], v[150:151] op_sel_hi:[1,0]
	s_nop 0
	v_mul_f32_e32 v23, 0xbfb8aa3b, v19
	v_exp_f32_e32 v23, v23
	s_nop 0
	v_add_f32_e32 v23, 1.0, v23
	v_rcp_f32_e32 v23, v23
	s_nop 0
	v_mul_f32_e32 v19, v19, v23
	v_mul_f32_e32 v23, v18, v19
	v_mov_b32_e32 v18, v24
	v_mov_b32_e32 v19, v20
	v_pk_mul_f32 v[18:19], v[18:19], v[150:151] op_sel_hi:[1,0]
	s_nop 0
	v_mul_f32_e32 v20, 0xbfb8aa3b, v19
	v_exp_f32_e32 v20, v20
	s_nop 0
	v_add_f32_e32 v20, 1.0, v20
	v_rcp_f32_e32 v20, v20
	s_nop 0
	v_mul_f32_e32 v19, v19, v20
	v_mov_b32_e32 v20, v25
	v_mul_f32_e32 v24, v18, v19
	v_pk_mul_f32 v[18:19], v[20:21], v[150:151] op_sel_hi:[1,0]
	v_add_u32_e32 v25, 0xa0, v144
	v_mul_f32_e32 v20, 0xbfb8aa3b, v19
	v_exp_f32_e32 v20, v20
	s_nop 0
	v_add_f32_e32 v20, 1.0, v20
	v_rcp_f32_e32 v20, v20
	s_nop 0
	v_mul_f32_e32 v19, v19, v20
	v_mul_f32_e32 v21, v18, v19
	v_cvt_pk_bf16_f32 v18, v30, v31
	v_cvt_pk_bf16_f32 v19, v32, v28
	v_cvt_pk_bf16_f32 v20, v22, v23
	v_mad_i64_i32 v[22:23], s[0:1], v25, s89, v[114:115]
	v_lshl_add_u64 v[22:23], v[22:23], 0, v[116:117]
	v_cvt_pk_bf16_f32 v21, v24, v21
	global_store_dwordx4 v[22:23], v[18:21], off
	s_nop 1
	v_mov_b32_e32 v18, v14
	v_mov_b32_e32 v19, v6
	v_pk_mul_f32 v[18:19], v[18:19], v[148:149] op_sel_hi:[1,0]
	s_nop 0
	v_mul_f32_e32 v6, 0xbfb8aa3b, v19
	v_exp_f32_e32 v6, v6
	s_nop 0
	v_add_f32_e32 v6, 1.0, v6
	v_rcp_f32_e32 v6, v6
	s_nop 0
	v_mul_f32_e32 v6, v19, v6
	v_mul_f32_e32 v14, v18, v6
	v_mov_b32_e32 v6, v15
	v_pk_mul_f32 v[6:7], v[6:7], v[148:149] op_sel_hi:[1,0]
	s_nop 0
	v_mul_f32_e32 v15, 0xbfb8aa3b, v7
	v_exp_f32_e32 v15, v15
	s_nop 0
	v_add_f32_e32 v15, 1.0, v15
	v_rcp_f32_e32 v15, v15
	s_nop 0
	v_mul_f32_e32 v7, v7, v15
	v_mul_f32_e32 v15, v6, v7
	v_mov_b32_e32 v6, v16
	v_mov_b32_e32 v7, v8
	v_pk_mul_f32 v[6:7], v[6:7], v[148:149] op_sel_hi:[1,0]
	s_nop 0
	v_mul_f32_e32 v8, 0xbfb8aa3b, v7
	v_exp_f32_e32 v8, v8
	s_nop 0
	v_add_f32_e32 v8, 1.0, v8
	v_rcp_f32_e32 v8, v8
	s_nop 0
	v_mul_f32_e32 v7, v7, v8
	v_mov_b32_e32 v8, v17
	v_mul_f32_e32 v16, v6, v7
	v_pk_mul_f32 v[6:7], v[8:9], v[148:149] op_sel_hi:[1,0]
	s_nop 0
	v_mul_f32_e32 v8, 0xbfb8aa3b, v7
	v_exp_f32_e32 v8, v8
	s_nop 0
	v_add_f32_e32 v8, 1.0, v8
	v_rcp_f32_e32 v8, v8
	s_nop 0
	v_mul_f32_e32 v7, v7, v8
	v_mul_f32_e32 v8, v6, v7
	v_mov_b32_e32 v6, v10
	v_mov_b32_e32 v7, v2
	v_pk_mul_f32 v[6:7], v[6:7], v[148:149] op_sel_hi:[1,0]
	v_add_u32_e32 v10, 0xb0, v144
	v_mul_f32_e32 v2, 0xbfb8aa3b, v7
	v_exp_f32_e32 v2, v2
	s_nop 0
	v_add_f32_e32 v2, 1.0, v2
	v_rcp_f32_e32 v2, v2
	s_nop 0
	v_mul_f32_e32 v2, v7, v2
	v_mul_f32_e32 v6, v6, v2
	v_mov_b32_e32 v2, v11
	v_pk_mul_f32 v[2:3], v[2:3], v[148:149] op_sel_hi:[1,0]
	s_nop 0
	v_mul_f32_e32 v7, 0xbfb8aa3b, v3
	v_exp_f32_e32 v7, v7
	s_nop 0
	v_add_f32_e32 v7, 1.0, v7
	v_rcp_f32_e32 v7, v7
	s_nop 0
	v_mul_f32_e32 v3, v3, v7
	v_mul_f32_e32 v7, v2, v3
	v_mov_b32_e32 v2, v12
	v_mov_b32_e32 v3, v4
	v_pk_mul_f32 v[2:3], v[2:3], v[148:149] op_sel_hi:[1,0]
	s_nop 0
	v_mul_f32_e32 v4, 0xbfb8aa3b, v3
	v_exp_f32_e32 v4, v4
	s_nop 0
	v_add_f32_e32 v4, 1.0, v4
	v_rcp_f32_e32 v4, v4
	s_nop 0
	v_mul_f32_e32 v3, v3, v4
	v_mov_b32_e32 v4, v13
	v_mul_f32_e32 v9, v2, v3
	v_pk_mul_f32 v[2:3], v[4:5], v[148:149] op_sel_hi:[1,0]
	s_nop 0
	v_mul_f32_e32 v4, 0xbfb8aa3b, v3
	v_exp_f32_e32 v4, v4
	s_nop 0
	v_add_f32_e32 v4, 1.0, v4
	v_rcp_f32_e32 v4, v4
	s_nop 0
	v_mul_f32_e32 v3, v3, v4
	v_mul_f32_e32 v5, v2, v3
	v_cvt_pk_bf16_f32 v2, v14, v15
	v_cvt_pk_bf16_f32 v3, v16, v8
	v_cvt_pk_bf16_f32 v4, v6, v7
	v_mad_i64_i32 v[6:7], s[0:1], v10, s89, v[114:115]
	v_lshl_add_u64 v[6:7], v[6:7], 0, v[116:117]
	v_cvt_pk_bf16_f32 v5, v9, v5
	global_store_dwordx4 v[6:7], v[2:5], off
	s_nop 1
	v_mov_b64_e32 v[2:3], v[146:147]
	s_cbranch_vccz .LBB0_815
	s_waitcnt vmcnt(0)
	s_cmpk_gt_u32 s2, 0xff
	v_readlane_b32 s89, v253, 39
	s_cbranch_scc1 .LBB0_14
	s_barrier
	s_branch .LBB0_14
